# hyena radix-8 FFT pass loops (12 in bp loop): hand-written packed-f32 complex math, 2-instr complex multiply with asymmetric neg_lo/neg_hi
# speedup vs baseline: 1.0191x; 1.0191x over previous
; #define LAS __attribute__((address_space(3)))
; __device__ __forceinline__ int otid() { int t = threadIdx.x; asm volatile("" : "+v"(t)); return t; }
; __device__ __forceinline__ cf twc(cf ws, int k16) { if (k16 == 0) return ws; if (k16 == 4) return cf{ws.y, -ws.x}; return cmul(ws, cf{c16(k16), -s16(k16)}); }
; template <int LR> __device__ __forceinline__ void dif_reg(cf (&x)[1 << LR], cf w) {
;     constexpr int R = 1 << LR; cf ws = w;
; #pragma unroll
;     for (int s = 0; s < LR; ++s) { const int half = R >> (s + 1);
; #pragma unroll
;         for (int m0 = 0; m0 < R; m0 += 2 * half)
; #pragma unroll
;             for (int mm = 0; mm < half; ++mm) { const int ia = m0 + mm, ib = ia + half; const cf a = x[ia], b = x[ib];
;                 x[ia] = cf{a.x + b.x, a.y + b.y}; const cf d{a.x - b.x, a.y - b.y};
;                 x[ib] = cmul(d, twc(ws, (mm << s) * (16 / R))); }
;         ws = cmul(ws, ws); }
; }
; template <int LR, bool INV> __device__ __forceinline__ void fft_pass(ldsf2 buf, int base, int stride, int twi) {
;     constexpr int R = 1 << LR; cf x[R];
;     const v2f wv = ((ldsf2)((LAS unsigned char*)buf + 139264))[twi];
; #pragma unroll
;     for (int m = 0; m < R; ++m) { const v2f v = buf[base + m * stride]; x[m] = cf{v.x, v.y}; }
;     const cf w{wv.x, wv.y};
;     if (INV) dit_reg<LR>(x, w); else dif_reg<LR>(x, w);
; #pragma unroll
;     for (int m = 0; m < R; ++m) buf[base + m * stride] = mkv2(x[m].x, x[m].y);
; }
; __device__ __forceinline__ void wave_lds_fence() { asm volatile("s_waitcnt lgkmcnt(0)" ::: "memory"); }
; __device__ __forceinline__ void fft_fwd_abc(ldsf2 buf) {
;     const int tid = otid(); const int wv = tid >> 6, l = tid & 63;
; #pragma unroll 1
;     for (int u = 0; u < 2; ++u) { const int bf = tid + NT * u; fft_pass<3, false>(buf, bf + (bf >> 4), 1088, bf); }
.LBB0_347:
	v_cndmask_b32_e64 v69, 0, 1, s[6:7]
	v_add_u32_e32 v72, s0, v68
	v_cmp_ne_u32_e32 vcc, 1, v69
	v_ashrrev_i32_e32 v69, 4, v72
	v_lshl_add_u32 v72, v72, 3, 0
	v_add_u32_e32 v73, 0x22000, v72
	v_lshl_add_u32 v69, v69, 3, v72
	ds_read_b64 v[88:89], v73
	ds_read2st64_b64 v[72:75], v69 offset1:17
	ds_read2st64_b64 v[76:79], v69 offset0:68 offset1:85
	ds_read2st64_b64 v[80:83], v69 offset0:34 offset1:51
	ds_read2st64_b64 v[84:87], v69 offset0:102 offset1:119
	s_waitcnt lgkmcnt(4)
	v_pk_add_f32 v[90:91], v[88:89], v[88:89] op_sel:[0,1] op_sel_hi:[1,0] neg_lo:[0,0] neg_hi:[0,1]
	v_pk_mul_f32 v[92:93], v[90:91], s[16:17] op_sel:[0,0] op_sel_hi:[1,0]
	v_pk_mul_f32 v[94:95], v[90:91], s[16:17] op_sel:[1,0] op_sel_hi:[0,0] neg_lo:[0,0] neg_hi:[1,0]
	v_pk_mul_f32 v[96:97], v[88:89], v[88:89] op_sel:[1,1] op_sel_hi:[1,0]
	v_pk_fma_f32 v[96:97], v[88:89], v[88:89], v[96:97] op_sel:[0,0,0] op_sel_hi:[0,1,1] neg_lo:[0,0,1] neg_hi:[0,0,0]
	v_pk_mul_f32 v[98:99], v[96:97], v[96:97] op_sel:[1,1] op_sel_hi:[1,0]
	v_pk_fma_f32 v[98:99], v[96:97], v[96:97], v[98:99] op_sel:[0,0,0] op_sel_hi:[0,1,1] neg_lo:[0,0,1] neg_hi:[0,0,0]
	s_waitcnt lgkmcnt(0)
	v_pk_add_f32 v[100:101], v[72:73], v[76:77] neg_lo:[0,1] neg_hi:[0,1]
	v_pk_add_f32 v[102:103], v[74:75], v[78:79] neg_lo:[0,1] neg_hi:[0,1]
	v_pk_add_f32 v[104:105], v[80:81], v[84:85] neg_lo:[0,1] neg_hi:[0,1]
	v_pk_add_f32 v[106:107], v[82:83], v[86:87] neg_lo:[0,1] neg_hi:[0,1]
	v_pk_add_f32 v[72:73], v[72:73], v[76:77]
	v_pk_add_f32 v[74:75], v[74:75], v[78:79]
	v_pk_add_f32 v[80:81], v[80:81], v[84:85]
	v_pk_add_f32 v[82:83], v[82:83], v[86:87]
	v_pk_mul_f32 v[76:77], v[100:101], v[88:89] op_sel:[1,1] op_sel_hi:[1,0]
	v_pk_mul_f32 v[78:79], v[102:103], v[92:93] op_sel:[1,1] op_sel_hi:[1,0]
	v_pk_mul_f32 v[84:85], v[104:105], v[88:89] op_sel:[1,0] op_sel_hi:[1,1]
	v_pk_mul_f32 v[86:87], v[106:107], v[94:95] op_sel:[1,1] op_sel_hi:[1,0]
	v_pk_fma_f32 v[76:77], v[100:101], v[88:89], v[76:77] op_sel:[0,0,0] op_sel_hi:[0,1,1] neg_lo:[0,0,1] neg_hi:[0,0,0]
	v_pk_fma_f32 v[78:79], v[102:103], v[92:93], v[78:79] op_sel:[0,0,0] op_sel_hi:[0,1,1] neg_lo:[0,0,1] neg_hi:[0,0,0]
	v_pk_fma_f32 v[84:85], v[104:105], v[88:89], v[84:85] op_sel:[0,1,0] op_sel_hi:[0,0,1] neg_lo:[0,0,0] neg_hi:[0,1,0]
	v_pk_fma_f32 v[86:87], v[106:107], v[94:95], v[86:87] op_sel:[0,0,0] op_sel_hi:[0,1,1] neg_lo:[0,0,1] neg_hi:[0,0,0]
	v_pk_add_f32 v[100:101], v[72:73], v[80:81] neg_lo:[0,1] neg_hi:[0,1]
	v_pk_add_f32 v[102:103], v[74:75], v[82:83] neg_lo:[0,1] neg_hi:[0,1]
	v_pk_add_f32 v[104:105], v[76:77], v[84:85] neg_lo:[0,1] neg_hi:[0,1]
	v_pk_add_f32 v[106:107], v[78:79], v[86:87] neg_lo:[0,1] neg_hi:[0,1]
	v_pk_add_f32 v[72:73], v[72:73], v[80:81]
	v_pk_add_f32 v[74:75], v[74:75], v[82:83]
	v_pk_add_f32 v[76:77], v[76:77], v[84:85]
	v_pk_add_f32 v[78:79], v[78:79], v[86:87]
	v_pk_mul_f32 v[80:81], v[100:101], v[96:97] op_sel:[1,1] op_sel_hi:[1,0]
	v_pk_mul_f32 v[82:83], v[102:103], v[96:97] op_sel:[1,0] op_sel_hi:[1,1]
	v_pk_mul_f32 v[84:85], v[104:105], v[96:97] op_sel:[1,1] op_sel_hi:[1,0]
	v_pk_mul_f32 v[86:87], v[106:107], v[96:97] op_sel:[1,0] op_sel_hi:[1,1]
	v_pk_fma_f32 v[80:81], v[100:101], v[96:97], v[80:81] op_sel:[0,0,0] op_sel_hi:[0,1,1] neg_lo:[0,0,1] neg_hi:[0,0,0]
	v_pk_fma_f32 v[82:83], v[102:103], v[96:97], v[82:83] op_sel:[0,1,0] op_sel_hi:[0,0,1] neg_lo:[0,0,0] neg_hi:[0,1,0]
	v_pk_fma_f32 v[84:85], v[104:105], v[96:97], v[84:85] op_sel:[0,0,0] op_sel_hi:[0,1,1] neg_lo:[0,0,1] neg_hi:[0,0,0]
	v_pk_fma_f32 v[86:87], v[106:107], v[96:97], v[86:87] op_sel:[0,1,0] op_sel_hi:[0,0,1] neg_lo:[0,0,0] neg_hi:[0,1,0]
	v_pk_add_f32 v[100:101], v[72:73], v[74:75] neg_lo:[0,1] neg_hi:[0,1]
	v_pk_add_f32 v[102:103], v[80:81], v[82:83] neg_lo:[0,1] neg_hi:[0,1]
	v_pk_add_f32 v[104:105], v[76:77], v[78:79] neg_lo:[0,1] neg_hi:[0,1]
	v_pk_add_f32 v[106:107], v[84:85], v[86:87] neg_lo:[0,1] neg_hi:[0,1]
	v_pk_add_f32 v[72:73], v[72:73], v[74:75]
	v_pk_add_f32 v[80:81], v[80:81], v[82:83]
	v_pk_add_f32 v[76:77], v[76:77], v[78:79]
	v_pk_add_f32 v[84:85], v[84:85], v[86:87]
	v_pk_mul_f32 v[74:75], v[100:101], v[98:99] op_sel:[1,1] op_sel_hi:[1,0]
	v_pk_mul_f32 v[82:83], v[102:103], v[98:99] op_sel:[1,1] op_sel_hi:[1,0]
	v_pk_mul_f32 v[78:79], v[104:105], v[98:99] op_sel:[1,1] op_sel_hi:[1,0]
	v_pk_mul_f32 v[86:87], v[106:107], v[98:99] op_sel:[1,1] op_sel_hi:[1,0]
	v_pk_fma_f32 v[74:75], v[100:101], v[98:99], v[74:75] op_sel:[0,0,0] op_sel_hi:[0,1,1] neg_lo:[0,0,1] neg_hi:[0,0,0]
	v_pk_fma_f32 v[82:83], v[102:103], v[98:99], v[82:83] op_sel:[0,0,0] op_sel_hi:[0,1,1] neg_lo:[0,0,1] neg_hi:[0,0,0]
	v_pk_fma_f32 v[78:79], v[104:105], v[98:99], v[78:79] op_sel:[0,0,0] op_sel_hi:[0,1,1] neg_lo:[0,0,1] neg_hi:[0,0,0]
	v_pk_fma_f32 v[86:87], v[106:107], v[98:99], v[86:87] op_sel:[0,0,0] op_sel_hi:[0,1,1] neg_lo:[0,0,1] neg_hi:[0,0,0]
	ds_write2st64_b64 v69, v[72:73], v[74:75] offset1:17
	ds_write2st64_b64 v69, v[80:81], v[82:83] offset0:34 offset1:51
	ds_write2st64_b64 v69, v[76:77], v[78:79] offset0:68 offset1:85
	ds_write2st64_b64 v69, v[84:85], v[86:87] offset0:102 offset1:119
	s_movk_i32 s0, 0x200
	s_mov_b64 s[6:7], 0
	s_cbranch_vccz .LBB0_347
	s_waitcnt lgkmcnt(0)
	s_barrier
	v_lshlrev_b32_e32 v72, 4, v68
	v_and_b32_e32 v69, 63, v68
	v_and_b32_e32 v72, 0xfffffc00, v72
	s_mov_b32 s0, 0
	s_mov_b64 s[6:7], -1
; #define LAS __attribute__((address_space(3)))
; __device__ __forceinline__ int otid() { int t = threadIdx.x; asm volatile("" : "+v"(t)); return t; }
; __device__ __forceinline__ cf twc(cf ws, int k16) { if (k16 == 0) return ws; if (k16 == 4) return cf{ws.y, -ws.x}; return cmul(ws, cf{c16(k16), -s16(k16)}); }
; __device__ __forceinline__ void lds_barrier() { asm volatile("s_waitcnt lgkmcnt(0)\n\ts_barrier" ::: "memory"); }
; template <int LR> __device__ __forceinline__ void dif_reg(cf (&x)[1 << LR], cf w) {
;     constexpr int R = 1 << LR; cf ws = w;
; #pragma unroll
;     for (int s = 0; s < LR; ++s) { const int half = R >> (s + 1);
; #pragma unroll
;         for (int m0 = 0; m0 < R; m0 += 2 * half)
; #pragma unroll
;             for (int mm = 0; mm < half; ++mm) { const int ia = m0 + mm, ib = ia + half; const cf a = x[ia], b = x[ib];
;                 x[ia] = cf{a.x + b.x, a.y + b.y}; const cf d{a.x - b.x, a.y - b.y};
;                 x[ib] = cmul(d, twc(ws, (mm << s) * (16 / R))); }
;         ws = cmul(ws, ws); }
; }
; template <int LR, bool INV> __device__ __forceinline__ void fft_pass(ldsf2 buf, int base, int stride, int twi) {
;     constexpr int R = 1 << LR; cf x[R];
;     const v2f wv = ((ldsf2)((LAS unsigned char*)buf + 139264))[twi];
; #pragma unroll
;     for (int m = 0; m < R; ++m) { const v2f v = buf[base + m * stride]; x[m] = cf{v.x, v.y}; }
;     const cf w{wv.x, wv.y};
;     if (INV) dit_reg<LR>(x, w); else dif_reg<LR>(x, w);
; #pragma unroll
;     for (int m = 0; m < R; ++m) buf[base + m * stride] = mkv2(x[m].x, x[m].y);
; }
; __device__ __forceinline__ void wave_lds_fence() { asm volatile("s_waitcnt lgkmcnt(0)" ::: "memory"); }
; __device__ __forceinline__ void fft_fwd_abc(ldsf2 buf) {
;     const int tid = otid(); const int wv = tid >> 6, l = tid & 63;
; #pragma unroll 1
;     for (int u = 0; u < 2; ++u) { const int bf = tid + NT * u; fft_pass<3, false>(buf, bf + (bf >> 4), 1088, bf); }
;     lds_barrier();
; #pragma unroll 1
;     for (int u = 0; u < 2; ++u) { const int o = l + 64 * u, e0 = wv * 1024 + o; fft_pass<3, false>(buf, e0 + (e0 >> 4), 136, o * 8); }
.LBB0_349:
	v_cndmask_b32_e64 v73, 0, 1, s[6:7]
	v_or_b32_e32 v74, s0, v69
	v_cmp_ne_u32_e32 vcc, 1, v73
	v_or_b32_e32 v73, v74, v72
	v_lshl_add_u32 v74, v74, 6, 0
	v_ashrrev_i32_e32 v75, 4, v73
	v_add_u32_e32 v74, 0x22000, v74
	v_lshlrev_b32_e32 v73, 3, v73
	ds_read_b64 v[90:91], v74
	v_lshlrev_b32_e32 v74, 3, v75
	v_add3_u32 v73, 0, v73, v74
	v_add_u32_e32 v113, 0x800, v73
	ds_read2_b64 v[74:77], v73 offset1:136
	v_add_u32_e32 v118, 0x1000, v73
	v_add_u32_e32 v119, 0x1800, v73
	ds_read2_b64 v[78:81], v113 offset0:16 offset1:152
	ds_read2_b64 v[82:85], v118 offset0:32 offset1:168
	ds_read2_b64 v[86:89], v119 offset0:48 offset1:184
	s_waitcnt lgkmcnt(4)
	v_pk_add_f32 v[92:93], v[90:91], v[90:91] op_sel:[0,1] op_sel_hi:[1,0] neg_lo:[0,0] neg_hi:[0,1]
	v_pk_mul_f32 v[94:95], v[92:93], s[16:17] op_sel:[0,0] op_sel_hi:[1,0]
	v_pk_mul_f32 v[96:97], v[92:93], s[16:17] op_sel:[1,0] op_sel_hi:[0,0] neg_lo:[0,0] neg_hi:[1,0]
	v_pk_mul_f32 v[98:99], v[90:91], v[90:91] op_sel:[1,1] op_sel_hi:[1,0]
	v_pk_fma_f32 v[98:99], v[90:91], v[90:91], v[98:99] op_sel:[0,0,0] op_sel_hi:[0,1,1] neg_lo:[0,0,1] neg_hi:[0,0,0]
	v_pk_mul_f32 v[100:101], v[98:99], v[98:99] op_sel:[1,1] op_sel_hi:[1,0]
	v_pk_fma_f32 v[100:101], v[98:99], v[98:99], v[100:101] op_sel:[0,0,0] op_sel_hi:[0,1,1] neg_lo:[0,0,1] neg_hi:[0,0,0]
	s_waitcnt lgkmcnt(0)
	v_pk_add_f32 v[102:103], v[74:75], v[82:83] neg_lo:[0,1] neg_hi:[0,1]
	v_pk_add_f32 v[104:105], v[76:77], v[84:85] neg_lo:[0,1] neg_hi:[0,1]
	v_pk_add_f32 v[106:107], v[78:79], v[86:87] neg_lo:[0,1] neg_hi:[0,1]
	v_pk_add_f32 v[108:109], v[80:81], v[88:89] neg_lo:[0,1] neg_hi:[0,1]
	v_pk_add_f32 v[74:75], v[74:75], v[82:83]
	v_pk_add_f32 v[76:77], v[76:77], v[84:85]
	v_pk_add_f32 v[78:79], v[78:79], v[86:87]
	v_pk_add_f32 v[80:81], v[80:81], v[88:89]
	v_pk_mul_f32 v[82:83], v[102:103], v[90:91] op_sel:[1,1] op_sel_hi:[1,0]
	v_pk_mul_f32 v[84:85], v[104:105], v[94:95] op_sel:[1,1] op_sel_hi:[1,0]
	v_pk_mul_f32 v[86:87], v[106:107], v[90:91] op_sel:[1,0] op_sel_hi:[1,1]
	v_pk_mul_f32 v[88:89], v[108:109], v[96:97] op_sel:[1,1] op_sel_hi:[1,0]
	v_pk_fma_f32 v[82:83], v[102:103], v[90:91], v[82:83] op_sel:[0,0,0] op_sel_hi:[0,1,1] neg_lo:[0,0,1] neg_hi:[0,0,0]
	v_pk_fma_f32 v[84:85], v[104:105], v[94:95], v[84:85] op_sel:[0,0,0] op_sel_hi:[0,1,1] neg_lo:[0,0,1] neg_hi:[0,0,0]
	v_pk_fma_f32 v[86:87], v[106:107], v[90:91], v[86:87] op_sel:[0,1,0] op_sel_hi:[0,0,1] neg_lo:[0,0,0] neg_hi:[0,1,0]
	v_pk_fma_f32 v[88:89], v[108:109], v[96:97], v[88:89] op_sel:[0,0,0] op_sel_hi:[0,1,1] neg_lo:[0,0,1] neg_hi:[0,0,0]
	v_pk_add_f32 v[102:103], v[74:75], v[78:79] neg_lo:[0,1] neg_hi:[0,1]
	v_pk_add_f32 v[104:105], v[76:77], v[80:81] neg_lo:[0,1] neg_hi:[0,1]
	v_pk_add_f32 v[106:107], v[82:83], v[86:87] neg_lo:[0,1] neg_hi:[0,1]
	v_pk_add_f32 v[108:109], v[84:85], v[88:89] neg_lo:[0,1] neg_hi:[0,1]
	v_pk_add_f32 v[74:75], v[74:75], v[78:79]
	v_pk_add_f32 v[76:77], v[76:77], v[80:81]
	v_pk_add_f32 v[82:83], v[82:83], v[86:87]
	v_pk_add_f32 v[84:85], v[84:85], v[88:89]
	v_pk_mul_f32 v[78:79], v[102:103], v[98:99] op_sel:[1,1] op_sel_hi:[1,0]
	v_pk_mul_f32 v[80:81], v[104:105], v[98:99] op_sel:[1,0] op_sel_hi:[1,1]
	v_pk_mul_f32 v[86:87], v[106:107], v[98:99] op_sel:[1,1] op_sel_hi:[1,0]
	v_pk_mul_f32 v[88:89], v[108:109], v[98:99] op_sel:[1,0] op_sel_hi:[1,1]
	v_pk_fma_f32 v[78:79], v[102:103], v[98:99], v[78:79] op_sel:[0,0,0] op_sel_hi:[0,1,1] neg_lo:[0,0,1] neg_hi:[0,0,0]
	v_pk_fma_f32 v[80:81], v[104:105], v[98:99], v[80:81] op_sel:[0,1,0] op_sel_hi:[0,0,1] neg_lo:[0,0,0] neg_hi:[0,1,0]
	v_pk_fma_f32 v[86:87], v[106:107], v[98:99], v[86:87] op_sel:[0,0,0] op_sel_hi:[0,1,1] neg_lo:[0,0,1] neg_hi:[0,0,0]
	v_pk_fma_f32 v[88:89], v[108:109], v[98:99], v[88:89] op_sel:[0,1,0] op_sel_hi:[0,0,1] neg_lo:[0,0,0] neg_hi:[0,1,0]
	v_pk_add_f32 v[102:103], v[74:75], v[76:77] neg_lo:[0,1] neg_hi:[0,1]
	v_pk_add_f32 v[104:105], v[78:79], v[80:81] neg_lo:[0,1] neg_hi:[0,1]
	v_pk_add_f32 v[106:107], v[82:83], v[84:85] neg_lo:[0,1] neg_hi:[0,1]
	v_pk_add_f32 v[108:109], v[86:87], v[88:89] neg_lo:[0,1] neg_hi:[0,1]
	v_pk_add_f32 v[74:75], v[74:75], v[76:77]
	v_pk_add_f32 v[78:79], v[78:79], v[80:81]
	v_pk_add_f32 v[82:83], v[82:83], v[84:85]
	v_pk_add_f32 v[86:87], v[86:87], v[88:89]
	v_pk_mul_f32 v[76:77], v[102:103], v[100:101] op_sel:[1,1] op_sel_hi:[1,0]
	v_pk_mul_f32 v[80:81], v[104:105], v[100:101] op_sel:[1,1] op_sel_hi:[1,0]
	v_pk_mul_f32 v[84:85], v[106:107], v[100:101] op_sel:[1,1] op_sel_hi:[1,0]
	v_pk_mul_f32 v[88:89], v[108:109], v[100:101] op_sel:[1,1] op_sel_hi:[1,0]
	v_pk_fma_f32 v[76:77], v[102:103], v[100:101], v[76:77] op_sel:[0,0,0] op_sel_hi:[0,1,1] neg_lo:[0,0,1] neg_hi:[0,0,0]
	v_pk_fma_f32 v[80:81], v[104:105], v[100:101], v[80:81] op_sel:[0,0,0] op_sel_hi:[0,1,1] neg_lo:[0,0,1] neg_hi:[0,0,0]
	v_pk_fma_f32 v[84:85], v[106:107], v[100:101], v[84:85] op_sel:[0,0,0] op_sel_hi:[0,1,1] neg_lo:[0,0,1] neg_hi:[0,0,0]
	v_pk_fma_f32 v[88:89], v[108:109], v[100:101], v[88:89] op_sel:[0,0,0] op_sel_hi:[0,1,1] neg_lo:[0,0,1] neg_hi:[0,0,0]
	ds_write2_b64 v73, v[74:75], v[76:77] offset1:136
	ds_write2_b64 v113, v[78:79], v[80:81] offset0:16 offset1:152
	ds_write2_b64 v118, v[82:83], v[84:85] offset0:32 offset1:168
	ds_write2_b64 v119, v[86:87], v[88:89] offset0:48 offset1:184
	s_mov_b32 s0, 64
	s_mov_b64 s[6:7], 0
	s_cbranch_vccz .LBB0_349
	v_and_b32_e32 v68, 15, v68
	s_waitcnt lgkmcnt(0)
	v_lshlrev_b32_e32 v69, 3, v69
	v_lshlrev_b32_e32 v73, 9, v68
	v_and_or_b32 v69, v69, s90, v72
	v_add_u32_e32 v72, 0, v73
	v_lshl_add_u32 v68, v68, 3, 0
	s_mov_b32 s0, 0
	s_mov_b64 s[6:7], -1
	v_add_u32_e32 v72, 0x22000, v72
; #define LAS __attribute__((address_space(3)))
; __device__ __forceinline__ int otid() { int t = threadIdx.x; asm volatile("" : "+v"(t)); return t; }
; __device__ __forceinline__ cf twc(cf ws, int k16) { if (k16 == 0) return ws; if (k16 == 4) return cf{ws.y, -ws.x}; return cmul(ws, cf{c16(k16), -s16(k16)}); }
; __device__ __forceinline__ void lds_barrier() { asm volatile("s_waitcnt lgkmcnt(0)\n\ts_barrier" ::: "memory"); }
; template <int LR> __device__ __forceinline__ void dif_reg(cf (&x)[1 << LR], cf w) {
;     constexpr int R = 1 << LR; cf ws = w;
; #pragma unroll
;     for (int s = 0; s < LR; ++s) { const int half = R >> (s + 1);
; #pragma unroll
;         for (int m0 = 0; m0 < R; m0 += 2 * half)
; #pragma unroll
;             for (int mm = 0; mm < half; ++mm) { const int ia = m0 + mm, ib = ia + half; const cf a = x[ia], b = x[ib];
;                 x[ia] = cf{a.x + b.x, a.y + b.y}; const cf d{a.x - b.x, a.y - b.y};
;                 x[ib] = cmul(d, twc(ws, (mm << s) * (16 / R))); }
;         ws = cmul(ws, ws); }
; }
; template <int LR, bool INV> __device__ __forceinline__ void fft_pass(ldsf2 buf, int base, int stride, int twi) {
;     constexpr int R = 1 << LR; cf x[R];
;     const v2f wv = ((ldsf2)((LAS unsigned char*)buf + 139264))[twi];
; #pragma unroll
;     for (int m = 0; m < R; ++m) { const v2f v = buf[base + m * stride]; x[m] = cf{v.x, v.y}; }
;     const cf w{wv.x, wv.y};
;     if (INV) dit_reg<LR>(x, w); else dif_reg<LR>(x, w);
; #pragma unroll
;     for (int m = 0; m < R; ++m) buf[base + m * stride] = mkv2(x[m].x, x[m].y);
; }
; __device__ __forceinline__ void wave_lds_fence() { asm volatile("s_waitcnt lgkmcnt(0)" ::: "memory"); }
; __device__ __forceinline__ void fft_fwd_abc(ldsf2 buf) {
;     const int tid = otid(); const int wv = tid >> 6, l = tid & 63;
; #pragma unroll 1
;     for (int u = 0; u < 2; ++u) { const int bf = tid + NT * u; fft_pass<3, false>(buf, bf + (bf >> 4), 1088, bf); }
;     lds_barrier();
; #pragma unroll 1
;     for (int u = 0; u < 2; ++u) { const int o = l + 64 * u, e0 = wv * 1024 + o; fft_pass<3, false>(buf, e0 + (e0 >> 4), 136, o * 8); }
;     wave_lds_fence();
; #pragma unroll 1
;     for (int u = 0; u < 2; ++u) { const int j = l + 64 * u, o = j & 15, e0 = wv * 1024 + (j >> 4) * 128 + o; fft_pass<3, false>(buf, e0 + (e0 >> 4), 17, o * 64); }
.LBB0_351:
	v_or_b32_e32 v73, s0, v69
	ds_read_b64 v[90:91], v72
	v_lshlrev_b32_e32 v74, 3, v73
	v_ashrrev_i32_e32 v73, 1, v73
	v_add3_u32 v73, v68, v74, v73
	ds_read2_b64 v[74:77], v73 offset1:17
	ds_read2_b64 v[78:81], v73 offset0:34 offset1:51
	ds_read2_b64 v[82:85], v73 offset0:68 offset1:85
	ds_read2_b64 v[86:89], v73 offset0:102 offset1:119
	s_waitcnt lgkmcnt(4)
	v_pk_add_f32 v[92:93], v[90:91], v[90:91] op_sel:[0,1] op_sel_hi:[1,0] neg_lo:[0,0] neg_hi:[0,1]
	v_pk_mul_f32 v[94:95], v[92:93], s[16:17] op_sel:[0,0] op_sel_hi:[1,0]
	v_pk_mul_f32 v[96:97], v[92:93], s[16:17] op_sel:[1,0] op_sel_hi:[0,0] neg_lo:[0,0] neg_hi:[1,0]
	v_pk_mul_f32 v[98:99], v[90:91], v[90:91] op_sel:[1,1] op_sel_hi:[1,0]
	v_pk_fma_f32 v[98:99], v[90:91], v[90:91], v[98:99] op_sel:[0,0,0] op_sel_hi:[0,1,1] neg_lo:[0,0,1] neg_hi:[0,0,0]
	v_pk_mul_f32 v[100:101], v[98:99], v[98:99] op_sel:[1,1] op_sel_hi:[1,0]
	v_pk_fma_f32 v[100:101], v[98:99], v[98:99], v[100:101] op_sel:[0,0,0] op_sel_hi:[0,1,1] neg_lo:[0,0,1] neg_hi:[0,0,0]
	s_waitcnt lgkmcnt(0)
	v_pk_add_f32 v[102:103], v[74:75], v[82:83] neg_lo:[0,1] neg_hi:[0,1]
	v_pk_add_f32 v[104:105], v[76:77], v[84:85] neg_lo:[0,1] neg_hi:[0,1]
	v_pk_add_f32 v[106:107], v[78:79], v[86:87] neg_lo:[0,1] neg_hi:[0,1]
	v_pk_add_f32 v[108:109], v[80:81], v[88:89] neg_lo:[0,1] neg_hi:[0,1]
	v_pk_add_f32 v[74:75], v[74:75], v[82:83]
	v_pk_add_f32 v[76:77], v[76:77], v[84:85]
	v_pk_add_f32 v[78:79], v[78:79], v[86:87]
	v_pk_add_f32 v[80:81], v[80:81], v[88:89]
	v_pk_mul_f32 v[82:83], v[102:103], v[90:91] op_sel:[1,1] op_sel_hi:[1,0]
	v_pk_mul_f32 v[84:85], v[104:105], v[94:95] op_sel:[1,1] op_sel_hi:[1,0]
	v_pk_mul_f32 v[86:87], v[106:107], v[90:91] op_sel:[1,0] op_sel_hi:[1,1]
	v_pk_mul_f32 v[88:89], v[108:109], v[96:97] op_sel:[1,1] op_sel_hi:[1,0]
	v_pk_fma_f32 v[82:83], v[102:103], v[90:91], v[82:83] op_sel:[0,0,0] op_sel_hi:[0,1,1] neg_lo:[0,0,1] neg_hi:[0,0,0]
	v_pk_fma_f32 v[84:85], v[104:105], v[94:95], v[84:85] op_sel:[0,0,0] op_sel_hi:[0,1,1] neg_lo:[0,0,1] neg_hi:[0,0,0]
	v_pk_fma_f32 v[86:87], v[106:107], v[90:91], v[86:87] op_sel:[0,1,0] op_sel_hi:[0,0,1] neg_lo:[0,0,0] neg_hi:[0,1,0]
	v_pk_fma_f32 v[88:89], v[108:109], v[96:97], v[88:89] op_sel:[0,0,0] op_sel_hi:[0,1,1] neg_lo:[0,0,1] neg_hi:[0,0,0]
	v_pk_add_f32 v[102:103], v[74:75], v[78:79] neg_lo:[0,1] neg_hi:[0,1]
	v_pk_add_f32 v[104:105], v[76:77], v[80:81] neg_lo:[0,1] neg_hi:[0,1]
	v_pk_add_f32 v[106:107], v[82:83], v[86:87] neg_lo:[0,1] neg_hi:[0,1]
	v_pk_add_f32 v[108:109], v[84:85], v[88:89] neg_lo:[0,1] neg_hi:[0,1]
	v_pk_add_f32 v[74:75], v[74:75], v[78:79]
	v_pk_add_f32 v[76:77], v[76:77], v[80:81]
	v_pk_add_f32 v[82:83], v[82:83], v[86:87]
	v_pk_add_f32 v[84:85], v[84:85], v[88:89]
	v_pk_mul_f32 v[78:79], v[102:103], v[98:99] op_sel:[1,1] op_sel_hi:[1,0]
	v_pk_mul_f32 v[80:81], v[104:105], v[98:99] op_sel:[1,0] op_sel_hi:[1,1]
	v_pk_mul_f32 v[86:87], v[106:107], v[98:99] op_sel:[1,1] op_sel_hi:[1,0]
	v_pk_mul_f32 v[88:89], v[108:109], v[98:99] op_sel:[1,0] op_sel_hi:[1,1]
	v_pk_fma_f32 v[78:79], v[102:103], v[98:99], v[78:79] op_sel:[0,0,0] op_sel_hi:[0,1,1] neg_lo:[0,0,1] neg_hi:[0,0,0]
	v_pk_fma_f32 v[80:81], v[104:105], v[98:99], v[80:81] op_sel:[0,1,0] op_sel_hi:[0,0,1] neg_lo:[0,0,0] neg_hi:[0,1,0]
	v_pk_fma_f32 v[86:87], v[106:107], v[98:99], v[86:87] op_sel:[0,0,0] op_sel_hi:[0,1,1] neg_lo:[0,0,1] neg_hi:[0,0,0]
	v_pk_fma_f32 v[88:89], v[108:109], v[98:99], v[88:89] op_sel:[0,1,0] op_sel_hi:[0,0,1] neg_lo:[0,0,0] neg_hi:[0,1,0]
	v_pk_add_f32 v[102:103], v[74:75], v[76:77] neg_lo:[0,1] neg_hi:[0,1]
	v_pk_add_f32 v[104:105], v[78:79], v[80:81] neg_lo:[0,1] neg_hi:[0,1]
	v_pk_add_f32 v[106:107], v[82:83], v[84:85] neg_lo:[0,1] neg_hi:[0,1]
	v_pk_add_f32 v[108:109], v[86:87], v[88:89] neg_lo:[0,1] neg_hi:[0,1]
	v_pk_add_f32 v[74:75], v[74:75], v[76:77]
	v_pk_add_f32 v[78:79], v[78:79], v[80:81]
	v_pk_add_f32 v[82:83], v[82:83], v[84:85]
	v_pk_add_f32 v[86:87], v[86:87], v[88:89]
	v_pk_mul_f32 v[76:77], v[102:103], v[100:101] op_sel:[1,1] op_sel_hi:[1,0]
	v_pk_mul_f32 v[80:81], v[104:105], v[100:101] op_sel:[1,1] op_sel_hi:[1,0]
	v_pk_mul_f32 v[84:85], v[106:107], v[100:101] op_sel:[1,1] op_sel_hi:[1,0]
	v_pk_mul_f32 v[88:89], v[108:109], v[100:101] op_sel:[1,1] op_sel_hi:[1,0]
	v_pk_fma_f32 v[76:77], v[102:103], v[100:101], v[76:77] op_sel:[0,0,0] op_sel_hi:[0,1,1] neg_lo:[0,0,1] neg_hi:[0,0,0]
	v_pk_fma_f32 v[80:81], v[104:105], v[100:101], v[80:81] op_sel:[0,0,0] op_sel_hi:[0,1,1] neg_lo:[0,0,1] neg_hi:[0,0,0]
	v_pk_fma_f32 v[84:85], v[106:107], v[100:101], v[84:85] op_sel:[0,0,0] op_sel_hi:[0,1,1] neg_lo:[0,0,1] neg_hi:[0,0,0]
	v_pk_fma_f32 v[88:89], v[108:109], v[100:101], v[88:89] op_sel:[0,0,0] op_sel_hi:[0,1,1] neg_lo:[0,0,1] neg_hi:[0,0,0]
	ds_write2_b64 v73, v[74:75], v[76:77] offset1:17
	ds_write2_b64 v73, v[78:79], v[80:81] offset0:34 offset1:51
	ds_write2_b64 v73, v[82:83], v[84:85] offset0:68 offset1:85
	ds_write2_b64 v73, v[86:87], v[88:89] offset0:102 offset1:119
	s_movk_i32 s0, 0x200
	s_and_b64 vcc, exec, s[6:7]
	s_mov_b64 s[6:7], 0
	s_cbranch_vccnz .LBB0_351
; #define LAS __attribute__((address_space(3)))
; __device__ __forceinline__ int otid() { int t = threadIdx.x; asm volatile("" : "+v"(t)); return t; }
; __device__ __forceinline__ cf twc(cf ws, int k16) { if (k16 == 0) return ws; if (k16 == 4) return cf{ws.y, -ws.x}; return cmul(ws, cf{c16(k16), -s16(k16)}); }
; template <int LR> __device__ __forceinline__ void dif_reg(cf (&x)[1 << LR], cf w) {
;     constexpr int R = 1 << LR; cf ws = w;
; #pragma unroll
;     for (int s = 0; s < LR; ++s) { const int half = R >> (s + 1);
; #pragma unroll
;         for (int m0 = 0; m0 < R; m0 += 2 * half)
; #pragma unroll
;             for (int mm = 0; mm < half; ++mm) { const int ia = m0 + mm, ib = ia + half; const cf a = x[ia], b = x[ib];
;                 x[ia] = cf{a.x + b.x, a.y + b.y}; const cf d{a.x - b.x, a.y - b.y};
;                 x[ib] = cmul(d, twc(ws, (mm << s) * (16 / R))); }
;         ws = cmul(ws, ws); }
; }
; __device__ __forceinline__ void fft_conv(ldsf2 buf, const LAS unsigned* spec) {
;     fft_fwd_abc(buf);
;     { const int tid = otid(); cf x[16];
; #pragma unroll
;       for (int m = 0; m < 16; ++m) { const v2f v = buf[tid * 17 + m]; x[m] = cf{v.x, v.y}; }
;       dif_reg<4>(x, cf{1.0f, 0.0f});
	v_mov_b32_e32 v158, v195
	s_movk_i32 s0, 0x88
	s_waitcnt lgkmcnt(0)
	s_mov_b32 s86, s63
	v_mul_lo_u32 v68, v158, s0
	v_add_u32_e32 v147, 0, v68
	ds_read2_b64 v[72:75], v147 offset1:1
	ds_read2_b64 v[76:79], v147 offset0:2 offset1:3
	ds_read2_b64 v[90:93], v147 offset0:4 offset1:5
	ds_read2_b64 v[94:97], v147 offset0:6 offset1:7
	ds_read2_b64 v[98:101], v147 offset0:8 offset1:9
	ds_read2_b64 v[102:105], v147 offset0:10 offset1:11
	ds_read2_b64 v[118:121], v147 offset0:12 offset1:13
	ds_read2_b64 v[126:129], v147 offset0:14 offset1:15
	s_waitcnt lgkmcnt(7)
	v_mov_b32_e32 v69, v74
	s_waitcnt lgkmcnt(3)
	v_pk_add_f32 v[106:107], v[72:73], v[98:99] neg_lo:[0,1] neg_hi:[0,1]
	v_mov_b32_e32 v80, v98
	s_waitcnt lgkmcnt(1)
	v_pk_add_f32 v[132:133], v[90:91], v[118:119] neg_lo:[0,1] neg_hi:[0,1]
	v_sub_f32_e32 v68, v93, v121
	v_mul_f32_e32 v107, 0x3f6c835e, v68
	v_mul_f32_e32 v132, 0x3ec3ef15, v68
	v_mov_b32_e32 v68, v72
	v_mov_b32_e32 v81, v100
	v_pk_add_f32 v[82:83], v[68:69], v[80:81]
	v_mov_b32_e32 v148, v102
	v_mov_b32_e32 v149, v104
	v_mov_b32_e32 v68, v90
	v_mov_b32_e32 v69, v92
	v_mov_b32_e32 v80, v118
	v_mov_b32_e32 v81, v120
	v_mov_b32_e32 v104, v103
	v_mov_b32_e32 v102, v91
	v_mov_b32_e32 v103, v93
	v_mov_b32_e32 v112, v119
	v_mov_b32_e32 v113, v121
	v_pk_add_f32 v[122:123], v[74:75], v[100:101] neg_lo:[0,1] neg_hi:[0,1]
	v_mov_b32_e32 v134, v76
	v_mov_b32_e32 v135, v78
	v_pk_add_f32 v[86:87], v[68:69], v[80:81]
	v_mov_b32_e32 v68, v94
	v_mov_b32_e32 v69, v96
	s_waitcnt lgkmcnt(0)
	v_mov_b32_e32 v80, v126
	v_mov_b32_e32 v81, v128
	v_mov_b32_e32 v74, v73
	v_mov_b32_e32 v100, v99
	v_mov_b32_e32 v78, v77
	v_pk_add_f32 v[102:103], v[102:103], v[112:113]
	v_mov_b32_e32 v112, v95
	v_mov_b32_e32 v113, v97
	v_mov_b32_e32 v114, v127
	v_mov_b32_e32 v115, v129
	v_pk_add_f32 v[84:85], v[134:135], v[148:149]
	v_pk_add_f32 v[88:89], v[68:69], v[80:81]
	v_pk_add_f32 v[110:111], v[74:75], v[100:101]
	v_pk_add_f32 v[76:77], v[78:79], v[104:105]
	v_pk_add_f32 v[150:151], v[112:113], v[114:115]
	v_pk_add_f32 v[80:81], v[82:83], v[86:87]
	v_pk_add_f32 v[108:109], v[84:85], v[88:89]
	v_pk_add_f32 v[112:113], v[110:111], v[102:103]
	v_pk_add_f32 v[114:115], v[76:77], v[150:151]
	v_sub_f32_e32 v68, v83, v87
	v_pk_add_f32 v[124:125], v[112:113], v[114:115]
	v_mov_b32_e32 v116, v80
	v_mov_b32_e32 v117, v113
	v_mov_b32_e32 v156, v108
	v_mov_b32_e32 v157, v115
	v_mov_b32_e32 v113, v81
	v_mov_b32_e32 v115, v109
	v_mul_f32_e32 v130, 0x3f3504f3, v68
	v_pk_add_f32 v[68:69], v[80:81], v[108:109]
	v_pk_add_f32 v[116:117], v[116:117], v[156:157] neg_lo:[0,1] neg_hi:[0,1]
	v_pk_add_f32 v[108:109], v[112:113], v[114:115] neg_lo:[0,1] neg_hi:[0,1]
	v_mov_b32_e32 v83, v85
	v_mov_b32_e32 v87, v89
	v_pk_fma_f32 v[80:81], v[108:109], 0, v[116:117] op_sel_hi:[1,0,1] neg_lo:[1,0,0] neg_hi:[1,0,0]
	v_pk_fma_f32 v[112:113], v[108:109], 0, v[116:117] op_sel_hi:[1,0,1]
	v_pk_fma_f32 v[114:115], v[116:117], 0, v[108:109] op_sel_hi:[1,0,1]
	v_pk_fma_f32 v[116:117], v[116:117], 0, v[108:109] op_sel_hi:[1,0,1] neg_lo:[0,0,1] neg_hi:[0,0,1]
	v_mov_b32_e32 v108, v84
	v_mov_b32_e32 v109, v111
	v_mov_b32_e32 v156, v88
	v_mov_b32_e32 v157, v103
	v_mov_b32_e32 v111, v77
	v_mov_b32_e32 v103, v151
	v_pk_add_f32 v[82:83], v[82:83], v[86:87] neg_lo:[0,1] neg_hi:[0,1]
	v_pk_add_f32 v[152:153], v[76:77], v[150:151] neg_lo:[0,1] neg_hi:[0,1]
	v_pk_add_f32 v[108:109], v[108:109], v[156:157] neg_lo:[0,1] neg_hi:[0,1]
	s_mov_b32 s6, s63
	s_mov_b32 s7, s16
	v_pk_add_f32 v[76:77], v[110:111], v[102:103] neg_lo:[0,1] neg_hi:[0,1]
	v_pk_mul_f32 v[84:85], v[82:83], s[86:87]
	v_pk_mul_f32 v[156:157], v[108:109], s[6:7]
	v_pk_mul_f32 v[102:103], v[76:77], s[86:87]
	v_mov_b32_e32 v153, v130
	v_mov_b32_e32 v84, v82
	v_mul_f32_e32 v154, 0, v152
	v_pk_fma_f32 v[150:151], v[108:109], s[6:7], v[152:153]
	v_mov_b32_e32 v155, v157
	v_mov_b32_e32 v109, v130
	v_pk_fma_f32 v[84:85], v[76:77], s[86:87], v[84:85] neg_lo:[1,0,0] neg_hi:[1,0,0]
	v_mov_b32_e32 v77, v103
	v_pk_add_f32 v[86:87], v[154:155], v[108:109] neg_lo:[0,1] neg_hi:[0,1]
	v_pk_fma_f32 v[76:77], v[82:83], s[86:87], v[76:77]
	v_mov_b32_e32 v82, v84
	v_pk_add_f32 v[110:111], v[76:77], v[86:87]
	v_mov_b32_e32 v83, v87
	v_mov_b32_e32 v88, v150
	v_mov_b32_e32 v89, v77
	v_mov_b32_e32 v77, v151
	v_mov_b32_e32 v87, v85
	v_pk_add_f32 v[88:89], v[82:83], v[88:89] neg_lo:[0,1] neg_hi:[0,1]
	v_pk_add_f32 v[76:77], v[76:77], v[86:87] neg_lo:[0,1] neg_hi:[0,1]
	v_pk_add_f32 v[108:109], v[84:85], v[150:151]
	v_pk_fma_f32 v[82:83], v[76:77], 0, v[88:89] op_sel_hi:[1,0,1] neg_lo:[1,0,0] neg_hi:[1,0,0]
	v_pk_fma_f32 v[84:85], v[76:77], 0, v[88:89] op_sel_hi:[1,0,1]
	v_pk_fma_f32 v[86:87], v[88:89], 0, v[76:77] op_sel_hi:[1,0,1]
	v_pk_fma_f32 v[88:89], v[88:89], 0, v[76:77] op_sel_hi:[1,0,1] neg_lo:[0,0,1] neg_hi:[0,0,1]
	v_pk_mov_b32 v[72:73], v[72:73], v[92:93] op_sel:[1,0]
	v_pk_mov_b32 v[76:77], v[98:99], v[120:121] op_sel:[1,0]
	v_mov_b32_e32 v91, v75
	v_mov_b32_e32 v119, v101
	v_pk_add_f32 v[72:73], v[72:73], v[76:77] neg_lo:[0,1] neg_hi:[0,1]
	v_pk_add_f32 v[76:77], v[90:91], v[118:119] neg_lo:[0,1] neg_hi:[0,1]
	v_mul_f32_e32 v92, 0x3ec3ef15, v122
	v_pk_mov_b32 v[90:91], v[76:77], v[122:123] op_sel:[1,0]
	v_pk_add_f32 v[78:79], v[78:79], v[104:105] neg_lo:[0,1] neg_hi:[0,1]
	v_pk_fma_f32 v[90:91], v[90:91], s[4:5], v[92:93] op_sel_hi:[1,1,0] neg_lo:[0,0,1] neg_hi:[0,0,1]
	v_pk_add_f32 v[92:93], v[134:135], v[148:149] neg_lo:[0,1] neg_hi:[0,1]
	s_mov_b32 s17, s5
	s_mov_b32 s0, s16
	s_mov_b32 s1, s4
	v_pk_mul_f32 v[98:99], v[92:93], s[16:17]
	v_pk_mul_f32 v[100:101], v[78:79], s[0:1]
	s_mov_b32 s0, s63
	s_mov_b32 s1, s5
	v_mul_f32_e32 v131, 0x3f6c835e, v122
; __device__ __forceinline__ int otid() { int t = threadIdx.x; asm volatile("" : "+v"(t)); return t; }
; __device__ __forceinline__ cf twc(cf ws, int k16) { if (k16 == 0) return ws; if (k16 == 4) return cf{ws.y, -ws.x}; return cmul(ws, cf{c16(k16), -s16(k16)}); }
; template <int LR> __device__ __forceinline__ void dif_reg(cf (&x)[1 << LR], cf w) {
;     constexpr int R = 1 << LR; cf ws = w;
; #pragma unroll
;     for (int s = 0; s < LR; ++s) { const int half = R >> (s + 1);
; #pragma unroll
;         for (int m0 = 0; m0 < R; m0 += 2 * half)
; #pragma unroll
;             for (int mm = 0; mm < half; ++mm) { const int ia = m0 + mm, ib = ia + half; const cf a = x[ia], b = x[ib];
;                 x[ia] = cf{a.x + b.x, a.y + b.y}; const cf d{a.x - b.x, a.y - b.y};
;                 x[ib] = cmul(d, twc(ws, (mm << s) * (16 / R))); }
;         ws = cmul(ws, ws); }
; }
; __device__ __forceinline__ void fft_conv(ldsf2 buf, const LAS unsigned* spec) {
;     ...
;     { const int tid = otid(); cf x[16];
; #pragma unroll
;       for (int m = 0; m < 16; ++m) { const v2f v = buf[tid * 17 + m]; x[m] = cf{v.x, v.y}; }
;       dif_reg<4>(x, cf{1.0f, 0.0f});
; #pragma unroll
;       for (int m = 0; m < 16; ++m) { const h2_t hv = __builtin_bit_cast(h2_t, spec[tid * 17 + m]); x[m] = cmul(x[m], cf{(float)hv.x, (float)hv.y}); }
	v_fma_f32 v74, 0, v106, v72
	v_pk_fma_f32 v[104:105], v[92:93], s[16:17], v[100:101]
	v_mul_f32_e32 v99, 0x3f6c835e, v93
	v_mov_b32_e32 v130, v133
	v_pk_fma_f32 v[92:93], v[72:73], s[0:1], v[106:107] neg_lo:[1,0,0] neg_hi:[1,0,0]
	v_pk_mov_b32 v[102:103], v[94:95], v[96:97] op_sel:[1,0]
	v_pk_mov_b32 v[106:107], v[126:127], v[128:129] op_sel:[1,0]
	v_mul_f32_e32 v101, 0x3ec3ef15, v79
	v_pk_fma_f32 v[78:79], v[76:77], s[0:1], v[130:131]
	v_pk_add_f32 v[102:103], v[102:103], v[106:107] neg_lo:[0,1] neg_hi:[0,1]
	v_mov_b32_e32 v95, v97
	v_mov_b32_e32 v127, v129
	s_mov_b32 s0, s87
	s_mov_b32 s1, s4
	v_pk_add_f32 v[94:95], v[94:95], v[126:127] neg_lo:[0,1] neg_hi:[0,1]
	v_pk_mul_f32 v[96:97], v[102:103], s[0:1]
	s_mov_b32 s1, s5
	v_pk_fma_f32 v[106:107], v[94:95], s[0:1], v[96:97]
	v_pk_fma_f32 v[120:121], v[94:95], s[0:1], v[96:97] neg_lo:[0,0,1] neg_hi:[0,0,1]
	v_mov_b32_e32 v94, v103
	s_mov_b32 s35, s4
	v_mul_f32_e32 v72, 0x3f6c835e, v95
	v_pk_fma_f32 v[122:123], v[94:95], s[34:35], v[72:73] op_sel_hi:[1,1,0] neg_lo:[0,0,1] neg_hi:[0,0,1]
	v_mov_b32_e32 v72, v133
	s_mov_b32 s12, s63
	v_mov_b32_e32 v77, v132
	v_pk_add_f32 v[128:129], v[100:101], v[98:99] neg_lo:[0,1] neg_hi:[0,1]
	v_pk_fma_f32 v[72:73], v[72:73], s[12:13], v[76:77] neg_lo:[0,0,1] neg_hi:[0,0,1]
	v_mov_b32_e32 v75, v90
	v_mov_b32_e32 v107, v122
	v_pk_add_f32 v[94:95], v[92:93], v[78:79]
	v_pk_add_f32 v[96:97], v[104:105], v[120:121]
	v_pk_add_f32 v[76:77], v[74:75], v[72:73]
	v_pk_add_f32 v[98:99], v[128:129], v[106:107]
	v_mov_b32_e32 v100, v94
	v_pk_add_f32 v[118:119], v[76:77], v[98:99]
	v_mov_b32_e32 v101, v77
	v_mov_b32_e32 v130, v96
	v_mov_b32_e32 v131, v99
	v_mov_b32_e32 v77, v95
	v_mov_b32_e32 v99, v97
	v_pk_add_f32 v[100:101], v[100:101], v[130:131] neg_lo:[0,1] neg_hi:[0,1]
	v_pk_add_f32 v[76:77], v[76:77], v[98:99] neg_lo:[0,1] neg_hi:[0,1]
	v_pk_add_f32 v[126:127], v[78:79], v[92:93] neg_lo:[0,1] neg_hi:[0,1]
	v_pk_add_f32 v[102:103], v[94:95], v[96:97]
	v_pk_fma_f32 v[94:95], v[76:77], 0, v[100:101] op_sel_hi:[1,0,1] neg_lo:[1,0,0] neg_hi:[1,0,0]
	v_pk_fma_f32 v[96:97], v[76:77], 0, v[100:101] op_sel_hi:[1,0,1]
	v_pk_fma_f32 v[98:99], v[100:101], 0, v[76:77] op_sel_hi:[1,0,1]
	v_pk_fma_f32 v[100:101], v[100:101], 0, v[76:77] op_sel_hi:[1,0,1] neg_lo:[0,0,1] neg_hi:[0,0,1]
	v_mov_b32_e32 v75, v129
	v_mov_b32_e32 v76, v72
	v_mov_b32_e32 v77, v122
	v_pk_add_f32 v[74:75], v[74:75], v[76:77] neg_lo:[0,1] neg_hi:[0,1]
	v_mov_b32_e32 v76, v104
	v_mov_b32_e32 v77, v90
	v_mov_b32_e32 v72, v120
	v_mov_b32_e32 v129, v245
	v_mov_b32_e32 v107, v127
	v_mov_b32_e32 v93, v105
	v_mov_b32_e32 v79, v121
	v_pk_add_f32 v[72:73], v[76:77], v[72:73] neg_lo:[0,1] neg_hi:[0,1]
	v_pk_add_f32 v[90:91], v[128:129], v[106:107] neg_lo:[0,1] neg_hi:[0,1]
	v_pk_mul_f32 v[106:107], v[128:129], v[106:107]
	v_pk_add_f32 v[78:79], v[92:93], v[78:79] neg_lo:[0,1] neg_hi:[0,1]
	v_pk_mul_f32 v[76:77], v[72:73], s[6:7]
	v_mov_b32_e32 v91, v107
	v_pk_mul_f32 v[92:93], v[78:79], s[86:87]
	v_pk_fma_f32 v[122:123], v[72:73], s[6:7], v[90:91]
	v_mul_f32_e32 v76, 0, v90
	v_pk_mul_f32 v[90:91], v[74:75], s[86:87]
	v_mov_b32_e32 v73, v107
	v_mov_b32_e32 v92, v78
	v_pk_add_f32 v[72:73], v[76:77], v[72:73] neg_lo:[0,1] neg_hi:[0,1]
	v_pk_fma_f32 v[76:77], v[74:75], s[86:87], v[92:93] neg_lo:[1,0,0] neg_hi:[1,0,0]
	v_mov_b32_e32 v75, v91
	v_pk_fma_f32 v[74:75], v[78:79], s[86:87], v[74:75]
	v_mov_b32_e32 v78, v76
	v_pk_add_f32 v[92:93], v[74:75], v[72:73]
	v_mov_b32_e32 v79, v73
	v_mov_b32_e32 v104, v122
	v_mov_b32_e32 v105, v75
	v_mov_b32_e32 v75, v123
	v_mov_b32_e32 v73, v77
	v_pk_add_f32 v[78:79], v[78:79], v[104:105] neg_lo:[0,1] neg_hi:[0,1]
	v_pk_add_f32 v[104:105], v[74:75], v[72:73] neg_lo:[0,1] neg_hi:[0,1]
	v_pk_add_f32 v[90:91], v[76:77], v[122:123]
	v_pk_fma_f32 v[72:73], v[104:105], 0, v[78:79] op_sel_hi:[1,0,1] neg_lo:[1,0,0] neg_hi:[1,0,0]
	v_pk_fma_f32 v[74:75], v[104:105], 0, v[78:79] op_sel_hi:[1,0,1]
	v_pk_fma_f32 v[76:77], v[78:79], 0, v[104:105] op_sel_hi:[1,0,1]
	v_pk_fma_f32 v[78:79], v[78:79], 0, v[104:105] op_sel_hi:[1,0,1] neg_lo:[0,0,1] neg_hi:[0,0,1]
	v_mov_b32_e32 v104, v68
	v_mov_b32_e32 v105, v124
	v_mov_b32_e32 v106, v69
	v_mov_b32_e32 v107, v125
	v_pk_add_f32 v[128:129], v[104:105], v[106:107] neg_lo:[0,1] neg_hi:[0,1]
	v_mov_b32_e32 v104, v80
	v_mov_b32_e32 v105, v114
	v_mov_b32_e32 v106, v113
	v_mov_b32_e32 v107, v117
	v_pk_add_f32 v[150:151], v[104:105], v[106:107] neg_lo:[0,1] neg_hi:[0,1]
	v_mov_b32_e32 v104, v108
	v_mov_b32_e32 v105, v110
	v_mov_b32_e32 v106, v109
	v_mov_b32_e32 v107, v111
	v_pk_add_f32 v[154:155], v[104:105], v[106:107] neg_lo:[0,1] neg_hi:[0,1]
	v_mov_b32_e32 v104, v82
	v_mov_b32_e32 v105, v86
	v_mov_b32_e32 v106, v85
	v_mov_b32_e32 v107, v89
	v_pk_add_f32 v[132:133], v[104:105], v[106:107] neg_lo:[0,1] neg_hi:[0,1]
	v_mov_b32_e32 v104, v102
	v_mov_b32_e32 v105, v118
	v_mov_b32_e32 v106, v103
	v_mov_b32_e32 v107, v119
	v_pk_add_f32 v[126:127], v[104:105], v[106:107] neg_lo:[0,1] neg_hi:[0,1]
	v_mov_b32_e32 v104, v94
	v_mov_b32_e32 v105, v98
	v_mov_b32_e32 v106, v97
	v_mov_b32_e32 v107, v101
	v_pk_add_f32 v[122:123], v[104:105], v[106:107] neg_lo:[0,1] neg_hi:[0,1]
	v_mov_b32_e32 v104, v90
	v_mov_b32_e32 v105, v92
	v_mov_b32_e32 v106, v91
	v_mov_b32_e32 v107, v93
	v_pk_add_f32 v[104:105], v[104:105], v[106:107] neg_lo:[0,1] neg_hi:[0,1]
	v_mov_b32_e32 v106, v72
	v_mov_b32_e32 v107, v76
	v_mov_b32_e32 v120, v75
	v_mov_b32_e32 v121, v79
	v_pk_add_f32 v[106:107], v[106:107], v[120:121] neg_lo:[0,1] neg_hi:[0,1]
	s_movk_i32 s0, 0x44
	v_fmamk_f32 v136, v133, 0x80000000, v132
	v_fmac_f32_e32 v133, 0, v132
	v_fmamk_f32 v132, v127, 0x80000000, v126
	v_fmac_f32_e32 v127, 0, v126
	v_fmamk_f32 v126, v123, 0x80000000, v122
	v_fmac_f32_e32 v123, 0, v122
	v_fmamk_f32 v122, v105, 0x80000000, v104
	v_fmac_f32_e32 v105, 0, v104
	v_fmamk_f32 v104, v107, 0x80000000, v106
	v_fmac_f32_e32 v107, 0, v106
	v_mul_lo_u32 v106, v158, s0
	v_add_u32_e32 v106, 0, v106
	v_add_u32_e32 v106, 0x11000, v106
	ds_read2_b32 v[156:157], v106 offset1:1
	ds_read2_b32 v[158:159], v106 offset0:2 offset1:3
	ds_read2_b32 v[160:161], v106 offset0:4 offset1:5
	ds_read2_b32 v[162:163], v106 offset0:6 offset1:7
	ds_read2_b32 v[164:165], v106 offset0:8 offset1:9
	ds_read2_b32 v[134:135], v106 offset0:10 offset1:11
	ds_read2_b32 v[130:131], v106 offset0:12 offset1:13
	ds_read2_b32 v[120:121], v106 offset0:14 offset1:15
	s_waitcnt lgkmcnt(7)
; __device__ __forceinline__ void fft_conv(ldsf2 buf, const LAS unsigned* spec) {
;     ...
;       for (int m = 0; m < 16; ++m) { const v2f v = buf[tid * 17 + m]; x[m] = cf{v.x, v.y}; }
;       dif_reg<4>(x, cf{1.0f, 0.0f});
; #pragma unroll
;       for (int m = 0; m < 16; ++m) { const h2_t hv = __builtin_bit_cast(h2_t, spec[tid * 17 + m]); x[m] = cmul(x[m], cf{(float)hv.x, (float)hv.y}); }
	v_cvt_f32_f16_e32 v166, v156
	v_cvt_f32_f16_sdwa v167, v156 dst_sel:DWORD dst_unused:UNUSED_PAD src0_sel:WORD_1
	v_cvt_f32_f16_e32 v156, v157
	v_cvt_f32_f16_sdwa v157, v157 dst_sel:DWORD dst_unused:UNUSED_PAD src0_sel:WORD_1
	v_fmamk_f32 v148, v129, 0x80000000, v128
	v_fmac_f32_e32 v129, 0, v128
	v_pk_add_f32 v[168:169], v[68:69], v[68:69] op_sel:[0,1] op_sel_hi:[0,1]
	v_pk_add_f32 v[68:69], v[124:125], v[124:125] op_sel:[0,1] op_sel_hi:[0,1]
	v_pk_mul_f32 v[124:125], v[68:69], v[166:167] op_sel:[0,1] op_sel_hi:[1,0]
	v_mov_b32_e32 v106, v129
	v_pk_fma_f32 v[68:69], v[168:169], v[166:167], v[124:125] neg_lo:[0,0,1] neg_hi:[0,0,1]
	v_pk_fma_f32 v[124:125], v[168:169], v[166:167], v[124:125]
	v_pk_mul_f32 v[128:129], v[106:107], v[156:157] op_sel:[0,1] op_sel_hi:[0,0]
	v_mov_b32_e32 v69, v125
	v_pk_fma_f32 v[124:125], v[148:149], v[156:157], v[128:129] op_sel_hi:[0,1,1] neg_lo:[0,0,1] neg_hi:[0,0,1]
	v_pk_fma_f32 v[128:129], v[148:149], v[156:157], v[128:129] op_sel_hi:[0,1,1]
	s_waitcnt lgkmcnt(6)
	v_cvt_f32_f16_e32 v148, v158
	v_cvt_f32_f16_sdwa v149, v158 dst_sel:DWORD dst_unused:UNUSED_PAD src0_sel:WORD_1
	v_pk_add_f32 v[112:113], v[80:81], v[112:113] op_sel:[0,1] op_sel_hi:[0,1]
	v_pk_add_f32 v[80:81], v[114:115], v[116:117] op_sel:[0,1] op_sel_hi:[0,1]
	v_fmamk_f32 v152, v151, 0x80000000, v150
	v_pk_mul_f32 v[114:115], v[80:81], v[148:149] op_sel:[0,1] op_sel_hi:[1,0]
	v_fmac_f32_e32 v151, 0, v150
	v_pk_fma_f32 v[80:81], v[112:113], v[148:149], v[114:115] neg_lo:[0,0,1] neg_hi:[0,0,1]
	v_pk_fma_f32 v[112:113], v[112:113], v[148:149], v[114:115]
	v_cvt_f32_f16_e32 v114, v159
	v_cvt_f32_f16_sdwa v115, v159 dst_sel:DWORD dst_unused:UNUSED_PAD src0_sel:WORD_1
	v_mov_b32_e32 v106, v151
	v_mov_b32_e32 v81, v113
	v_pk_add_f32 v[148:149], v[108:109], v[108:109] op_sel:[0,1] op_sel_hi:[0,1]
	v_pk_mul_f32 v[116:117], v[106:107], v[114:115] op_sel:[0,1] op_sel_hi:[0,0]
	v_pk_fma_f32 v[112:113], v[152:153], v[114:115], v[116:117] op_sel_hi:[0,1,1] neg_lo:[0,0,1] neg_hi:[0,0,1]
	v_pk_fma_f32 v[114:115], v[152:153], v[114:115], v[116:117] op_sel_hi:[0,1,1]
	s_waitcnt lgkmcnt(5)
	v_cvt_f32_f16_e32 v116, v160
	v_cvt_f32_f16_sdwa v117, v160 dst_sel:DWORD dst_unused:UNUSED_PAD src0_sel:WORD_1
	v_pk_add_f32 v[108:109], v[110:111], v[110:111] op_sel:[0,1] op_sel_hi:[0,1]
	v_fmamk_f32 v150, v155, 0x80000000, v154
	v_fmac_f32_e32 v155, 0, v154
	v_pk_mul_f32 v[110:111], v[108:109], v[116:117] op_sel:[0,1] op_sel_hi:[1,0]
	v_mov_b32_e32 v106, v155
	v_pk_fma_f32 v[108:109], v[148:149], v[116:117], v[110:111] neg_lo:[0,0,1] neg_hi:[0,0,1]
	v_pk_fma_f32 v[110:111], v[148:149], v[116:117], v[110:111]
	v_cvt_f32_f16_e32 v116, v161
	v_cvt_f32_f16_sdwa v117, v161 dst_sel:DWORD dst_unused:UNUSED_PAD src0_sel:WORD_1
	v_pk_add_f32 v[82:83], v[82:83], v[84:85] op_sel:[0,1] op_sel_hi:[0,1]
	v_pk_add_f32 v[84:85], v[86:87], v[88:89] op_sel:[0,1] op_sel_hi:[0,1]
	v_pk_add_f32 v[102:103], v[102:103], v[102:103] op_sel:[0,1] op_sel_hi:[0,1]
	v_pk_mul_f32 v[148:149], v[106:107], v[116:117] op_sel:[0,1] op_sel_hi:[0,0]
	v_pk_fma_f32 v[152:153], v[150:151], v[116:117], v[148:149] op_sel_hi:[0,1,1] neg_lo:[0,0,1] neg_hi:[0,0,1]
	v_pk_fma_f32 v[116:117], v[150:151], v[116:117], v[148:149] op_sel_hi:[0,1,1]
	s_waitcnt lgkmcnt(4)
	v_cvt_f32_f16_e32 v150, v162
	v_cvt_f32_f16_sdwa v151, v162 dst_sel:DWORD dst_unused:UNUSED_PAD src0_sel:WORD_1
	v_pk_add_f32 v[94:95], v[94:95], v[96:97] op_sel:[0,1] op_sel_hi:[0,1]
	v_pk_add_f32 v[92:93], v[92:93], v[92:93] op_sel:[0,1] op_sel_hi:[0,1]
	v_pk_add_f32 v[90:91], v[90:91], v[90:91] op_sel:[0,1] op_sel_hi:[0,1]
	v_pk_mul_f32 v[84:85], v[84:85], v[150:151] op_sel:[0,1] op_sel_hi:[1,0]
	v_pk_add_f32 v[72:73], v[72:73], v[74:75] op_sel:[0,1] op_sel_hi:[0,1]
	v_pk_fma_f32 v[86:87], v[82:83], v[150:151], v[84:85] neg_lo:[0,0,1] neg_hi:[0,0,1]
	v_pk_fma_f32 v[82:83], v[82:83], v[150:151], v[84:85]
	v_mov_b32_e32 v84, v133
	v_mov_b32_e32 v87, v83
	v_cvt_f32_f16_e32 v82, v163
	v_cvt_f32_f16_sdwa v83, v163 dst_sel:DWORD dst_unused:UNUSED_PAD src0_sel:WORD_1
	v_pk_add_f32 v[74:75], v[76:77], v[78:79] op_sel:[0,1] op_sel_hi:[0,1]
	v_mov_b32_e32 v148, v152
	v_mov_b32_e32 v149, v117
	v_pk_mul_f32 v[84:85], v[84:85], v[82:83] op_sel:[0,1] op_sel_hi:[0,0]
	v_pk_fma_f32 v[88:89], v[136:137], v[82:83], v[84:85] op_sel_hi:[0,1,1] neg_lo:[0,0,1] neg_hi:[0,0,1]
	v_pk_fma_f32 v[150:151], v[136:137], v[82:83], v[84:85] op_sel_hi:[0,1,1]
	s_waitcnt lgkmcnt(3)
	v_cvt_f32_f16_e32 v84, v164
	v_cvt_f32_f16_sdwa v85, v164 dst_sel:DWORD dst_unused:UNUSED_PAD src0_sel:WORD_1
	v_pk_add_f32 v[82:83], v[118:119], v[118:119] op_sel:[0,1] op_sel_hi:[0,1]
	v_mov_b32_e32 v109, v111
	s_mov_b32 s0, s5
	v_pk_mul_f32 v[118:119], v[82:83], v[84:85] op_sel:[0,1] op_sel_hi:[1,0]
	s_mov_b64 s[6:7], -1
	v_pk_fma_f32 v[82:83], v[102:103], v[84:85], v[118:119] neg_lo:[0,0,1] neg_hi:[0,0,1]
	v_pk_fma_f32 v[84:85], v[102:103], v[84:85], v[118:119]
	v_mov_b32_e32 v102, v127
	v_mov_b32_e32 v83, v85
	v_cvt_f32_f16_e32 v84, v165
	v_cvt_f32_f16_sdwa v85, v165 dst_sel:DWORD dst_unused:UNUSED_PAD src0_sel:WORD_1
	v_pk_mul_f32 v[102:103], v[102:103], v[84:85] op_sel:[0,1] op_sel_hi:[0,0]
	v_pk_fma_f32 v[118:119], v[132:133], v[84:85], v[102:103] op_sel_hi:[0,1,1] neg_lo:[0,0,1] neg_hi:[0,0,1]
	v_pk_fma_f32 v[102:103], v[132:133], v[84:85], v[102:103] op_sel_hi:[0,1,1]
	s_waitcnt lgkmcnt(2)
; __device__ __forceinline__ cf twc(cf ws, int k16) { if (k16 == 0) return ws; if (k16 == 4) return cf{ws.y, -ws.x}; return cmul(ws, cf{c16(k16), -s16(k16)}); }
; template <int LR> __device__ __forceinline__ void dit_reg(cf (&x)[1 << LR], cf w) {
;     constexpr int R = 1 << LR; cf wsv[LR]; wsv[0] = w;
; #pragma unroll
;     for (int s = 1; s < LR; ++s) wsv[s] = cmul(wsv[s - 1], wsv[s - 1]);
; #pragma unroll
;     for (int s = LR - 1; s >= 0; --s) { const int half = R >> (s + 1);
; #pragma unroll
;         for (int m0 = 0; m0 < R; m0 += 2 * half)
; #pragma unroll
;             for (int mm = 0; mm < half; ++mm) { const int ia = m0 + mm, ib = ia + half; const cf a = x[ia];
;                 const cf b = cmulc(x[ib], twc(wsv[s], (mm << s) * (16 / R)));
;                 x[ia] = cf{a.x + b.x, a.y + b.y}; x[ib] = cf{a.x - b.x, a.y - b.y}; } }
; }
; __device__ __forceinline__ void fft_conv(ldsf2 buf, const LAS unsigned* spec) {
;     ...
;       for (int m = 0; m < 16; ++m) { const h2_t hv = __builtin_bit_cast(h2_t, spec[tid * 17 + m]); x[m] = cmul(x[m], cf{(float)hv.x, (float)hv.y}); }
;       dit_reg<4>(x, cf{1.0f, 0.0f});
	v_cvt_f32_f16_e32 v132, v134
	v_cvt_f32_f16_sdwa v133, v134 dst_sel:DWORD dst_unused:UNUSED_PAD src0_sel:WORD_1
	v_pk_add_f32 v[84:85], v[98:99], v[100:101] op_sel:[0,1] op_sel_hi:[0,1]
	v_pk_mul_f32 v[96:97], v[84:85], v[132:133] op_sel:[0,1] op_sel_hi:[1,0]
	s_nop 0
	v_pk_fma_f32 v[84:85], v[94:95], v[132:133], v[96:97] neg_lo:[0,0,1] neg_hi:[0,0,1]
	v_pk_fma_f32 v[94:95], v[94:95], v[132:133], v[96:97]
	v_mov_b32_e32 v96, v123
	v_mov_b32_e32 v85, v95
	v_cvt_f32_f16_e32 v94, v135
	v_cvt_f32_f16_sdwa v95, v135 dst_sel:DWORD dst_unused:UNUSED_PAD src0_sel:WORD_1
	v_pk_mul_f32 v[96:97], v[96:97], v[94:95] op_sel:[0,1] op_sel_hi:[0,0]
	v_pk_fma_f32 v[98:99], v[126:127], v[94:95], v[96:97] op_sel_hi:[0,1,1] neg_lo:[0,0,1] neg_hi:[0,0,1]
	v_pk_fma_f32 v[94:95], v[126:127], v[94:95], v[96:97] op_sel_hi:[0,1,1]
	s_waitcnt lgkmcnt(1)
	v_cvt_f32_f16_e32 v96, v130
	v_cvt_f32_f16_sdwa v97, v130 dst_sel:DWORD dst_unused:UNUSED_PAD src0_sel:WORD_1
	v_pk_mul_f32 v[92:93], v[92:93], v[96:97] op_sel:[0,1] op_sel_hi:[1,0]
	s_nop 0
	v_pk_fma_f32 v[100:101], v[90:91], v[96:97], v[92:93] neg_lo:[0,0,1] neg_hi:[0,0,1]
	v_pk_fma_f32 v[90:91], v[90:91], v[96:97], v[92:93]
	v_cvt_f32_f16_e32 v92, v131
	v_cvt_f32_f16_sdwa v93, v131 dst_sel:DWORD dst_unused:UNUSED_PAD src0_sel:WORD_1
	v_mov_b32_e32 v90, v105
	v_mov_b32_e32 v101, v91
	v_pk_mul_f32 v[96:97], v[90:91], v[92:93] op_sel:[0,1] op_sel_hi:[0,0]
	v_pk_fma_f32 v[126:127], v[122:123], v[92:93], v[96:97] op_sel_hi:[0,1,1] neg_lo:[0,0,1] neg_hi:[0,0,1]
	v_pk_fma_f32 v[92:93], v[122:123], v[92:93], v[96:97] op_sel_hi:[0,1,1]
	s_waitcnt lgkmcnt(0)
	v_cvt_f32_f16_e32 v122, v120
	v_cvt_f32_f16_sdwa v123, v120 dst_sel:DWORD dst_unused:UNUSED_PAD src0_sel:WORD_1
	v_mov_b32_e32 v97, v93
	v_mov_b32_e32 v96, v126
	v_pk_mul_f32 v[74:75], v[74:75], v[122:123] op_sel:[0,1] op_sel_hi:[1,0]
	s_nop 0
	v_pk_fma_f32 v[76:77], v[72:73], v[122:123], v[74:75] neg_lo:[0,0,1] neg_hi:[0,0,1]
	v_pk_fma_f32 v[72:73], v[72:73], v[122:123], v[74:75]
	v_mov_b32_e32 v74, v107
	v_pk_mov_b32 v[106:107], v[114:115], v[112:113] op_sel:[1,0]
	v_mov_b32_e32 v77, v73
	v_pk_fma_f32 v[112:113], v[106:107], 0, v[112:113] op_sel_hi:[1,0,1]
	v_pk_fma_f32 v[106:107], v[106:107], 0, v[114:115] op_sel_hi:[1,0,1] neg_lo:[1,0,0] neg_hi:[1,0,0]
	v_pk_mov_b32 v[114:115], v[116:117], v[152:153] op_sel:[1,0]
	v_cvt_f32_f16_e32 v72, v121
	v_cvt_f32_f16_sdwa v73, v121 dst_sel:DWORD dst_unused:UNUSED_PAD src0_sel:WORD_1
	v_pk_fma_f32 v[120:121], v[114:115], 0, v[148:149] op_sel_hi:[1,0,1]
	v_pk_fma_f32 v[114:115], v[114:115], 0, v[116:117] op_sel_hi:[1,0,1] neg_lo:[1,0,0] neg_hi:[1,0,0]
	v_mov_b32_e32 v113, v107
	v_sub_f32_e32 v122, v111, v115
	v_pk_mov_b32 v[110:111], v[150:151], v[88:89] op_sel:[1,0]
	v_mov_b32_e32 v121, v115
	v_pk_fma_f32 v[88:89], v[110:111], 0, v[88:89] op_sel_hi:[1,0,1]
	v_pk_fma_f32 v[110:111], v[110:111], 0, v[150:151] op_sel_hi:[1,0,1] neg_lo:[1,0,0] neg_hi:[1,0,0]
	v_pk_mul_f32 v[74:75], v[74:75], v[72:73] op_sel:[0,1] op_sel_hi:[0,0]
	v_mov_b32_e32 v89, v111
	v_pk_add_f32 v[110:111], v[86:87], v[88:89]
	v_pk_add_f32 v[86:87], v[86:87], v[88:89] neg_lo:[0,1] neg_hi:[0,1]
	v_pk_mov_b32 v[88:89], v[102:103], v[118:119] op_sel:[1,0]
	v_pk_fma_f32 v[78:79], v[104:105], v[72:73], v[74:75] op_sel_hi:[0,1,1] neg_lo:[0,0,1] neg_hi:[0,0,1]
	v_pk_fma_f32 v[114:115], v[88:89], 0, v[118:119] op_sel_hi:[1,0,1]
	v_pk_fma_f32 v[88:89], v[88:89], 0, v[102:103] op_sel_hi:[1,0,1] neg_lo:[1,0,0] neg_hi:[1,0,0]
	v_pk_mov_b32 v[102:103], v[94:95], v[98:99] op_sel:[1,0]
	v_pk_fma_f32 v[72:73], v[104:105], v[72:73], v[74:75] op_sel_hi:[0,1,1]
	v_pk_fma_f32 v[98:99], v[102:103], 0, v[98:99] op_sel_hi:[1,0,1]
	v_pk_fma_f32 v[94:95], v[102:103], 0, v[94:95] op_sel_hi:[1,0,1] neg_lo:[1,0,0] neg_hi:[1,0,0]
	v_pk_mov_b32 v[102:103], v[92:93], v[126:127] op_sel:[1,0]
	v_mov_b32_e32 v99, v95
	v_pk_fma_f32 v[92:93], v[102:103], 0, v[92:93] op_sel_hi:[1,0,1] neg_lo:[1,0,0] neg_hi:[1,0,0]
	v_pk_add_f32 v[116:117], v[108:109], v[120:121]
	v_sub_f32_e32 v118, v91, v93
	v_pk_mov_b32 v[90:91], v[72:73], v[78:79] op_sel:[1,0]
	v_pk_add_f32 v[94:95], v[84:85], v[98:99]
	v_pk_fma_f32 v[78:79], v[90:91], 0, v[78:79] op_sel_hi:[1,0,1]
	v_pk_fma_f32 v[72:73], v[90:91], 0, v[72:73] op_sel_hi:[1,0,1] neg_lo:[1,0,0] neg_hi:[1,0,0]
	v_mul_f32_e32 v109, 0, v86
	v_mov_b32_e32 v121, v87
	v_fmac_f32_e32 v86, 0, v87
	v_mov_b32_e32 v115, v89
	v_mov_b32_e32 v79, v73
	v_pk_add_f32 v[108:109], v[108:109], v[120:121] neg_lo:[0,1] neg_hi:[0,1]
	v_add_f32_e32 v120, v122, v86
	v_sub_f32_e32 v122, v122, v86
	v_pk_mul_f32 v[86:87], v[94:95], 0 op_sel_hi:[1,0]
	v_pk_add_f32 v[106:107], v[80:81], v[112:113]
	v_pk_add_f32 v[88:89], v[82:83], v[114:115]
	v_pk_fma_f32 v[96:97], v[102:103], 0, v[96:97] op_sel_hi:[1,0,1]
	v_pk_add_f32 v[72:73], v[76:77], v[78:79]
	v_add_f32_e32 v119, v108, v109
	v_sub_f32_e32 v121, v108, v109
	v_pk_add_f32 v[108:109], v[94:95], v[86:87] op_sel:[0,1] op_sel_hi:[1,0]
	v_pk_add_f32 v[86:87], v[94:95], v[86:87] op_sel:[0,1] op_sel_hi:[1,0] neg_lo:[0,1] neg_hi:[0,1]
	v_mov_b32_e32 v97, v93
	v_pk_add_f32 v[76:77], v[76:77], v[78:79] neg_lo:[0,1] neg_hi:[0,1]
	v_pk_mul_f32 v[78:79], v[106:107], 0 op_sel_hi:[1,0]
	v_pk_mul_f32 v[92:93], v[110:111], 0 op_sel_hi:[1,0]
	v_mov_b32_e32 v109, v87
	v_sub_f32_e32 v123, v89, v87
	v_pk_mul_f32 v[86:87], v[72:73], 0 op_sel_hi:[1,0]
	v_pk_add_f32 v[90:91], v[106:107], v[78:79] op_sel:[0,1] op_sel_hi:[1,0]
	v_pk_add_f32 v[78:79], v[106:107], v[78:79] op_sel:[0,1] op_sel_hi:[1,0] neg_lo:[0,1] neg_hi:[0,1]
	v_pk_add_f32 v[106:107], v[110:111], v[92:93] op_sel:[0,1] op_sel_hi:[1,0]
	v_pk_add_f32 v[92:93], v[110:111], v[92:93] op_sel:[0,1] op_sel_hi:[1,0] neg_lo:[0,1] neg_hi:[0,1]
; __device__ __forceinline__ cf twc(cf ws, int k16) { if (k16 == 0) return ws; if (k16 == 4) return cf{ws.y, -ws.x}; return cmul(ws, cf{c16(k16), -s16(k16)}); }
; template <int LR> __device__ __forceinline__ void dit_reg(cf (&x)[1 << LR], cf w) {
;     constexpr int R = 1 << LR; cf wsv[LR]; wsv[0] = w;
; #pragma unroll
;     for (int s = 1; s < LR; ++s) wsv[s] = cmul(wsv[s - 1], wsv[s - 1]);
; #pragma unroll
;     for (int s = LR - 1; s >= 0; --s) { const int half = R >> (s + 1);
; #pragma unroll
;         for (int m0 = 0; m0 < R; m0 += 2 * half)
; #pragma unroll
;             for (int mm = 0; mm < half; ++mm) { const int ia = m0 + mm, ib = ia + half; const cf a = x[ia];
;                 const cf b = cmulc(x[ib], twc(wsv[s], (mm << s) * (16 / R)));
;                 x[ia] = cf{a.x + b.x, a.y + b.y}; x[ib] = cf{a.x - b.x, a.y - b.y}; } }
; }
	v_pk_add_f32 v[110:111], v[72:73], v[86:87] op_sel:[0,1] op_sel_hi:[1,0]
	v_pk_add_f32 v[72:73], v[72:73], v[86:87] op_sel:[0,1] op_sel_hi:[1,0] neg_lo:[0,1] neg_hi:[0,1]
	v_pk_add_f32 v[102:103], v[100:101], v[96:97]
	v_mov_b32_e32 v111, v73
	v_pk_add_f32 v[72:73], v[102:103], v[110:111]
	v_mul_f32_e32 v101, 0, v76
	v_mov_b32_e32 v97, v77
	v_pk_add_f32 v[96:97], v[100:101], v[96:97] neg_lo:[0,1] neg_hi:[0,1]
	v_pk_mul_f32 v[100:101], v[72:73], 0 op_sel_hi:[1,0]
	v_pk_mov_b32 v[74:75], v[128:129], v[124:125] op_sel:[1,0]
	v_mov_b32_e32 v107, v93
	v_pk_add_f32 v[86:87], v[102:103], v[110:111] neg_lo:[0,1] neg_hi:[0,1]
	v_fmac_f32_e32 v76, 0, v77
	v_pk_add_f32 v[102:103], v[72:73], v[100:101] op_sel:[0,1] op_sel_hi:[1,0]
	v_pk_add_f32 v[72:73], v[72:73], v[100:101] op_sel:[0,1] op_sel_hi:[1,0] neg_lo:[0,1] neg_hi:[0,1]
	v_pk_fma_f32 v[104:105], v[74:75], 0, v[124:125] op_sel_hi:[1,0,1]
	v_pk_fma_f32 v[74:75], v[74:75], 0, v[128:129] op_sel_hi:[1,0,1] neg_lo:[1,0,0] neg_hi:[1,0,0]
	v_pk_add_f32 v[92:93], v[116:117], v[106:107]
	v_pk_add_f32 v[94:95], v[88:89], v[108:109]
	v_add_f32_e32 v89, v118, v76
	v_mov_b32_e32 v103, v73
	v_mov_b32_e32 v105, v75
	v_sub_f32_e32 v118, v118, v76
	v_pk_mul_f32 v[76:77], v[92:93], 0 op_sel_hi:[1,0]
	v_pk_add_f32 v[72:73], v[94:95], v[102:103]
	v_mul_f32_e32 v101, 0x3f3504f3, v89
	v_mul_f32_e32 v89, 0, v86
	v_mov_b32_e32 v109, v87
	v_fmac_f32_e32 v86, 0, v87
	v_pk_add_f32 v[74:75], v[68:69], v[104:105]
	v_mov_b32_e32 v91, v79
	v_add_f32_e32 v110, v96, v97
	v_sub_f32_e32 v111, v96, v97
	v_pk_add_f32 v[96:97], v[92:93], v[76:77] op_sel:[0,1] op_sel_hi:[1,0]
	v_pk_add_f32 v[76:77], v[92:93], v[76:77] op_sel:[0,1] op_sel_hi:[1,0] neg_lo:[0,1] neg_hi:[0,1]
	v_pk_add_f32 v[88:89], v[88:89], v[108:109] neg_lo:[0,1] neg_hi:[0,1]
	v_add_f32_e32 v125, v123, v86
	v_sub_f32_e32 v123, v123, v86
	v_pk_mul_f32 v[86:87], v[72:73], 0 op_sel_hi:[1,0]
	v_pk_add_f32 v[78:79], v[74:75], v[90:91]
	v_mov_b32_e32 v97, v77
	v_add_f32_e32 v124, v88, v89
	v_sub_f32_e32 v126, v88, v89
	v_pk_add_f32 v[88:89], v[72:73], v[86:87] op_sel:[0,1] op_sel_hi:[1,0]
	v_pk_add_f32 v[72:73], v[72:73], v[86:87] op_sel:[0,1] op_sel_hi:[1,0] neg_lo:[0,1] neg_hi:[0,1]
	v_pk_add_f32 v[76:77], v[78:79], v[96:97]
	v_mov_b32_e32 v89, v73
	v_pk_add_f32 v[84:85], v[84:85], v[98:99] neg_lo:[0,1] neg_hi:[0,1]
	v_pk_add_f32 v[72:73], v[76:77], v[88:89]
	v_pk_add_f32 v[76:77], v[76:77], v[88:89] neg_lo:[0,1] neg_hi:[0,1]
	v_pk_add_f32 v[80:81], v[80:81], v[112:113] neg_lo:[0,1] neg_hi:[0,1]
	v_pk_fma_f32 v[88:89], v[84:85], 0, v[84:85] op_sel:[0,0,1] op_sel_hi:[1,0,0] neg_lo:[0,0,1] neg_hi:[0,0,1]
	v_pk_fma_f32 v[84:85], v[84:85], 0, v[84:85] op_sel:[0,0,1] op_sel_hi:[1,0,0]
	v_mul_f32_e32 v100, 0x3f3504f3, v110
	v_pk_add_f32 v[82:83], v[82:83], v[114:115] neg_lo:[0,1] neg_hi:[0,1]
	v_pk_fma_f32 v[86:87], v[80:81], 0, v[80:81] op_sel:[0,0,1] op_sel_hi:[1,0,0] neg_lo:[0,0,1] neg_hi:[0,0,1]
	v_pk_fma_f32 v[80:81], v[80:81], 0, v[80:81] op_sel:[0,0,1] op_sel_hi:[1,0,0]
	v_mov_b32_e32 v89, v85
	v_mul_f32_e32 v92, 0x3f3504f3, v119
	v_mul_f32_e32 v93, 0x3f3504f3, v120
	v_pk_add_f32 v[68:69], v[68:69], v[104:105] neg_lo:[0,1] neg_hi:[0,1]
	v_mov_b32_e32 v87, v81
	v_pk_add_f32 v[84:85], v[82:83], v[88:89]
	v_sub_f32_e32 v100, v100, v101
	v_fmac_f32_e32 v101, 0x3f3504f3, v110
	v_pk_add_f32 v[80:81], v[68:69], v[86:87]
	v_sub_f32_e32 v92, v92, v93
	v_fmac_f32_e32 v93, 0x3f3504f3, v119
	v_pk_add_f32 v[104:105], v[84:85], v[100:101]
	v_pk_add_f32 v[84:85], v[84:85], v[100:101] neg_lo:[0,1] neg_hi:[0,1]
	v_mul_f32_e32 v111, 0xbf3504f3, v111
	v_mul_f32_e32 v127, 0xbf3504f3, v118
	v_pk_add_f32 v[98:99], v[80:81], v[92:93]
	v_pk_add_f32 v[74:75], v[74:75], v[90:91] neg_lo:[0,1] neg_hi:[0,1]
	v_pk_add_f32 v[90:91], v[116:117], v[106:107] neg_lo:[0,1] neg_hi:[0,1]
	v_pk_add_f32 v[80:81], v[80:81], v[92:93] neg_lo:[0,1] neg_hi:[0,1]
	v_pk_mul_f32 v[92:93], v[84:85], s[4:5] op_sel:[1,0]
	v_pk_mul_f32 v[100:101], v[104:105], s[0:1] op_sel_hi:[1,0]
	v_pk_fma_f32 v[106:107], v[90:91], 0, v[90:91] op_sel:[0,0,1] op_sel_hi:[1,0,0] neg_lo:[0,0,1] neg_hi:[0,0,1]
	v_pk_fma_f32 v[90:91], v[90:91], 0, v[90:91] op_sel:[0,0,1] op_sel_hi:[1,0,0]
	v_add_f32_e32 v110, v127, v111
	v_fma_f32 v111, v118, s87, -v111
	v_pk_add_f32 v[82:83], v[82:83], v[88:89] neg_lo:[0,1] neg_hi:[0,1]
	v_pk_add_f32 v[94:95], v[94:95], v[102:103] neg_lo:[0,1] neg_hi:[0,1]
	v_pk_fma_f32 v[84:85], v[84:85], s[34:35], v[92:93] op_sel_hi:[0,1,1] neg_lo:[0,0,1] neg_hi:[0,0,1]
	v_pk_fma_f32 v[108:109], v[104:105], s[4:5], v[100:101] op_sel:[0,0,1] op_sel_hi:[1,0,0] neg_lo:[0,0,1] neg_hi:[0,0,1]
	v_pk_fma_f32 v[100:101], v[104:105], s[4:5], v[100:101] op_sel:[0,0,1] op_sel_hi:[1,0,0]
	v_mul_f32_e32 v104, 0x3f3504f3, v124
	v_mul_f32_e32 v105, 0x3f3504f3, v125
	v_mov_b32_e32 v107, v91
	v_pk_add_f32 v[88:89], v[82:83], v[110:111]
	v_pk_add_f32 v[78:79], v[78:79], v[96:97] neg_lo:[0,1] neg_hi:[0,1]
	v_pk_fma_f32 v[96:97], v[94:95], 0, v[94:95] op_sel:[0,0,1] op_sel_hi:[1,0,0] neg_lo:[0,0,1] neg_hi:[0,0,1]
	v_pk_fma_f32 v[94:95], v[94:95], 0, v[94:95] op_sel:[0,0,1] op_sel_hi:[1,0,0]
	v_pk_add_f32 v[92:93], v[80:81], v[84:85]
	v_pk_add_f32 v[80:81], v[80:81], v[84:85] neg_lo:[0,1] neg_hi:[0,1]
	v_mul_f32_e32 v85, 0xbf3504f3, v126
	v_mul_f32_e32 v84, 0xbf3504f3, v123
	v_mul_f32_e32 v120, 0xbf3504f3, v121
	v_mul_f32_e32 v121, 0xbf3504f3, v122
	v_mov_b32_e32 v109, v101
	v_pk_add_f32 v[90:91], v[74:75], v[106:107]
	v_sub_f32_e32 v104, v104, v105
	v_fmac_f32_e32 v105, 0x3f3504f3, v124
	v_pk_add_f32 v[82:83], v[82:83], v[110:111] neg_lo:[0,1] neg_hi:[0,1]
	v_pk_mul_f32 v[110:111], v[88:89], s[4:5] op_sel_hi:[1,0]
	v_mov_b32_e32 v97, v95
; #define LAS __attribute__((address_space(3)))
; __device__ __forceinline__ int otid() { int t = threadIdx.x; asm volatile("" : "+v"(t)); return t; }
; __device__ __forceinline__ cf twc(cf ws, int k16) { if (k16 == 0) return ws; if (k16 == 4) return cf{ws.y, -ws.x}; return cmul(ws, cf{c16(k16), -s16(k16)}); }
; __device__ __forceinline__ void wave_lds_fence() { asm volatile("s_waitcnt lgkmcnt(0)" ::: "memory"); }
; template <int LR> __device__ __forceinline__ void dit_reg(cf (&x)[1 << LR], cf w) {
;     constexpr int R = 1 << LR; cf wsv[LR]; wsv[0] = w;
; #pragma unroll
;     for (int s = 1; s < LR; ++s) wsv[s] = cmul(wsv[s - 1], wsv[s - 1]);
; #pragma unroll
;     for (int s = LR - 1; s >= 0; --s) { const int half = R >> (s + 1);
; #pragma unroll
;         for (int m0 = 0; m0 < R; m0 += 2 * half)
; #pragma unroll
;             for (int mm = 0; mm < half; ++mm) { const int ia = m0 + mm, ib = ia + half; const cf a = x[ia];
;                 const cf b = cmulc(x[ib], twc(wsv[s], (mm << s) * (16 / R)));
;                 x[ia] = cf{a.x + b.x, a.y + b.y}; x[ib] = cf{a.x - b.x, a.y - b.y}; } }
; }
; __device__ __forceinline__ void lds_barrier() { asm volatile("s_waitcnt lgkmcnt(0)\n\ts_barrier" ::: "memory"); }
; template <int LR, bool INV> __device__ __forceinline__ void fft_pass(ldsf2 buf, int base, int stride, int twi) {
;     constexpr int R = 1 << LR; cf x[R];
;     const v2f wv = ((ldsf2)((LAS unsigned char*)buf + 139264))[twi];
; #pragma unroll
;     for (int m = 0; m < R; ++m) { const v2f v = buf[base + m * stride]; x[m] = cf{v.x, v.y}; }
;     const cf w{wv.x, wv.y};
;     if (INV) dit_reg<LR>(x, w); else dif_reg<LR>(x, w);
; #pragma unroll
;     for (int m = 0; m < R; ++m) buf[base + m * stride] = mkv2(x[m].x, x[m].y);
; }
; __device__ __forceinline__ void fft_inv_cba(ldsf2 buf) {
;     const int tid = otid(); const int wv = tid >> 6, l = tid & 63;
; #pragma unroll 1
;     for (int u = 0; u < 2; ++u) { const int j = l + 64 * u, o = j & 15, e0 = wv * 1024 + (j >> 4) * 128 + o; fft_pass<3, true>(buf, e0 + (e0 >> 4), 17, o * 64); }
;     wave_lds_fence();
	v_pk_add_f32 v[74:75], v[74:75], v[106:107] neg_lo:[0,1] neg_hi:[0,1]
	v_add_f32_e32 v84, v84, v85
	v_fma_f32 v85, v123, s87, -v85
	s_mov_b32 s35, s13
	v_pk_add_f32 v[100:101], v[98:99], v[108:109]
	v_pk_add_f32 v[98:99], v[98:99], v[108:109] neg_lo:[0,1] neg_hi:[0,1]
	v_pk_add_f32 v[108:109], v[90:91], v[104:105]
	v_pk_add_f32 v[90:91], v[90:91], v[104:105] neg_lo:[0,1] neg_hi:[0,1]
	v_add_f32_e32 v104, v121, v120
	v_fma_f32 v105, v122, s87, -v120
	v_pk_add_f32 v[68:69], v[68:69], v[86:87] neg_lo:[0,1] neg_hi:[0,1]
	v_pk_fma_f32 v[112:113], v[88:89], s[0:1], v[110:111] op_sel:[0,0,1] op_sel_hi:[1,0,0] neg_lo:[0,0,1] neg_hi:[0,0,1]
	v_pk_fma_f32 v[88:89], v[88:89], s[0:1], v[110:111] op_sel:[0,0,1] op_sel_hi:[1,0,0]
	v_pk_add_f32 v[94:95], v[78:79], v[96:97]
	v_pk_add_f32 v[78:79], v[78:79], v[96:97] neg_lo:[0,1] neg_hi:[0,1]
	v_pk_add_f32 v[96:97], v[74:75], v[84:85]
	v_pk_add_f32 v[74:75], v[74:75], v[84:85] neg_lo:[0,1] neg_hi:[0,1]
	v_pk_mul_f32 v[84:85], v[82:83], s[34:35] op_sel:[1,0]
	s_mov_b32 s0, s13
	v_pk_add_f32 v[86:87], v[68:69], v[104:105]
	v_pk_add_f32 v[68:69], v[68:69], v[104:105] neg_lo:[0,1] neg_hi:[0,1]
	v_pk_fma_f32 v[82:83], v[82:83], s[0:1], v[84:85] op_sel_hi:[0,1,1]
	v_mov_b32_e32 v113, v89
	v_pk_add_f32 v[84:85], v[68:69], v[82:83]
	v_pk_add_f32 v[68:69], v[68:69], v[82:83] neg_lo:[0,1] neg_hi:[0,1]
	v_pk_add_f32 v[88:89], v[86:87], v[112:113]
	v_pk_add_f32 v[86:87], v[86:87], v[112:113] neg_lo:[0,1] neg_hi:[0,1]
	ds_write2_b64 v147, v[72:73], v[100:101] offset1:1
	ds_write2_b64 v147, v[108:109], v[88:89] offset0:2 offset1:3
	ds_write2_b64 v147, v[94:95], v[92:93] offset0:4 offset1:5
	ds_write2_b64 v147, v[96:97], v[84:85] offset0:6 offset1:7
	ds_write2_b64 v147, v[76:77], v[98:99] offset0:8 offset1:9
	ds_write2_b64 v147, v[90:91], v[86:87] offset0:10 offset1:11
	ds_write2_b64 v147, v[78:79], v[80:81] offset0:12 offset1:13
	ds_write2_b64 v147, v[74:75], v[68:69] offset0:14 offset1:15
	v_mov_b32_e32 v68, v195
	s_waitcnt lgkmcnt(0)
	s_mov_b32 s0, 0
	v_and_b32_e32 v73, 15, v68
	v_lshlrev_b32_e32 v72, 4, v68
	v_lshlrev_b32_e32 v75, 9, v73
	v_and_b32_e32 v72, 0xfffffc00, v72
	v_lshlrev_b32_e32 v74, 3, v68
	v_add_u32_e32 v75, 0, v75
	v_and_b32_e32 v69, 63, v68
	v_lshl_add_u32 v73, v73, 3, 0
	v_and_or_b32 v74, v74, s90, v72
	v_add_u32_e32 v75, 0x22000, v75
.LBB0_353:
	ds_read_b64 v[92:93], v75
	v_cndmask_b32_e64 v76, 0, 1, s[6:7]
	v_cmp_ne_u32_e32 vcc, 1, v76
	v_or_b32_e32 v76, s0, v74
	v_lshlrev_b32_e32 v77, 3, v76
	v_ashrrev_i32_e32 v76, 1, v76
	v_add3_u32 v122, v73, v77, v76
	ds_read2_b64 v[76:79], v122 offset1:17
	ds_read2_b64 v[80:83], v122 offset0:34 offset1:51
	ds_read2_b64 v[84:87], v122 offset0:68 offset1:85
	ds_read2_b64 v[88:91], v122 offset0:102 offset1:119
	s_waitcnt lgkmcnt(4)
	v_pk_add_f32 v[94:95], v[92:93], v[92:93] op_sel:[0,1] op_sel_hi:[1,0] neg_lo:[0,0] neg_hi:[0,1]
	v_pk_mul_f32 v[96:97], v[94:95], s[16:17] op_sel:[0,0] op_sel_hi:[1,0]
	v_pk_mul_f32 v[98:99], v[94:95], s[16:17] op_sel:[1,0] op_sel_hi:[0,0] neg_lo:[0,0] neg_hi:[1,0]
	v_pk_mul_f32 v[100:101], v[92:93], v[92:93] op_sel:[1,1] op_sel_hi:[1,0]
	v_pk_fma_f32 v[100:101], v[92:93], v[92:93], v[100:101] op_sel:[0,0,0] op_sel_hi:[0,1,1] neg_lo:[0,0,1] neg_hi:[0,0,0]
	v_pk_mul_f32 v[102:103], v[100:101], v[100:101] op_sel:[1,1] op_sel_hi:[1,0]
	v_pk_fma_f32 v[102:103], v[100:101], v[100:101], v[102:103] op_sel:[0,0,0] op_sel_hi:[0,1,1] neg_lo:[0,0,1] neg_hi:[0,0,0]
	s_waitcnt lgkmcnt(0)
	v_pk_mul_f32 v[104:105], v[78:79], v[102:103] op_sel:[1,1] op_sel_hi:[1,0]
	v_pk_mul_f32 v[106:107], v[82:83], v[102:103] op_sel:[1,1] op_sel_hi:[1,0]
	v_pk_mul_f32 v[108:109], v[86:87], v[102:103] op_sel:[1,1] op_sel_hi:[1,0]
	v_pk_mul_f32 v[110:111], v[90:91], v[102:103] op_sel:[1,1] op_sel_hi:[1,0]
	v_pk_fma_f32 v[104:105], v[78:79], v[102:103], v[104:105] op_sel:[0,0,0] op_sel_hi:[0,1,1] neg_lo:[0,0,0] neg_hi:[0,1,0]
	v_pk_fma_f32 v[106:107], v[82:83], v[102:103], v[106:107] op_sel:[0,0,0] op_sel_hi:[0,1,1] neg_lo:[0,0,0] neg_hi:[0,1,0]
	v_pk_fma_f32 v[108:109], v[86:87], v[102:103], v[108:109] op_sel:[0,0,0] op_sel_hi:[0,1,1] neg_lo:[0,0,0] neg_hi:[0,1,0]
	v_pk_fma_f32 v[110:111], v[90:91], v[102:103], v[110:111] op_sel:[0,0,0] op_sel_hi:[0,1,1] neg_lo:[0,0,0] neg_hi:[0,1,0]
	v_pk_add_f32 v[78:79], v[76:77], v[104:105] neg_lo:[0,1] neg_hi:[0,1]
	v_pk_add_f32 v[82:83], v[80:81], v[106:107] neg_lo:[0,1] neg_hi:[0,1]
	v_pk_add_f32 v[86:87], v[84:85], v[108:109] neg_lo:[0,1] neg_hi:[0,1]
	v_pk_add_f32 v[90:91], v[88:89], v[110:111] neg_lo:[0,1] neg_hi:[0,1]
	v_pk_add_f32 v[76:77], v[76:77], v[104:105]
	v_pk_add_f32 v[80:81], v[80:81], v[106:107]
	v_pk_add_f32 v[84:85], v[84:85], v[108:109]
	v_pk_add_f32 v[88:89], v[88:89], v[110:111]
	v_pk_mul_f32 v[104:105], v[80:81], v[100:101] op_sel:[1,1] op_sel_hi:[1,0]
	v_pk_mul_f32 v[106:107], v[82:83], v[100:101] op_sel:[1,0] op_sel_hi:[1,1]
	v_pk_mul_f32 v[108:109], v[88:89], v[100:101] op_sel:[1,1] op_sel_hi:[1,0]
	v_pk_mul_f32 v[110:111], v[90:91], v[100:101] op_sel:[1,0] op_sel_hi:[1,1]
	v_pk_fma_f32 v[104:105], v[80:81], v[100:101], v[104:105] op_sel:[0,0,0] op_sel_hi:[0,1,1] neg_lo:[0,0,0] neg_hi:[0,1,0]
	v_pk_fma_f32 v[106:107], v[82:83], v[100:101], v[106:107] op_sel:[0,1,0] op_sel_hi:[0,0,1] neg_lo:[0,0,1] neg_hi:[0,0,0]
	v_pk_fma_f32 v[108:109], v[88:89], v[100:101], v[108:109] op_sel:[0,0,0] op_sel_hi:[0,1,1] neg_lo:[0,0,0] neg_hi:[0,1,0]
	v_pk_fma_f32 v[110:111], v[90:91], v[100:101], v[110:111] op_sel:[0,1,0] op_sel_hi:[0,0,1] neg_lo:[0,0,1] neg_hi:[0,0,0]
	v_pk_add_f32 v[80:81], v[76:77], v[104:105] neg_lo:[0,1] neg_hi:[0,1]
	v_pk_add_f32 v[82:83], v[78:79], v[106:107] neg_lo:[0,1] neg_hi:[0,1]
; #define LAS __attribute__((address_space(3)))
; __device__ __forceinline__ cf twc(cf ws, int k16) { if (k16 == 0) return ws; if (k16 == 4) return cf{ws.y, -ws.x}; return cmul(ws, cf{c16(k16), -s16(k16)}); }
; __device__ __forceinline__ void wave_lds_fence() { asm volatile("s_waitcnt lgkmcnt(0)" ::: "memory"); }
; template <int LR> __device__ __forceinline__ void dit_reg(cf (&x)[1 << LR], cf w) {
;     constexpr int R = 1 << LR; cf wsv[LR]; wsv[0] = w;
; #pragma unroll
;     for (int s = 1; s < LR; ++s) wsv[s] = cmul(wsv[s - 1], wsv[s - 1]);
; #pragma unroll
;     for (int s = LR - 1; s >= 0; --s) { const int half = R >> (s + 1);
; #pragma unroll
;         for (int m0 = 0; m0 < R; m0 += 2 * half)
; #pragma unroll
;             for (int mm = 0; mm < half; ++mm) { const int ia = m0 + mm, ib = ia + half; const cf a = x[ia];
;                 const cf b = cmulc(x[ib], twc(wsv[s], (mm << s) * (16 / R)));
;                 x[ia] = cf{a.x + b.x, a.y + b.y}; x[ib] = cf{a.x - b.x, a.y - b.y}; } }
; }
; __device__ __forceinline__ void lds_barrier() { asm volatile("s_waitcnt lgkmcnt(0)\n\ts_barrier" ::: "memory"); }
; template <int LR, bool INV> __device__ __forceinline__ void fft_pass(ldsf2 buf, int base, int stride, int twi) {
;     constexpr int R = 1 << LR; cf x[R];
;     const v2f wv = ((ldsf2)((LAS unsigned char*)buf + 139264))[twi];
; #pragma unroll
;     for (int m = 0; m < R; ++m) { const v2f v = buf[base + m * stride]; x[m] = cf{v.x, v.y}; }
;     const cf w{wv.x, wv.y};
;     if (INV) dit_reg<LR>(x, w); else dif_reg<LR>(x, w);
; #pragma unroll
;     for (int m = 0; m < R; ++m) buf[base + m * stride] = mkv2(x[m].x, x[m].y);
; }
; __device__ __forceinline__ void fft_inv_cba(ldsf2 buf) {
;     ...
;     for (int u = 0; u < 2; ++u) { const int j = l + 64 * u, o = j & 15, e0 = wv * 1024 + (j >> 4) * 128 + o; fft_pass<3, true>(buf, e0 + (e0 >> 4), 17, o * 64); }
;     wave_lds_fence();
; #pragma unroll 1
;     for (int u = 0; u < 2; ++u) { const int o = l + 64 * u, e0 = wv * 1024 + o; fft_pass<3, true>(buf, e0 + (e0 >> 4), 136, o * 8); }
	v_pk_add_f32 v[88:89], v[84:85], v[108:109] neg_lo:[0,1] neg_hi:[0,1]
	v_pk_add_f32 v[90:91], v[86:87], v[110:111] neg_lo:[0,1] neg_hi:[0,1]
	v_pk_add_f32 v[76:77], v[76:77], v[104:105]
	v_pk_add_f32 v[78:79], v[78:79], v[106:107]
	v_pk_add_f32 v[84:85], v[84:85], v[108:109]
	v_pk_add_f32 v[86:87], v[86:87], v[110:111]
	v_pk_mul_f32 v[104:105], v[84:85], v[92:93] op_sel:[1,1] op_sel_hi:[1,0]
	v_pk_mul_f32 v[106:107], v[86:87], v[96:97] op_sel:[1,1] op_sel_hi:[1,0]
	v_pk_mul_f32 v[108:109], v[88:89], v[92:93] op_sel:[1,0] op_sel_hi:[1,1]
	v_pk_mul_f32 v[110:111], v[90:91], v[98:99] op_sel:[1,1] op_sel_hi:[1,0]
	v_pk_fma_f32 v[104:105], v[84:85], v[92:93], v[104:105] op_sel:[0,0,0] op_sel_hi:[0,1,1] neg_lo:[0,0,0] neg_hi:[0,1,0]
	v_pk_fma_f32 v[106:107], v[86:87], v[96:97], v[106:107] op_sel:[0,0,0] op_sel_hi:[0,1,1] neg_lo:[0,0,0] neg_hi:[0,1,0]
	v_pk_fma_f32 v[108:109], v[88:89], v[92:93], v[108:109] op_sel:[0,1,0] op_sel_hi:[0,0,1] neg_lo:[0,0,1] neg_hi:[0,0,0]
	v_pk_fma_f32 v[110:111], v[90:91], v[98:99], v[110:111] op_sel:[0,0,0] op_sel_hi:[0,1,1] neg_lo:[0,0,0] neg_hi:[0,1,0]
	v_pk_add_f32 v[84:85], v[76:77], v[104:105] neg_lo:[0,1] neg_hi:[0,1]
	v_pk_add_f32 v[86:87], v[78:79], v[106:107] neg_lo:[0,1] neg_hi:[0,1]
	v_pk_add_f32 v[88:89], v[80:81], v[108:109] neg_lo:[0,1] neg_hi:[0,1]
	v_pk_add_f32 v[90:91], v[82:83], v[110:111] neg_lo:[0,1] neg_hi:[0,1]
	v_pk_add_f32 v[76:77], v[76:77], v[104:105]
	v_pk_add_f32 v[78:79], v[78:79], v[106:107]
	v_pk_add_f32 v[80:81], v[80:81], v[108:109]
	v_pk_add_f32 v[82:83], v[82:83], v[110:111]
	ds_write2_b64 v122, v[76:77], v[78:79] offset1:17
	ds_write2_b64 v122, v[80:81], v[82:83] offset0:34 offset1:51
	ds_write2_b64 v122, v[84:85], v[86:87] offset0:68 offset1:85
	ds_write2_b64 v122, v[88:89], v[90:91] offset0:102 offset1:119
	s_movk_i32 s0, 0x200
	s_mov_b64 s[6:7], 0
	s_and_b64 vcc, exec, vcc
	s_cbranch_vccz .LBB0_353
	s_waitcnt lgkmcnt(0)
	s_mov_b32 s0, 0
	s_mov_b64 s[6:7], -1
.LBB0_355:
	v_cndmask_b32_e64 v73, 0, 1, s[6:7]
	v_cmp_ne_u32_e32 vcc, 1, v73
	v_or_b32_e32 v73, s0, v69
	v_or_b32_e32 v74, v73, v72
	v_lshl_add_u32 v73, v73, 6, 0
	v_add_u32_e32 v73, 0x22000, v73
	ds_read_b64 v[90:91], v73
	v_ashrrev_i32_e32 v75, 4, v74
	v_lshlrev_b32_e32 v73, 3, v74
	v_lshlrev_b32_e32 v74, 3, v75
	v_add3_u32 v73, 0, v73, v74
	v_add_u32_e32 v122, 0x1800, v73
	v_add_u32_e32 v121, 0x1000, v73
	ds_read2_b64 v[86:89], v122 offset0:48 offset1:184
	ds_read2_b64 v[82:85], v121 offset0:32 offset1:168
	v_add_u32_e32 v120, 0x800, v73
	ds_read2_b64 v[74:77], v73 offset1:136
	ds_read2_b64 v[78:81], v120 offset0:16 offset1:152
	s_waitcnt lgkmcnt(4)
	v_pk_add_f32 v[92:93], v[90:91], v[90:91] op_sel:[0,1] op_sel_hi:[1,0] neg_lo:[0,0] neg_hi:[0,1]
	v_pk_mul_f32 v[94:95], v[92:93], s[16:17] op_sel:[0,0] op_sel_hi:[1,0]
	v_pk_mul_f32 v[96:97], v[92:93], s[16:17] op_sel:[1,0] op_sel_hi:[0,0] neg_lo:[0,0] neg_hi:[1,0]
	v_pk_mul_f32 v[98:99], v[90:91], v[90:91] op_sel:[1,1] op_sel_hi:[1,0]
	v_pk_fma_f32 v[98:99], v[90:91], v[90:91], v[98:99] op_sel:[0,0,0] op_sel_hi:[0,1,1] neg_lo:[0,0,1] neg_hi:[0,0,0]
	v_pk_mul_f32 v[100:101], v[98:99], v[98:99] op_sel:[1,1] op_sel_hi:[1,0]
	v_pk_fma_f32 v[100:101], v[98:99], v[98:99], v[100:101] op_sel:[0,0,0] op_sel_hi:[0,1,1] neg_lo:[0,0,1] neg_hi:[0,0,0]
	s_waitcnt lgkmcnt(0)
	v_pk_mul_f32 v[102:103], v[76:77], v[100:101] op_sel:[1,1] op_sel_hi:[1,0]
	v_pk_mul_f32 v[104:105], v[80:81], v[100:101] op_sel:[1,1] op_sel_hi:[1,0]
	v_pk_mul_f32 v[106:107], v[84:85], v[100:101] op_sel:[1,1] op_sel_hi:[1,0]
	v_pk_mul_f32 v[108:109], v[88:89], v[100:101] op_sel:[1,1] op_sel_hi:[1,0]
	v_pk_fma_f32 v[102:103], v[76:77], v[100:101], v[102:103] op_sel:[0,0,0] op_sel_hi:[0,1,1] neg_lo:[0,0,0] neg_hi:[0,1,0]
	v_pk_fma_f32 v[104:105], v[80:81], v[100:101], v[104:105] op_sel:[0,0,0] op_sel_hi:[0,1,1] neg_lo:[0,0,0] neg_hi:[0,1,0]
	v_pk_fma_f32 v[106:107], v[84:85], v[100:101], v[106:107] op_sel:[0,0,0] op_sel_hi:[0,1,1] neg_lo:[0,0,0] neg_hi:[0,1,0]
	v_pk_fma_f32 v[108:109], v[88:89], v[100:101], v[108:109] op_sel:[0,0,0] op_sel_hi:[0,1,1] neg_lo:[0,0,0] neg_hi:[0,1,0]
	v_pk_add_f32 v[76:77], v[74:75], v[102:103] neg_lo:[0,1] neg_hi:[0,1]
	v_pk_add_f32 v[80:81], v[78:79], v[104:105] neg_lo:[0,1] neg_hi:[0,1]
	v_pk_add_f32 v[84:85], v[82:83], v[106:107] neg_lo:[0,1] neg_hi:[0,1]
	v_pk_add_f32 v[88:89], v[86:87], v[108:109] neg_lo:[0,1] neg_hi:[0,1]
	v_pk_add_f32 v[74:75], v[74:75], v[102:103]
	v_pk_add_f32 v[78:79], v[78:79], v[104:105]
	v_pk_add_f32 v[82:83], v[82:83], v[106:107]
	v_pk_add_f32 v[86:87], v[86:87], v[108:109]
	v_pk_mul_f32 v[102:103], v[78:79], v[98:99] op_sel:[1,1] op_sel_hi:[1,0]
	v_pk_mul_f32 v[104:105], v[80:81], v[98:99] op_sel:[1,0] op_sel_hi:[1,1]
	v_pk_mul_f32 v[106:107], v[86:87], v[98:99] op_sel:[1,1] op_sel_hi:[1,0]
	v_pk_mul_f32 v[108:109], v[88:89], v[98:99] op_sel:[1,0] op_sel_hi:[1,1]
	v_pk_fma_f32 v[102:103], v[78:79], v[98:99], v[102:103] op_sel:[0,0,0] op_sel_hi:[0,1,1] neg_lo:[0,0,0] neg_hi:[0,1,0]
	v_pk_fma_f32 v[104:105], v[80:81], v[98:99], v[104:105] op_sel:[0,1,0] op_sel_hi:[0,0,1] neg_lo:[0,0,1] neg_hi:[0,0,0]
	v_pk_fma_f32 v[106:107], v[86:87], v[98:99], v[106:107] op_sel:[0,0,0] op_sel_hi:[0,1,1] neg_lo:[0,0,0] neg_hi:[0,1,0]
	v_pk_fma_f32 v[108:109], v[88:89], v[98:99], v[108:109] op_sel:[0,1,0] op_sel_hi:[0,0,1] neg_lo:[0,0,1] neg_hi:[0,0,0]
	v_pk_add_f32 v[78:79], v[74:75], v[102:103] neg_lo:[0,1] neg_hi:[0,1]
	v_pk_add_f32 v[80:81], v[76:77], v[104:105] neg_lo:[0,1] neg_hi:[0,1]
	v_pk_add_f32 v[86:87], v[82:83], v[106:107] neg_lo:[0,1] neg_hi:[0,1]
	v_pk_add_f32 v[88:89], v[84:85], v[108:109] neg_lo:[0,1] neg_hi:[0,1]
	v_pk_add_f32 v[74:75], v[74:75], v[102:103]
; #define LAS __attribute__((address_space(3)))
; __device__ __forceinline__ cf twc(cf ws, int k16) { if (k16 == 0) return ws; if (k16 == 4) return cf{ws.y, -ws.x}; return cmul(ws, cf{c16(k16), -s16(k16)}); }
; template <int LR> __device__ __forceinline__ void dit_reg(cf (&x)[1 << LR], cf w) {
;     constexpr int R = 1 << LR; cf wsv[LR]; wsv[0] = w;
; #pragma unroll
;     for (int s = 1; s < LR; ++s) wsv[s] = cmul(wsv[s - 1], wsv[s - 1]);
; #pragma unroll
;     for (int s = LR - 1; s >= 0; --s) { const int half = R >> (s + 1);
; #pragma unroll
;         for (int m0 = 0; m0 < R; m0 += 2 * half)
; #pragma unroll
;             for (int mm = 0; mm < half; ++mm) { const int ia = m0 + mm, ib = ia + half; const cf a = x[ia];
;                 const cf b = cmulc(x[ib], twc(wsv[s], (mm << s) * (16 / R)));
;                 x[ia] = cf{a.x + b.x, a.y + b.y}; x[ib] = cf{a.x - b.x, a.y - b.y}; } }
; }
; __device__ __forceinline__ void lds_barrier() { asm volatile("s_waitcnt lgkmcnt(0)\n\ts_barrier" ::: "memory"); }
; template <int LR, bool INV> __device__ __forceinline__ void fft_pass(ldsf2 buf, int base, int stride, int twi) {
;     constexpr int R = 1 << LR; cf x[R];
;     const v2f wv = ((ldsf2)((LAS unsigned char*)buf + 139264))[twi];
; #pragma unroll
;     for (int m = 0; m < R; ++m) { const v2f v = buf[base + m * stride]; x[m] = cf{v.x, v.y}; }
;     const cf w{wv.x, wv.y};
;     if (INV) dit_reg<LR>(x, w); else dif_reg<LR>(x, w);
; #pragma unroll
;     for (int m = 0; m < R; ++m) buf[base + m * stride] = mkv2(x[m].x, x[m].y);
; }
; __device__ __forceinline__ void fft_inv_cba(ldsf2 buf) {
;     ...
;     for (int u = 0; u < 2; ++u) { const int o = l + 64 * u, e0 = wv * 1024 + o; fft_pass<3, true>(buf, e0 + (e0 >> 4), 136, o * 8); }
;     lds_barrier();
; #pragma unroll 1
;     for (int u = 0; u < 2; ++u) { const int bf = tid + NT * u; fft_pass<3, true>(buf, bf + (bf >> 4), 1088, bf); }
	v_pk_add_f32 v[76:77], v[76:77], v[104:105]
	v_pk_add_f32 v[82:83], v[82:83], v[106:107]
	v_pk_add_f32 v[84:85], v[84:85], v[108:109]
	v_pk_mul_f32 v[102:103], v[82:83], v[90:91] op_sel:[1,1] op_sel_hi:[1,0]
	v_pk_mul_f32 v[104:105], v[84:85], v[94:95] op_sel:[1,1] op_sel_hi:[1,0]
	v_pk_mul_f32 v[106:107], v[86:87], v[90:91] op_sel:[1,0] op_sel_hi:[1,1]
	v_pk_mul_f32 v[108:109], v[88:89], v[96:97] op_sel:[1,1] op_sel_hi:[1,0]
	v_pk_fma_f32 v[102:103], v[82:83], v[90:91], v[102:103] op_sel:[0,0,0] op_sel_hi:[0,1,1] neg_lo:[0,0,0] neg_hi:[0,1,0]
	v_pk_fma_f32 v[104:105], v[84:85], v[94:95], v[104:105] op_sel:[0,0,0] op_sel_hi:[0,1,1] neg_lo:[0,0,0] neg_hi:[0,1,0]
	v_pk_fma_f32 v[106:107], v[86:87], v[90:91], v[106:107] op_sel:[0,1,0] op_sel_hi:[0,0,1] neg_lo:[0,0,1] neg_hi:[0,0,0]
	v_pk_fma_f32 v[108:109], v[88:89], v[96:97], v[108:109] op_sel:[0,0,0] op_sel_hi:[0,1,1] neg_lo:[0,0,0] neg_hi:[0,1,0]
	v_pk_add_f32 v[82:83], v[74:75], v[102:103] neg_lo:[0,1] neg_hi:[0,1]
	v_pk_add_f32 v[84:85], v[76:77], v[104:105] neg_lo:[0,1] neg_hi:[0,1]
	v_pk_add_f32 v[86:87], v[78:79], v[106:107] neg_lo:[0,1] neg_hi:[0,1]
	v_pk_add_f32 v[88:89], v[80:81], v[108:109] neg_lo:[0,1] neg_hi:[0,1]
	v_pk_add_f32 v[74:75], v[74:75], v[102:103]
	v_pk_add_f32 v[76:77], v[76:77], v[104:105]
	v_pk_add_f32 v[78:79], v[78:79], v[106:107]
	v_pk_add_f32 v[80:81], v[80:81], v[108:109]
	ds_write2_b64 v73, v[74:75], v[76:77] offset1:136
	ds_write2_b64 v120, v[78:79], v[80:81] offset0:16 offset1:152
	ds_write2_b64 v121, v[82:83], v[84:85] offset0:32 offset1:168
	ds_write2_b64 v122, v[86:87], v[88:89] offset0:48 offset1:184
	s_mov_b32 s0, 64
	s_mov_b64 s[6:7], 0
	s_and_b64 vcc, exec, vcc
	s_cbranch_vccz .LBB0_355
	s_waitcnt lgkmcnt(0)
	s_barrier
	s_mov_b32 s0, 0
	s_mov_b64 s[6:7], -1
.LBB0_357:
	v_add_u32_e32 v69, s0, v68
	v_ashrrev_i32_e32 v72, 4, v69
	v_lshl_add_u32 v69, v69, 3, 0
	v_add_u32_e32 v73, 0x22000, v69
	ds_read_b64 v[88:89], v73
	v_lshl_add_u32 v69, v72, 3, v69
	ds_read2st64_b64 v[72:75], v69 offset1:17
	ds_read2st64_b64 v[76:79], v69 offset0:34 offset1:51
	ds_read2st64_b64 v[80:83], v69 offset0:68 offset1:85
	ds_read2st64_b64 v[84:87], v69 offset0:102 offset1:119
	s_waitcnt lgkmcnt(4)
	v_pk_add_f32 v[90:91], v[88:89], v[88:89] op_sel:[0,1] op_sel_hi:[1,0] neg_lo:[0,0] neg_hi:[0,1]
	v_pk_mul_f32 v[92:93], v[90:91], s[16:17] op_sel:[0,0] op_sel_hi:[1,0]
	v_pk_mul_f32 v[94:95], v[90:91], s[16:17] op_sel:[1,0] op_sel_hi:[0,0] neg_lo:[0,0] neg_hi:[1,0]
	v_pk_mul_f32 v[96:97], v[88:89], v[88:89] op_sel:[1,1] op_sel_hi:[1,0]
	v_pk_fma_f32 v[96:97], v[88:89], v[88:89], v[96:97] op_sel:[0,0,0] op_sel_hi:[0,1,1] neg_lo:[0,0,1] neg_hi:[0,0,0]
	v_pk_mul_f32 v[98:99], v[96:97], v[96:97] op_sel:[1,1] op_sel_hi:[1,0]
	v_pk_fma_f32 v[98:99], v[96:97], v[96:97], v[98:99] op_sel:[0,0,0] op_sel_hi:[0,1,1] neg_lo:[0,0,1] neg_hi:[0,0,0]
	s_waitcnt lgkmcnt(0)
	v_pk_mul_f32 v[100:101], v[74:75], v[98:99] op_sel:[1,1] op_sel_hi:[1,0]
	v_pk_mul_f32 v[102:103], v[78:79], v[98:99] op_sel:[1,1] op_sel_hi:[1,0]
	v_pk_mul_f32 v[104:105], v[82:83], v[98:99] op_sel:[1,1] op_sel_hi:[1,0]
	v_pk_mul_f32 v[106:107], v[86:87], v[98:99] op_sel:[1,1] op_sel_hi:[1,0]
	v_pk_fma_f32 v[100:101], v[74:75], v[98:99], v[100:101] op_sel:[0,0,0] op_sel_hi:[0,1,1] neg_lo:[0,0,0] neg_hi:[0,1,0]
	v_pk_fma_f32 v[102:103], v[78:79], v[98:99], v[102:103] op_sel:[0,0,0] op_sel_hi:[0,1,1] neg_lo:[0,0,0] neg_hi:[0,1,0]
	v_pk_fma_f32 v[104:105], v[82:83], v[98:99], v[104:105] op_sel:[0,0,0] op_sel_hi:[0,1,1] neg_lo:[0,0,0] neg_hi:[0,1,0]
	v_pk_fma_f32 v[106:107], v[86:87], v[98:99], v[106:107] op_sel:[0,0,0] op_sel_hi:[0,1,1] neg_lo:[0,0,0] neg_hi:[0,1,0]
	v_pk_add_f32 v[74:75], v[72:73], v[100:101] neg_lo:[0,1] neg_hi:[0,1]
	v_pk_add_f32 v[78:79], v[76:77], v[102:103] neg_lo:[0,1] neg_hi:[0,1]
	v_pk_add_f32 v[82:83], v[80:81], v[104:105] neg_lo:[0,1] neg_hi:[0,1]
	v_pk_add_f32 v[86:87], v[84:85], v[106:107] neg_lo:[0,1] neg_hi:[0,1]
	v_pk_add_f32 v[72:73], v[72:73], v[100:101]
	v_pk_add_f32 v[76:77], v[76:77], v[102:103]
	v_pk_add_f32 v[80:81], v[80:81], v[104:105]
	v_pk_add_f32 v[84:85], v[84:85], v[106:107]
	v_pk_mul_f32 v[100:101], v[76:77], v[96:97] op_sel:[1,1] op_sel_hi:[1,0]
	v_pk_mul_f32 v[102:103], v[78:79], v[96:97] op_sel:[1,0] op_sel_hi:[1,1]
	v_pk_mul_f32 v[104:105], v[84:85], v[96:97] op_sel:[1,1] op_sel_hi:[1,0]
	v_pk_mul_f32 v[106:107], v[86:87], v[96:97] op_sel:[1,0] op_sel_hi:[1,1]
	v_pk_fma_f32 v[100:101], v[76:77], v[96:97], v[100:101] op_sel:[0,0,0] op_sel_hi:[0,1,1] neg_lo:[0,0,0] neg_hi:[0,1,0]
	v_pk_fma_f32 v[102:103], v[78:79], v[96:97], v[102:103] op_sel:[0,1,0] op_sel_hi:[0,0,1] neg_lo:[0,0,1] neg_hi:[0,0,0]
	v_pk_fma_f32 v[104:105], v[84:85], v[96:97], v[104:105] op_sel:[0,0,0] op_sel_hi:[0,1,1] neg_lo:[0,0,0] neg_hi:[0,1,0]
	v_pk_fma_f32 v[106:107], v[86:87], v[96:97], v[106:107] op_sel:[0,1,0] op_sel_hi:[0,0,1] neg_lo:[0,0,1] neg_hi:[0,0,0]
	v_pk_add_f32 v[76:77], v[72:73], v[100:101] neg_lo:[0,1] neg_hi:[0,1]
	v_pk_add_f32 v[78:79], v[74:75], v[102:103] neg_lo:[0,1] neg_hi:[0,1]
	v_pk_add_f32 v[84:85], v[80:81], v[104:105] neg_lo:[0,1] neg_hi:[0,1]
	v_pk_add_f32 v[86:87], v[82:83], v[106:107] neg_lo:[0,1] neg_hi:[0,1]
	v_pk_add_f32 v[72:73], v[72:73], v[100:101]
	v_pk_add_f32 v[74:75], v[74:75], v[102:103]
	v_pk_add_f32 v[80:81], v[80:81], v[104:105]
	v_pk_add_f32 v[82:83], v[82:83], v[106:107]
	v_pk_mul_f32 v[100:101], v[80:81], v[88:89] op_sel:[1,1] op_sel_hi:[1,0]
	v_pk_mul_f32 v[102:103], v[82:83], v[92:93] op_sel:[1,1] op_sel_hi:[1,0]
	v_pk_mul_f32 v[104:105], v[84:85], v[88:89] op_sel:[1,0] op_sel_hi:[1,1]
	v_pk_mul_f32 v[106:107], v[86:87], v[94:95] op_sel:[1,1] op_sel_hi:[1,0]
	v_pk_fma_f32 v[100:101], v[80:81], v[88:89], v[100:101] op_sel:[0,0,0] op_sel_hi:[0,1,1] neg_lo:[0,0,0] neg_hi:[0,1,0]
	v_pk_fma_f32 v[102:103], v[82:83], v[92:93], v[102:103] op_sel:[0,0,0] op_sel_hi:[0,1,1] neg_lo:[0,0,0] neg_hi:[0,1,0]
	v_pk_fma_f32 v[104:105], v[84:85], v[88:89], v[104:105] op_sel:[0,1,0] op_sel_hi:[0,0,1] neg_lo:[0,0,1] neg_hi:[0,0,0]
	v_pk_fma_f32 v[106:107], v[86:87], v[94:95], v[106:107] op_sel:[0,0,0] op_sel_hi:[0,1,1] neg_lo:[0,0,0] neg_hi:[0,1,0]
	v_pk_add_f32 v[80:81], v[72:73], v[100:101] neg_lo:[0,1] neg_hi:[0,1]
	v_pk_add_f32 v[82:83], v[74:75], v[102:103] neg_lo:[0,1] neg_hi:[0,1]
	v_pk_add_f32 v[84:85], v[76:77], v[104:105] neg_lo:[0,1] neg_hi:[0,1]
	v_pk_add_f32 v[86:87], v[78:79], v[106:107] neg_lo:[0,1] neg_hi:[0,1]
	v_pk_add_f32 v[72:73], v[72:73], v[100:101]
	v_pk_add_f32 v[74:75], v[74:75], v[102:103]
	v_pk_add_f32 v[76:77], v[76:77], v[104:105]
	v_pk_add_f32 v[78:79], v[78:79], v[106:107]
	ds_write2st64_b64 v69, v[72:73], v[74:75] offset1:17
	ds_write2st64_b64 v69, v[76:77], v[78:79] offset0:34 offset1:51
	ds_write2st64_b64 v69, v[80:81], v[82:83] offset0:68 offset1:85
	ds_write2st64_b64 v69, v[84:85], v[86:87] offset0:102 offset1:119
	s_movk_i32 s0, 0x200
	s_and_b64 vcc, exec, s[6:7]
	s_mov_b64 s[6:7], 0
	s_cbranch_vccnz .LBB0_357
; __device__ __forceinline__ float bf2f(bf16_t b) { return __uint_as_float(((unsigned)b) << 16); }
; __device__ __forceinline__ void lds_barrier() { asm volatile("s_waitcnt lgkmcnt(0)\n\ts_barrier" ::: "memory"); }
; __device__ __forceinline__ void sconv8(const Raw8& r, int n0, float w0, float w1, float w2, float b, float (&out)[8]) {
;     float a[10]; a[0] = n0 > 0 ? bf2f(r.eL) : 0.f; a[9] = n0 + 8 < SEQ ? bf2f(r.eR) : 0.f;
;     a[1] = __uint_as_float(r.body.x << 16); a[2] = __uint_as_float(r.body.x & 0xffff0000u); a[3] = __uint_as_float(r.body.y << 16); a[4] = __uint_as_float(r.body.y & 0xffff0000u);
;     a[5] = __uint_as_float(r.body.z << 16); a[6] = __uint_as_float(r.body.z & 0xffff0000u); a[7] = __uint_as_float(r.body.w << 16); a[8] = __uint_as_float(r.body.w & 0xffff0000u);
; #pragma unroll
;     for (int k = 0; k < 8; ++k) out[k] = w0 * a[k] + w1 * a[k + 1] + w2 * a[k + 2] + b;
; }
; __device__ void ph_hyena_fft(const Params& P, int j, const bf16_t* __restrict__ projAT, const float* __restrict__ kf, bf16_t* __restrict__ yaT, unsigned char* lds_raw) {
;     ...
;             const Raw8 xa0 = load_raw8(x1row + o0, n0), xa1 = load_raw8(x1row + o1, n0);
;             lds_barrier();
;             fft_conv(buf, spec1);
;             { float xa[8], xb[8]; sconv8(xa0, n0, wa0, wa1, wa2, ba, xa); sconv8(xa1, n0, wa0, wa1, wa2, ba, xb);
	s_waitcnt vmcnt(5)
	v_lshlrev_b32_e32 v68, 16, v143
	v_cndmask_b32_e64 v69, 0, v68, s[42:43]
	s_waitcnt vmcnt(3)
	v_lshlrev_b32_e32 v68, 16, v144
	v_lshlrev_b32_e32 v75, 16, v5
	v_cndmask_b32_e64 v73, 0, v68, s[44:45]
	v_lshlrev_b32_e32 v74, 16, v4
	v_and_b32_e32 v76, 0xffff0000, v4
	v_mov_b32_e32 v68, v75
	v_and_b32_e32 v77, 0xffff0000, v5
	v_mov_b32_e32 v80, v74
	v_mov_b32_e32 v81, v76
	v_pk_mul_f32 v[68:69], v[56:57], v[68:69]
	v_lshlrev_b32_e32 v79, 16, v6
	v_pk_fma_f32 v[68:69], v[56:57], v[80:81], v[68:69] op_sel:[0,0,1] op_sel_hi:[1,1,0]
	v_pk_mul_f32 v[80:81], v[32:33], v[76:77]
	v_and_b32_e32 v5, 0xffff0000, v7
	v_mov_b32_e32 v78, v75
	v_pk_fma_f32 v[74:75], v[30:31], v[74:75], v[80:81]
	v_and_b32_e32 v81, 16, v7
	v_and_b32_e32 v80, 0xffff0000, v6
	v_lshlrev_b32_e32 v7, 16, v7
	v_pk_fma_f32 v[68:69], v[34:35], v[76:77], v[68:69]
	v_mov_b32_e32 v6, v80
	v_mov_b32_e32 v4, v80
	v_pk_mov_b32 v[76:77], v[76:77], v[80:81] op_sel:[1,0]
	v_mov_b32_e32 v80, v79
	v_mov_b32_e32 v81, v7
	v_pk_mul_f32 v[80:81], v[32:33], v[80:81]
	v_pk_fma_f32 v[74:75], v[34:35], v[78:79], v[74:75]
	v_pk_fma_f32 v[76:77], v[30:31], v[76:77], v[80:81]
	v_mov_b32_e32 v78, v5
	v_pk_fma_f32 v[80:81], v[34:35], v[4:5], v[76:77]
	v_pk_mul_f32 v[4:5], v[56:57], v[78:79]
	v_mov_b32_e32 v72, v7
	v_pk_fma_f32 v[4:5], v[56:57], v[6:7], v[4:5] op_sel:[0,0,1] op_sel_hi:[1,1,0]
	s_waitcnt vmcnt(1)
	v_lshlrev_b32_e32 v77, 16, v1
	v_pk_fma_f32 v[72:73], v[34:35], v[72:73], v[4:5]
	v_lshlrev_b32_e32 v4, 16, v139
	v_cndmask_b32_e64 v5, 0, v4, s[42:43]
	s_waitcnt vmcnt(0)
	v_lshlrev_b32_e32 v4, 16, v141
	v_cndmask_b32_e64 v7, 0, v4, s[44:45]
	v_lshlrev_b32_e32 v76, 16, v0
	v_and_b32_e32 v78, 0xffff0000, v0
	v_mov_b32_e32 v4, v77
	v_mov_b32_e32 v84, v76
	v_mov_b32_e32 v85, v78
	v_pk_mul_f32 v[4:5], v[56:57], v[4:5]
	v_and_b32_e32 v79, 0xffff0000, v1
	v_pk_fma_f32 v[4:5], v[56:57], v[84:85], v[4:5] op_sel:[0,0,1] op_sel_hi:[1,1,0]
	v_lshlrev_b32_e32 v83, 16, v2
	v_pk_fma_f32 v[84:85], v[34:35], v[78:79], v[4:5]
	v_pk_mul_f32 v[4:5], v[32:33], v[78:79]
	v_mov_b32_e32 v82, v77
	v_pk_fma_f32 v[4:5], v[30:31], v[76:77], v[4:5]
	v_and_b32_e32 v1, 0xffff0000, v3
	v_pk_fma_f32 v[86:87], v[34:35], v[82:83], v[4:5]
	v_and_b32_e32 v5, 16, v3
	v_lshlrev_b32_e32 v3, 16, v3
	v_and_b32_e32 v4, 0xffff0000, v2
	v_mov_b32_e32 v76, v83
	v_mov_b32_e32 v77, v3
	v_mov_b32_e32 v2, v4
	v_mov_b32_e32 v0, v4
	v_pk_mov_b32 v[4:5], v[78:79], v[4:5] op_sel:[1,0]
	v_pk_mul_f32 v[76:77], v[32:33], v[76:77]
	v_mov_b32_e32 v82, v1
	v_pk_fma_f32 v[4:5], v[30:31], v[4:5], v[76:77]
	s_waitcnt lgkmcnt(0)
	s_barrier
; __device__ __forceinline__ uint4 ntld_u4(const void* p) { const ntu4_t v = __builtin_nontemporal_load((const ntu4_t*)p); return make_uint4(v.x, v.y, v.z, v.w); }
; __device__ __forceinline__ Raw8 load_raw8(const bf16_t* __restrict__ row, int n0) {
;     Raw8 r; r.body = ntld_u4(row + n0); r.eL = row[n0 > 0 ? n0 - 1 : 0]; r.eR = row[n0 + 8 < SEQ ? n0 + 8 : SEQ - 1]; return r; }
; __device__ void ph_hyena_fft(const Params& P, int j, const bf16_t* __restrict__ projAT, const float* __restrict__ kf, bf16_t* __restrict__ yaT, unsigned char* lds_raw) {
;     ...
;             { float xa[8], xb[8]; sconv8(xa0, n0, wa0, wa1, wa2, ba, xa); sconv8(xa1, n0, wa0, wa1, wa2, ba, xb);
; #pragma unroll
;               for (int k = 0; k < 8; ++k) { const v2f y = buf[ph0 + k]; va[k] = xa[k] * (y.x * invN + sk0 * va[k]); vb[k] = xb[k] * (y.y * invN + sk0 * vb[k]);
;                   buf[ph0 + k] = mkv2(va[k], vb[k]); buf[ph0 + 4352 + k] = mkv2(0.f, 0.f); } }
;             const Raw8 xb0 = load_raw8(x2row + o0, n0), xb1 = load_raw8(x2row + o1, n0);
;             const uint4 g0 = ntld_u4(grow + o0 + n0), g1 = ntld_u4(grow + o1 + n0);
	v_mov_b32_e32 v6, v3
	v_pk_fma_f32 v[78:79], v[34:35], v[0:1], v[4:5]
	v_pk_mul_f32 v[0:1], v[56:57], v[82:83]
	v_pk_add_f32 v[74:75], v[36:37], v[74:75]
	v_pk_fma_f32 v[0:1], v[56:57], v[2:3], v[0:1] op_sel:[0,0,1] op_sel_hi:[1,1,0]
	v_pk_add_f32 v[68:69], v[36:37], v[68:69]
	v_pk_fma_f32 v[82:83], v[34:35], v[6:7], v[0:1]
	ds_read2_b64 v[0:3], v145 offset1:1
	ds_read2_b64 v[4:7], v145 offset0:2 offset1:3
	s_mov_b32 s14, 0
	s_mov_b32 s15, s14
	s_mov_b32 s0, s14
	s_waitcnt lgkmcnt(1)
	v_mov_b32_e32 v76, v0
	s_waitcnt lgkmcnt(0)
	v_mov_b32_e32 v77, v4
	v_mov_b32_e32 v4, v1
	v_pk_mul_f32 v[0:1], v[4:5], s[80:81] op_sel_hi:[1,0]
	v_mov_b32_e32 v4, v2
	v_mov_b32_e32 v5, v6
	v_pk_mul_f32 v[4:5], v[4:5], s[80:81] op_sel_hi:[1,0]
	v_pk_mul_f32 v[76:77], v[76:77], s[80:81] op_sel_hi:[1,0]
	v_pk_fma_f32 v[4:5], v[44:45], v[62:63], v[4:5]
	v_mov_b32_e32 v6, v3
	v_pk_fma_f32 v[64:65], v[44:45], v[64:65], v[76:77]
	v_pk_mul_f32 v[74:75], v[74:75], v[4:5]
	v_pk_mul_f32 v[2:3], v[6:7], s[80:81] op_sel_hi:[1,0]
	v_pk_add_f32 v[4:5], v[36:37], v[84:85]
	v_pk_fma_f32 v[0:1], v[44:45], v[66:67], v[0:1]
	v_pk_mul_f32 v[76:77], v[68:69], v[64:65]
	v_pk_add_f32 v[6:7], v[36:37], v[86:87]
	v_pk_mul_f32 v[68:69], v[4:5], v[0:1]
	v_pk_fma_f32 v[0:1], v[44:45], v[70:71], v[2:3]
	s_mov_b32 s1, s14
	v_pk_mul_f32 v[66:67], v[6:7], v[0:1]
	v_mov_b32_e32 v0, v76
	v_mov_b32_e32 v1, v68
	v_mov_b32_e32 v2, v74
	v_mov_b32_e32 v3, v66
	v_mov_b64_e32 v[88:89], s[14:15]
	v_mov_b64_e32 v[90:91], s[0:1]
	ds_write2_b64 v145, v[0:1], v[2:3] offset1:1
	v_mov_b32_e32 v0, v77
	v_mov_b32_e32 v1, v69
	v_mov_b32_e32 v2, v75
	v_mov_b32_e32 v3, v67
	ds_write2_b64 v142, v[88:89], v[90:91] offset1:1
	ds_write2_b64 v145, v[0:1], v[2:3] offset0:2 offset1:3
	ds_write2_b64 v138, v[88:89], v[90:91] offset1:1
	ds_read2_b64 v[0:3], v145 offset0:4 offset1:5
	ds_read2_b64 v[4:7], v145 offset0:6 offset1:7
	v_pk_add_f32 v[70:71], v[36:37], v[72:73]
	v_pk_add_f32 v[64:65], v[36:37], v[80:81]
	s_lshl_b32 s62, s11, 1
	s_waitcnt lgkmcnt(1)
	v_mov_b32_e32 v62, v0
	s_waitcnt lgkmcnt(0)
	v_mov_b32_e32 v63, v4
	v_mov_b32_e32 v4, v1
	v_pk_mul_f32 v[0:1], v[4:5], s[80:81] op_sel_hi:[1,0]
	v_mov_b32_e32 v4, v2
	v_mov_b32_e32 v5, v6
	v_pk_mul_f32 v[4:5], v[4:5], s[80:81] op_sel_hi:[1,0]
	v_pk_mul_f32 v[62:63], v[62:63], s[80:81] op_sel_hi:[1,0]
	v_pk_fma_f32 v[4:5], v[44:45], v[10:11], v[4:5]
	v_mov_b32_e32 v6, v3
	v_pk_fma_f32 v[8:9], v[44:45], v[8:9], v[62:63]
	v_pk_mul_f32 v[70:71], v[70:71], v[4:5]
	v_pk_mul_f32 v[2:3], v[6:7], s[80:81] op_sel_hi:[1,0]
	v_pk_add_f32 v[4:5], v[36:37], v[78:79]
	v_pk_fma_f32 v[0:1], v[44:45], v[12:13], v[0:1]
	v_pk_mul_f32 v[72:73], v[64:65], v[8:9]
	v_pk_add_f32 v[6:7], v[36:37], v[82:83]
	v_pk_mul_f32 v[64:65], v[4:5], v[0:1]
	v_pk_fma_f32 v[0:1], v[44:45], v[14:15], v[2:3]
	v_mov_b32_e32 v2, v70
	v_pk_mul_f32 v[62:63], v[6:7], v[0:1]
	v_mov_b32_e32 v0, v72
	v_mov_b32_e32 v1, v64
	v_mov_b32_e32 v3, v62
	s_add_u32 s0, s61, s62
	ds_write2_b64 v145, v[0:1], v[2:3] offset0:4 offset1:5
	v_mov_b32_e32 v0, v73
	v_mov_b32_e32 v1, v65
	v_mov_b32_e32 v2, v71
	v_mov_b32_e32 v3, v63
	s_addc_u32 s1, s52, 0
	ds_write2_b64 v140, v[88:89], v[90:91] offset1:1
	ds_write2_b64 v145, v[0:1], v[2:3] offset0:6 offset1:7
	ds_write2_b64 v137, v[88:89], v[90:91] offset1:1
	v_lshl_add_u64 v[0:1], s[0:1], 0, v[16:17]
	s_lshl_b32 s6, s10, 1
	global_load_dwordx4 v[4:7], v[0:1], off nt
	global_load_ushort v147, v146, s[0:1] offset:-2
	v_lshl_add_u64 v[0:1], s[0:1], 0, v[22:23]
	s_add_u32 s0, s61, s6
	s_addc_u32 s1, s52, 0
	global_load_ushort v148, v[0:1], off offset:16
	v_lshl_add_u64 v[0:1], s[0:1], 0, v[16:17]
	global_load_dwordx4 v[8:11], v[0:1], off nt
	global_load_ushort v149, v146, s[0:1] offset:-2
	v_lshl_add_u64 v[0:1], s[0:1], 0, v[22:23]
	s_mov_b32 s7, s63
	global_load_ushort v150, v[0:1], off offset:16
	v_lshl_add_u64 v[0:1], v[48:49], 0, s[62:63]
	global_load_dwordx4 v[12:15], v[0:1], off nt
	v_lshl_add_u64 v[0:1], v[48:49], 0, s[6:7]
	global_load_dwordx4 v[0:3], v[0:1], off nt
	s_cmp_eq_u32 s53, 3
	s_cbranch_scc1 .Lhy_nopf
	s_add_i32 s100, s53, 1
	s_lshl_b32 s100, s100, 14
	s_add_u32 s100, s47, s100
	s_addc_u32 s101, s58, 0
	v_lshl_add_u64 v[188:189], s[100:101], 0, v[16:17]
	v_lshl_add_u64 v[190:191], s[100:101], 0, v[22:23]
	global_load_ushort v184, v146, s[100:101] offset:-2
	global_load_dwordx4 v[176:179], v[188:189], off nt
	s_add_u32 s100, s100, 0x2000
	s_addc_u32 s101, s101, 0
	v_lshl_add_u64 v[188:189], s[100:101], 0, v[22:23]
	global_load_ushort v185, v146, s[100:101] offset:-2
	global_load_ushort v186, v[188:189], off offset:16
	global_load_ushort v187, v[190:191], off offset:16
	v_lshl_add_u64 v[188:189], s[100:101], 0, v[16:17]
	global_load_dwordx4 v[180:183], v[188:189], off nt

; #define LAS __attribute__((address_space(3)))
; __device__ __forceinline__ int otid() { int t = threadIdx.x; asm volatile("" : "+v"(t)); return t; }
; __device__ __forceinline__ cf twc(cf ws, int k16) { if (k16 == 0) return ws; if (k16 == 4) return cf{ws.y, -ws.x}; return cmul(ws, cf{c16(k16), -s16(k16)}); }
; template <int LR> __device__ __forceinline__ void dif_reg(cf (&x)[1 << LR], cf w) {
;     constexpr int R = 1 << LR; cf ws = w;
; #pragma unroll
;     for (int s = 0; s < LR; ++s) { const int half = R >> (s + 1);
; #pragma unroll
;         for (int m0 = 0; m0 < R; m0 += 2 * half)
; #pragma unroll
;             for (int mm = 0; mm < half; ++mm) { const int ia = m0 + mm, ib = ia + half; const cf a = x[ia], b = x[ib];
;                 x[ia] = cf{a.x + b.x, a.y + b.y}; const cf d{a.x - b.x, a.y - b.y};
;                 x[ib] = cmul(d, twc(ws, (mm << s) * (16 / R))); }
;         ws = cmul(ws, ws); }
; }
; template <int LR, bool INV> __device__ __forceinline__ void fft_pass(ldsf2 buf, int base, int stride, int twi) {
;     constexpr int R = 1 << LR; cf x[R];
;     const v2f wv = ((ldsf2)((LAS unsigned char*)buf + 139264))[twi];
; #pragma unroll
;     for (int m = 0; m < R; ++m) { const v2f v = buf[base + m * stride]; x[m] = cf{v.x, v.y}; }
;     const cf w{wv.x, wv.y};
;     if (INV) dit_reg<LR>(x, w); else dif_reg<LR>(x, w);
; #pragma unroll
;     for (int m = 0; m < R; ++m) buf[base + m * stride] = mkv2(x[m].x, x[m].y);
; }
; __device__ __forceinline__ void wave_lds_fence() { asm volatile("s_waitcnt lgkmcnt(0)" ::: "memory"); }
; __device__ __forceinline__ void fft_fwd_abc(ldsf2 buf) {
;     const int tid = otid(); const int wv = tid >> 6, l = tid & 63;
; #pragma unroll 1
;     for (int u = 0; u < 2; ++u) { const int bf = tid + NT * u; fft_pass<3, false>(buf, bf + (bf >> 4), 1088, bf); }
.LBB0_359:
	v_cndmask_b32_e64 v79, 0, 1, s[10:11]
	v_add_u32_e32 v80, s14, v78
	v_cmp_ne_u32_e32 vcc, 1, v79
	v_ashrrev_i32_e32 v79, 4, v80
	v_lshl_add_u32 v80, v80, 3, 0
	v_add_u32_e32 v81, 0x22000, v80
	v_lshl_add_u32 v79, v79, 3, v80
	ds_read_b64 v[96:97], v81
	ds_read2st64_b64 v[80:83], v79 offset1:17
	ds_read2st64_b64 v[84:87], v79 offset0:68 offset1:85
	ds_read2st64_b64 v[88:91], v79 offset0:34 offset1:51
	ds_read2st64_b64 v[92:95], v79 offset0:102 offset1:119
	s_waitcnt lgkmcnt(4)
	v_pk_add_f32 v[98:99], v[96:97], v[96:97] op_sel:[0,1] op_sel_hi:[1,0] neg_lo:[0,0] neg_hi:[0,1]
	v_pk_mul_f32 v[100:101], v[98:99], s[16:17] op_sel:[0,0] op_sel_hi:[1,0]
	v_pk_mul_f32 v[102:103], v[98:99], s[16:17] op_sel:[1,0] op_sel_hi:[0,0] neg_lo:[0,0] neg_hi:[1,0]
	v_pk_mul_f32 v[104:105], v[96:97], v[96:97] op_sel:[1,1] op_sel_hi:[1,0]
	v_pk_fma_f32 v[104:105], v[96:97], v[96:97], v[104:105] op_sel:[0,0,0] op_sel_hi:[0,1,1] neg_lo:[0,0,1] neg_hi:[0,0,0]
	v_pk_mul_f32 v[106:107], v[104:105], v[104:105] op_sel:[1,1] op_sel_hi:[1,0]
	v_pk_fma_f32 v[106:107], v[104:105], v[104:105], v[106:107] op_sel:[0,0,0] op_sel_hi:[0,1,1] neg_lo:[0,0,1] neg_hi:[0,0,0]
	s_waitcnt lgkmcnt(0)
	v_pk_add_f32 v[108:109], v[80:81], v[84:85] neg_lo:[0,1] neg_hi:[0,1]
	v_pk_add_f32 v[110:111], v[82:83], v[86:87] neg_lo:[0,1] neg_hi:[0,1]
	v_pk_add_f32 v[112:113], v[88:89], v[92:93] neg_lo:[0,1] neg_hi:[0,1]
	v_pk_add_f32 v[114:115], v[90:91], v[94:95] neg_lo:[0,1] neg_hi:[0,1]
	v_pk_add_f32 v[80:81], v[80:81], v[84:85]
	v_pk_add_f32 v[82:83], v[82:83], v[86:87]
	v_pk_add_f32 v[88:89], v[88:89], v[92:93]
	v_pk_add_f32 v[90:91], v[90:91], v[94:95]
	v_pk_mul_f32 v[84:85], v[108:109], v[96:97] op_sel:[1,1] op_sel_hi:[1,0]
	v_pk_mul_f32 v[86:87], v[110:111], v[100:101] op_sel:[1,1] op_sel_hi:[1,0]
	v_pk_mul_f32 v[92:93], v[112:113], v[96:97] op_sel:[1,0] op_sel_hi:[1,1]
	v_pk_mul_f32 v[94:95], v[114:115], v[102:103] op_sel:[1,1] op_sel_hi:[1,0]
	v_pk_fma_f32 v[84:85], v[108:109], v[96:97], v[84:85] op_sel:[0,0,0] op_sel_hi:[0,1,1] neg_lo:[0,0,1] neg_hi:[0,0,0]
	v_pk_fma_f32 v[86:87], v[110:111], v[100:101], v[86:87] op_sel:[0,0,0] op_sel_hi:[0,1,1] neg_lo:[0,0,1] neg_hi:[0,0,0]
	v_pk_fma_f32 v[92:93], v[112:113], v[96:97], v[92:93] op_sel:[0,1,0] op_sel_hi:[0,0,1] neg_lo:[0,0,0] neg_hi:[0,1,0]
	v_pk_fma_f32 v[94:95], v[114:115], v[102:103], v[94:95] op_sel:[0,0,0] op_sel_hi:[0,1,1] neg_lo:[0,0,1] neg_hi:[0,0,0]
	v_pk_add_f32 v[108:109], v[80:81], v[88:89] neg_lo:[0,1] neg_hi:[0,1]
	v_pk_add_f32 v[110:111], v[82:83], v[90:91] neg_lo:[0,1] neg_hi:[0,1]
	v_pk_add_f32 v[112:113], v[84:85], v[92:93] neg_lo:[0,1] neg_hi:[0,1]
	v_pk_add_f32 v[114:115], v[86:87], v[94:95] neg_lo:[0,1] neg_hi:[0,1]
	v_pk_add_f32 v[80:81], v[80:81], v[88:89]
	v_pk_add_f32 v[82:83], v[82:83], v[90:91]
	v_pk_add_f32 v[84:85], v[84:85], v[92:93]
	v_pk_add_f32 v[86:87], v[86:87], v[94:95]
	v_pk_mul_f32 v[88:89], v[108:109], v[104:105] op_sel:[1,1] op_sel_hi:[1,0]
	v_pk_mul_f32 v[90:91], v[110:111], v[104:105] op_sel:[1,0] op_sel_hi:[1,1]
	v_pk_mul_f32 v[92:93], v[112:113], v[104:105] op_sel:[1,1] op_sel_hi:[1,0]
	v_pk_mul_f32 v[94:95], v[114:115], v[104:105] op_sel:[1,0] op_sel_hi:[1,1]
	v_pk_fma_f32 v[88:89], v[108:109], v[104:105], v[88:89] op_sel:[0,0,0] op_sel_hi:[0,1,1] neg_lo:[0,0,1] neg_hi:[0,0,0]
	v_pk_fma_f32 v[90:91], v[110:111], v[104:105], v[90:91] op_sel:[0,1,0] op_sel_hi:[0,0,1] neg_lo:[0,0,0] neg_hi:[0,1,0]
	v_pk_fma_f32 v[92:93], v[112:113], v[104:105], v[92:93] op_sel:[0,0,0] op_sel_hi:[0,1,1] neg_lo:[0,0,1] neg_hi:[0,0,0]
	v_pk_fma_f32 v[94:95], v[114:115], v[104:105], v[94:95] op_sel:[0,1,0] op_sel_hi:[0,0,1] neg_lo:[0,0,0] neg_hi:[0,1,0]
	v_pk_add_f32 v[108:109], v[80:81], v[82:83] neg_lo:[0,1] neg_hi:[0,1]
	v_pk_add_f32 v[110:111], v[88:89], v[90:91] neg_lo:[0,1] neg_hi:[0,1]
	v_pk_add_f32 v[112:113], v[84:85], v[86:87] neg_lo:[0,1] neg_hi:[0,1]
	v_pk_add_f32 v[114:115], v[92:93], v[94:95] neg_lo:[0,1] neg_hi:[0,1]
	v_pk_add_f32 v[80:81], v[80:81], v[82:83]
	v_pk_add_f32 v[88:89], v[88:89], v[90:91]
	v_pk_add_f32 v[84:85], v[84:85], v[86:87]
	v_pk_add_f32 v[92:93], v[92:93], v[94:95]
	v_pk_mul_f32 v[82:83], v[108:109], v[106:107] op_sel:[1,1] op_sel_hi:[1,0]
	v_pk_mul_f32 v[90:91], v[110:111], v[106:107] op_sel:[1,1] op_sel_hi:[1,0]
	v_pk_mul_f32 v[86:87], v[112:113], v[106:107] op_sel:[1,1] op_sel_hi:[1,0]
	v_pk_mul_f32 v[94:95], v[114:115], v[106:107] op_sel:[1,1] op_sel_hi:[1,0]
	v_pk_fma_f32 v[82:83], v[108:109], v[106:107], v[82:83] op_sel:[0,0,0] op_sel_hi:[0,1,1] neg_lo:[0,0,1] neg_hi:[0,0,0]
	v_pk_fma_f32 v[90:91], v[110:111], v[106:107], v[90:91] op_sel:[0,0,0] op_sel_hi:[0,1,1] neg_lo:[0,0,1] neg_hi:[0,0,0]
	v_pk_fma_f32 v[86:87], v[112:113], v[106:107], v[86:87] op_sel:[0,0,0] op_sel_hi:[0,1,1] neg_lo:[0,0,1] neg_hi:[0,0,0]
	v_pk_fma_f32 v[94:95], v[114:115], v[106:107], v[94:95] op_sel:[0,0,0] op_sel_hi:[0,1,1] neg_lo:[0,0,1] neg_hi:[0,0,0]
	ds_write2st64_b64 v79, v[80:81], v[82:83] offset1:17
	ds_write2st64_b64 v79, v[88:89], v[90:91] offset0:34 offset1:51
	ds_write2st64_b64 v79, v[84:85], v[86:87] offset0:68 offset1:85
	ds_write2st64_b64 v79, v[92:93], v[94:95] offset0:102 offset1:119
	s_movk_i32 s14, 0x200
	s_mov_b64 s[10:11], 0
	s_cbranch_vccz .LBB0_359
	s_waitcnt lgkmcnt(0)
	s_barrier
	v_lshlrev_b32_e32 v80, 4, v78
	v_and_b32_e32 v79, 63, v78
	v_and_b32_e32 v80, 0xfffffc00, v80
	s_mov_b32 s0, 0
	s_mov_b64 s[10:11], -1
; #define LAS __attribute__((address_space(3)))
; __device__ __forceinline__ int otid() { int t = threadIdx.x; asm volatile("" : "+v"(t)); return t; }
; __device__ __forceinline__ cf twc(cf ws, int k16) { if (k16 == 0) return ws; if (k16 == 4) return cf{ws.y, -ws.x}; return cmul(ws, cf{c16(k16), -s16(k16)}); }
; __device__ __forceinline__ void lds_barrier() { asm volatile("s_waitcnt lgkmcnt(0)\n\ts_barrier" ::: "memory"); }
; template <int LR> __device__ __forceinline__ void dif_reg(cf (&x)[1 << LR], cf w) {
;     constexpr int R = 1 << LR; cf ws = w;
; #pragma unroll
;     for (int s = 0; s < LR; ++s) { const int half = R >> (s + 1);
; #pragma unroll
;         for (int m0 = 0; m0 < R; m0 += 2 * half)
; #pragma unroll
;             for (int mm = 0; mm < half; ++mm) { const int ia = m0 + mm, ib = ia + half; const cf a = x[ia], b = x[ib];
;                 x[ia] = cf{a.x + b.x, a.y + b.y}; const cf d{a.x - b.x, a.y - b.y};
;                 x[ib] = cmul(d, twc(ws, (mm << s) * (16 / R))); }
;         ws = cmul(ws, ws); }
; }
; template <int LR, bool INV> __device__ __forceinline__ void fft_pass(ldsf2 buf, int base, int stride, int twi) {
;     constexpr int R = 1 << LR; cf x[R];
;     const v2f wv = ((ldsf2)((LAS unsigned char*)buf + 139264))[twi];
; #pragma unroll
;     for (int m = 0; m < R; ++m) { const v2f v = buf[base + m * stride]; x[m] = cf{v.x, v.y}; }
;     const cf w{wv.x, wv.y};
;     if (INV) dit_reg<LR>(x, w); else dif_reg<LR>(x, w);
; #pragma unroll
;     for (int m = 0; m < R; ++m) buf[base + m * stride] = mkv2(x[m].x, x[m].y);
; }
; __device__ __forceinline__ void wave_lds_fence() { asm volatile("s_waitcnt lgkmcnt(0)" ::: "memory"); }
; __device__ __forceinline__ void fft_fwd_abc(ldsf2 buf) {
;     const int tid = otid(); const int wv = tid >> 6, l = tid & 63;
; #pragma unroll 1
;     for (int u = 0; u < 2; ++u) { const int bf = tid + NT * u; fft_pass<3, false>(buf, bf + (bf >> 4), 1088, bf); }
;     lds_barrier();
; #pragma unroll 1
;     for (int u = 0; u < 2; ++u) { const int o = l + 64 * u, e0 = wv * 1024 + o; fft_pass<3, false>(buf, e0 + (e0 >> 4), 136, o * 8); }
.LBB0_361:
	v_cndmask_b32_e64 v81, 0, 1, s[10:11]
	v_or_b32_e32 v82, s0, v79
	v_cmp_ne_u32_e32 vcc, 1, v81
	v_or_b32_e32 v81, v82, v80
	v_lshl_add_u32 v82, v82, 6, 0
	v_ashrrev_i32_e32 v83, 4, v81
	v_add_u32_e32 v82, 0x22000, v82
	v_lshlrev_b32_e32 v81, 3, v81
	ds_read_b64 v[98:99], v82
	v_lshlrev_b32_e32 v82, 3, v83
	v_add3_u32 v81, 0, v81, v82
	v_add_u32_e32 v121, 0x800, v81
	ds_read2_b64 v[82:85], v81 offset1:136
	v_add_u32_e32 v126, 0x1000, v81
	v_add_u32_e32 v127, 0x1800, v81
	ds_read2_b64 v[86:89], v121 offset0:16 offset1:152
	ds_read2_b64 v[90:93], v126 offset0:32 offset1:168
	ds_read2_b64 v[94:97], v127 offset0:48 offset1:184
	s_waitcnt lgkmcnt(4)
	v_pk_add_f32 v[100:101], v[98:99], v[98:99] op_sel:[0,1] op_sel_hi:[1,0] neg_lo:[0,0] neg_hi:[0,1]
	v_pk_mul_f32 v[102:103], v[100:101], s[16:17] op_sel:[0,0] op_sel_hi:[1,0]
	v_pk_mul_f32 v[104:105], v[100:101], s[16:17] op_sel:[1,0] op_sel_hi:[0,0] neg_lo:[0,0] neg_hi:[1,0]
	v_pk_mul_f32 v[106:107], v[98:99], v[98:99] op_sel:[1,1] op_sel_hi:[1,0]
	v_pk_fma_f32 v[106:107], v[98:99], v[98:99], v[106:107] op_sel:[0,0,0] op_sel_hi:[0,1,1] neg_lo:[0,0,1] neg_hi:[0,0,0]
	v_pk_mul_f32 v[108:109], v[106:107], v[106:107] op_sel:[1,1] op_sel_hi:[1,0]
	v_pk_fma_f32 v[108:109], v[106:107], v[106:107], v[108:109] op_sel:[0,0,0] op_sel_hi:[0,1,1] neg_lo:[0,0,1] neg_hi:[0,0,0]
	s_waitcnt lgkmcnt(0)
	v_pk_add_f32 v[110:111], v[82:83], v[90:91] neg_lo:[0,1] neg_hi:[0,1]
	v_pk_add_f32 v[112:113], v[84:85], v[92:93] neg_lo:[0,1] neg_hi:[0,1]
	v_pk_add_f32 v[114:115], v[86:87], v[94:95] neg_lo:[0,1] neg_hi:[0,1]
	v_pk_add_f32 v[116:117], v[88:89], v[96:97] neg_lo:[0,1] neg_hi:[0,1]
	v_pk_add_f32 v[82:83], v[82:83], v[90:91]
	v_pk_add_f32 v[84:85], v[84:85], v[92:93]
	v_pk_add_f32 v[86:87], v[86:87], v[94:95]
	v_pk_add_f32 v[88:89], v[88:89], v[96:97]
	v_pk_mul_f32 v[90:91], v[110:111], v[98:99] op_sel:[1,1] op_sel_hi:[1,0]
	v_pk_mul_f32 v[92:93], v[112:113], v[102:103] op_sel:[1,1] op_sel_hi:[1,0]
	v_pk_mul_f32 v[94:95], v[114:115], v[98:99] op_sel:[1,0] op_sel_hi:[1,1]
	v_pk_mul_f32 v[96:97], v[116:117], v[104:105] op_sel:[1,1] op_sel_hi:[1,0]
	v_pk_fma_f32 v[90:91], v[110:111], v[98:99], v[90:91] op_sel:[0,0,0] op_sel_hi:[0,1,1] neg_lo:[0,0,1] neg_hi:[0,0,0]
	v_pk_fma_f32 v[92:93], v[112:113], v[102:103], v[92:93] op_sel:[0,0,0] op_sel_hi:[0,1,1] neg_lo:[0,0,1] neg_hi:[0,0,0]
	v_pk_fma_f32 v[94:95], v[114:115], v[98:99], v[94:95] op_sel:[0,1,0] op_sel_hi:[0,0,1] neg_lo:[0,0,0] neg_hi:[0,1,0]
	v_pk_fma_f32 v[96:97], v[116:117], v[104:105], v[96:97] op_sel:[0,0,0] op_sel_hi:[0,1,1] neg_lo:[0,0,1] neg_hi:[0,0,0]
	v_pk_add_f32 v[110:111], v[82:83], v[86:87] neg_lo:[0,1] neg_hi:[0,1]
	v_pk_add_f32 v[112:113], v[84:85], v[88:89] neg_lo:[0,1] neg_hi:[0,1]
	v_pk_add_f32 v[114:115], v[90:91], v[94:95] neg_lo:[0,1] neg_hi:[0,1]
	v_pk_add_f32 v[116:117], v[92:93], v[96:97] neg_lo:[0,1] neg_hi:[0,1]
	v_pk_add_f32 v[82:83], v[82:83], v[86:87]
	v_pk_add_f32 v[84:85], v[84:85], v[88:89]
	v_pk_add_f32 v[90:91], v[90:91], v[94:95]
	v_pk_add_f32 v[92:93], v[92:93], v[96:97]
	v_pk_mul_f32 v[86:87], v[110:111], v[106:107] op_sel:[1,1] op_sel_hi:[1,0]
	v_pk_mul_f32 v[88:89], v[112:113], v[106:107] op_sel:[1,0] op_sel_hi:[1,1]
	v_pk_mul_f32 v[94:95], v[114:115], v[106:107] op_sel:[1,1] op_sel_hi:[1,0]
	v_pk_mul_f32 v[96:97], v[116:117], v[106:107] op_sel:[1,0] op_sel_hi:[1,1]
	v_pk_fma_f32 v[86:87], v[110:111], v[106:107], v[86:87] op_sel:[0,0,0] op_sel_hi:[0,1,1] neg_lo:[0,0,1] neg_hi:[0,0,0]
	v_pk_fma_f32 v[88:89], v[112:113], v[106:107], v[88:89] op_sel:[0,1,0] op_sel_hi:[0,0,1] neg_lo:[0,0,0] neg_hi:[0,1,0]
	v_pk_fma_f32 v[94:95], v[114:115], v[106:107], v[94:95] op_sel:[0,0,0] op_sel_hi:[0,1,1] neg_lo:[0,0,1] neg_hi:[0,0,0]
	v_pk_fma_f32 v[96:97], v[116:117], v[106:107], v[96:97] op_sel:[0,1,0] op_sel_hi:[0,0,1] neg_lo:[0,0,0] neg_hi:[0,1,0]
	v_pk_add_f32 v[110:111], v[82:83], v[84:85] neg_lo:[0,1] neg_hi:[0,1]
	v_pk_add_f32 v[112:113], v[86:87], v[88:89] neg_lo:[0,1] neg_hi:[0,1]
	v_pk_add_f32 v[114:115], v[90:91], v[92:93] neg_lo:[0,1] neg_hi:[0,1]
	v_pk_add_f32 v[116:117], v[94:95], v[96:97] neg_lo:[0,1] neg_hi:[0,1]
	v_pk_add_f32 v[82:83], v[82:83], v[84:85]
	v_pk_add_f32 v[86:87], v[86:87], v[88:89]
	v_pk_add_f32 v[90:91], v[90:91], v[92:93]
	v_pk_add_f32 v[94:95], v[94:95], v[96:97]
	v_pk_mul_f32 v[84:85], v[110:111], v[108:109] op_sel:[1,1] op_sel_hi:[1,0]
	v_pk_mul_f32 v[88:89], v[112:113], v[108:109] op_sel:[1,1] op_sel_hi:[1,0]
	v_pk_mul_f32 v[92:93], v[114:115], v[108:109] op_sel:[1,1] op_sel_hi:[1,0]
	v_pk_mul_f32 v[96:97], v[116:117], v[108:109] op_sel:[1,1] op_sel_hi:[1,0]
	v_pk_fma_f32 v[84:85], v[110:111], v[108:109], v[84:85] op_sel:[0,0,0] op_sel_hi:[0,1,1] neg_lo:[0,0,1] neg_hi:[0,0,0]
	v_pk_fma_f32 v[88:89], v[112:113], v[108:109], v[88:89] op_sel:[0,0,0] op_sel_hi:[0,1,1] neg_lo:[0,0,1] neg_hi:[0,0,0]
	v_pk_fma_f32 v[92:93], v[114:115], v[108:109], v[92:93] op_sel:[0,0,0] op_sel_hi:[0,1,1] neg_lo:[0,0,1] neg_hi:[0,0,0]
	v_pk_fma_f32 v[96:97], v[116:117], v[108:109], v[96:97] op_sel:[0,0,0] op_sel_hi:[0,1,1] neg_lo:[0,0,1] neg_hi:[0,0,0]
	ds_write2_b64 v81, v[82:83], v[84:85] offset1:136
	ds_write2_b64 v121, v[86:87], v[88:89] offset0:16 offset1:152
	ds_write2_b64 v126, v[90:91], v[92:93] offset0:32 offset1:168
	ds_write2_b64 v127, v[94:95], v[96:97] offset0:48 offset1:184
	s_mov_b32 s0, 64
	s_mov_b64 s[10:11], 0
	s_cbranch_vccz .LBB0_361
	v_and_b32_e32 v78, 15, v78
	s_waitcnt lgkmcnt(0)
	v_lshlrev_b32_e32 v79, 3, v79
	v_lshlrev_b32_e32 v81, 9, v78
	v_and_or_b32 v79, v79, s90, v80
	v_add_u32_e32 v80, 0, v81
	v_lshl_add_u32 v78, v78, 3, 0
	s_mov_b32 s0, 0
	s_mov_b64 s[10:11], -1
	v_add_u32_e32 v80, 0x22000, v80
; #define LAS __attribute__((address_space(3)))
; __device__ __forceinline__ int otid() { int t = threadIdx.x; asm volatile("" : "+v"(t)); return t; }
; __device__ __forceinline__ cf twc(cf ws, int k16) { if (k16 == 0) return ws; if (k16 == 4) return cf{ws.y, -ws.x}; return cmul(ws, cf{c16(k16), -s16(k16)}); }
; __device__ __forceinline__ void lds_barrier() { asm volatile("s_waitcnt lgkmcnt(0)\n\ts_barrier" ::: "memory"); }
; template <int LR> __device__ __forceinline__ void dif_reg(cf (&x)[1 << LR], cf w) {
;     constexpr int R = 1 << LR; cf ws = w;
; #pragma unroll
;     for (int s = 0; s < LR; ++s) { const int half = R >> (s + 1);
; #pragma unroll
;         for (int m0 = 0; m0 < R; m0 += 2 * half)
; #pragma unroll
;             for (int mm = 0; mm < half; ++mm) { const int ia = m0 + mm, ib = ia + half; const cf a = x[ia], b = x[ib];
;                 x[ia] = cf{a.x + b.x, a.y + b.y}; const cf d{a.x - b.x, a.y - b.y};
;                 x[ib] = cmul(d, twc(ws, (mm << s) * (16 / R))); }
;         ws = cmul(ws, ws); }
; }
; template <int LR, bool INV> __device__ __forceinline__ void fft_pass(ldsf2 buf, int base, int stride, int twi) {
;     constexpr int R = 1 << LR; cf x[R];
;     const v2f wv = ((ldsf2)((LAS unsigned char*)buf + 139264))[twi];
; #pragma unroll
;     for (int m = 0; m < R; ++m) { const v2f v = buf[base + m * stride]; x[m] = cf{v.x, v.y}; }
;     const cf w{wv.x, wv.y};
;     if (INV) dit_reg<LR>(x, w); else dif_reg<LR>(x, w);
; #pragma unroll
;     for (int m = 0; m < R; ++m) buf[base + m * stride] = mkv2(x[m].x, x[m].y);
; }
; __device__ __forceinline__ void wave_lds_fence() { asm volatile("s_waitcnt lgkmcnt(0)" ::: "memory"); }
; __device__ __forceinline__ void fft_fwd_abc(ldsf2 buf) {
;     const int tid = otid(); const int wv = tid >> 6, l = tid & 63;
; #pragma unroll 1
;     for (int u = 0; u < 2; ++u) { const int bf = tid + NT * u; fft_pass<3, false>(buf, bf + (bf >> 4), 1088, bf); }
;     lds_barrier();
; #pragma unroll 1
;     for (int u = 0; u < 2; ++u) { const int o = l + 64 * u, e0 = wv * 1024 + o; fft_pass<3, false>(buf, e0 + (e0 >> 4), 136, o * 8); }
;     wave_lds_fence();
; #pragma unroll 1
;     for (int u = 0; u < 2; ++u) { const int j = l + 64 * u, o = j & 15, e0 = wv * 1024 + (j >> 4) * 128 + o; fft_pass<3, false>(buf, e0 + (e0 >> 4), 17, o * 64); }
.LBB0_363:
	v_or_b32_e32 v81, s0, v79
	ds_read_b64 v[98:99], v80
	v_lshlrev_b32_e32 v82, 3, v81
	v_ashrrev_i32_e32 v81, 1, v81
	v_add3_u32 v81, v78, v82, v81
	ds_read2_b64 v[82:85], v81 offset1:17
	ds_read2_b64 v[86:89], v81 offset0:34 offset1:51
	ds_read2_b64 v[90:93], v81 offset0:68 offset1:85
	ds_read2_b64 v[94:97], v81 offset0:102 offset1:119
	s_waitcnt lgkmcnt(4)
	v_pk_add_f32 v[100:101], v[98:99], v[98:99] op_sel:[0,1] op_sel_hi:[1,0] neg_lo:[0,0] neg_hi:[0,1]
	v_pk_mul_f32 v[102:103], v[100:101], s[16:17] op_sel:[0,0] op_sel_hi:[1,0]
	v_pk_mul_f32 v[104:105], v[100:101], s[16:17] op_sel:[1,0] op_sel_hi:[0,0] neg_lo:[0,0] neg_hi:[1,0]
	v_pk_mul_f32 v[106:107], v[98:99], v[98:99] op_sel:[1,1] op_sel_hi:[1,0]
	v_pk_fma_f32 v[106:107], v[98:99], v[98:99], v[106:107] op_sel:[0,0,0] op_sel_hi:[0,1,1] neg_lo:[0,0,1] neg_hi:[0,0,0]
	v_pk_mul_f32 v[108:109], v[106:107], v[106:107] op_sel:[1,1] op_sel_hi:[1,0]
	v_pk_fma_f32 v[108:109], v[106:107], v[106:107], v[108:109] op_sel:[0,0,0] op_sel_hi:[0,1,1] neg_lo:[0,0,1] neg_hi:[0,0,0]
	s_waitcnt lgkmcnt(0)
	v_pk_add_f32 v[110:111], v[82:83], v[90:91] neg_lo:[0,1] neg_hi:[0,1]
	v_pk_add_f32 v[112:113], v[84:85], v[92:93] neg_lo:[0,1] neg_hi:[0,1]
	v_pk_add_f32 v[114:115], v[86:87], v[94:95] neg_lo:[0,1] neg_hi:[0,1]
	v_pk_add_f32 v[116:117], v[88:89], v[96:97] neg_lo:[0,1] neg_hi:[0,1]
	v_pk_add_f32 v[82:83], v[82:83], v[90:91]
	v_pk_add_f32 v[84:85], v[84:85], v[92:93]
	v_pk_add_f32 v[86:87], v[86:87], v[94:95]
	v_pk_add_f32 v[88:89], v[88:89], v[96:97]
	v_pk_mul_f32 v[90:91], v[110:111], v[98:99] op_sel:[1,1] op_sel_hi:[1,0]
	v_pk_mul_f32 v[92:93], v[112:113], v[102:103] op_sel:[1,1] op_sel_hi:[1,0]
	v_pk_mul_f32 v[94:95], v[114:115], v[98:99] op_sel:[1,0] op_sel_hi:[1,1]
	v_pk_mul_f32 v[96:97], v[116:117], v[104:105] op_sel:[1,1] op_sel_hi:[1,0]
	v_pk_fma_f32 v[90:91], v[110:111], v[98:99], v[90:91] op_sel:[0,0,0] op_sel_hi:[0,1,1] neg_lo:[0,0,1] neg_hi:[0,0,0]
	v_pk_fma_f32 v[92:93], v[112:113], v[102:103], v[92:93] op_sel:[0,0,0] op_sel_hi:[0,1,1] neg_lo:[0,0,1] neg_hi:[0,0,0]
	v_pk_fma_f32 v[94:95], v[114:115], v[98:99], v[94:95] op_sel:[0,1,0] op_sel_hi:[0,0,1] neg_lo:[0,0,0] neg_hi:[0,1,0]
	v_pk_fma_f32 v[96:97], v[116:117], v[104:105], v[96:97] op_sel:[0,0,0] op_sel_hi:[0,1,1] neg_lo:[0,0,1] neg_hi:[0,0,0]
	v_pk_add_f32 v[110:111], v[82:83], v[86:87] neg_lo:[0,1] neg_hi:[0,1]
	v_pk_add_f32 v[112:113], v[84:85], v[88:89] neg_lo:[0,1] neg_hi:[0,1]
	v_pk_add_f32 v[114:115], v[90:91], v[94:95] neg_lo:[0,1] neg_hi:[0,1]
	v_pk_add_f32 v[116:117], v[92:93], v[96:97] neg_lo:[0,1] neg_hi:[0,1]
	v_pk_add_f32 v[82:83], v[82:83], v[86:87]
	v_pk_add_f32 v[84:85], v[84:85], v[88:89]
	v_pk_add_f32 v[90:91], v[90:91], v[94:95]
	v_pk_add_f32 v[92:93], v[92:93], v[96:97]
	v_pk_mul_f32 v[86:87], v[110:111], v[106:107] op_sel:[1,1] op_sel_hi:[1,0]
	v_pk_mul_f32 v[88:89], v[112:113], v[106:107] op_sel:[1,0] op_sel_hi:[1,1]
	v_pk_mul_f32 v[94:95], v[114:115], v[106:107] op_sel:[1,1] op_sel_hi:[1,0]
	v_pk_mul_f32 v[96:97], v[116:117], v[106:107] op_sel:[1,0] op_sel_hi:[1,1]
	v_pk_fma_f32 v[86:87], v[110:111], v[106:107], v[86:87] op_sel:[0,0,0] op_sel_hi:[0,1,1] neg_lo:[0,0,1] neg_hi:[0,0,0]
	v_pk_fma_f32 v[88:89], v[112:113], v[106:107], v[88:89] op_sel:[0,1,0] op_sel_hi:[0,0,1] neg_lo:[0,0,0] neg_hi:[0,1,0]
	v_pk_fma_f32 v[94:95], v[114:115], v[106:107], v[94:95] op_sel:[0,0,0] op_sel_hi:[0,1,1] neg_lo:[0,0,1] neg_hi:[0,0,0]
	v_pk_fma_f32 v[96:97], v[116:117], v[106:107], v[96:97] op_sel:[0,1,0] op_sel_hi:[0,0,1] neg_lo:[0,0,0] neg_hi:[0,1,0]
	v_pk_add_f32 v[110:111], v[82:83], v[84:85] neg_lo:[0,1] neg_hi:[0,1]
	v_pk_add_f32 v[112:113], v[86:87], v[88:89] neg_lo:[0,1] neg_hi:[0,1]
	v_pk_add_f32 v[114:115], v[90:91], v[92:93] neg_lo:[0,1] neg_hi:[0,1]
	v_pk_add_f32 v[116:117], v[94:95], v[96:97] neg_lo:[0,1] neg_hi:[0,1]
	v_pk_add_f32 v[82:83], v[82:83], v[84:85]
	v_pk_add_f32 v[86:87], v[86:87], v[88:89]
	v_pk_add_f32 v[90:91], v[90:91], v[92:93]
	v_pk_add_f32 v[94:95], v[94:95], v[96:97]
	v_pk_mul_f32 v[84:85], v[110:111], v[108:109] op_sel:[1,1] op_sel_hi:[1,0]
	v_pk_mul_f32 v[88:89], v[112:113], v[108:109] op_sel:[1,1] op_sel_hi:[1,0]
	v_pk_mul_f32 v[92:93], v[114:115], v[108:109] op_sel:[1,1] op_sel_hi:[1,0]
	v_pk_mul_f32 v[96:97], v[116:117], v[108:109] op_sel:[1,1] op_sel_hi:[1,0]
	v_pk_fma_f32 v[84:85], v[110:111], v[108:109], v[84:85] op_sel:[0,0,0] op_sel_hi:[0,1,1] neg_lo:[0,0,1] neg_hi:[0,0,0]
	v_pk_fma_f32 v[88:89], v[112:113], v[108:109], v[88:89] op_sel:[0,0,0] op_sel_hi:[0,1,1] neg_lo:[0,0,1] neg_hi:[0,0,0]
	v_pk_fma_f32 v[92:93], v[114:115], v[108:109], v[92:93] op_sel:[0,0,0] op_sel_hi:[0,1,1] neg_lo:[0,0,1] neg_hi:[0,0,0]
	v_pk_fma_f32 v[96:97], v[116:117], v[108:109], v[96:97] op_sel:[0,0,0] op_sel_hi:[0,1,1] neg_lo:[0,0,1] neg_hi:[0,0,0]
	ds_write2_b64 v81, v[82:83], v[84:85] offset1:17
	ds_write2_b64 v81, v[86:87], v[88:89] offset0:34 offset1:51
	ds_write2_b64 v81, v[90:91], v[92:93] offset0:68 offset1:85
	ds_write2_b64 v81, v[94:95], v[96:97] offset0:102 offset1:119
	s_movk_i32 s0, 0x200
	s_and_b64 vcc, exec, s[10:11]
	s_mov_b64 s[10:11], 0
	s_cbranch_vccnz .LBB0_363
; __device__ __forceinline__ int otid() { int t = threadIdx.x; asm volatile("" : "+v"(t)); return t; }
; __device__ __forceinline__ cf twc(cf ws, int k16) { if (k16 == 0) return ws; if (k16 == 4) return cf{ws.y, -ws.x}; return cmul(ws, cf{c16(k16), -s16(k16)}); }
; template <int LR> __device__ __forceinline__ void dif_reg(cf (&x)[1 << LR], cf w) {
;     constexpr int R = 1 << LR; cf ws = w;
; #pragma unroll
;     for (int s = 0; s < LR; ++s) { const int half = R >> (s + 1);
; #pragma unroll
;         for (int m0 = 0; m0 < R; m0 += 2 * half)
; #pragma unroll
;             for (int mm = 0; mm < half; ++mm) { const int ia = m0 + mm, ib = ia + half; const cf a = x[ia], b = x[ib];
;                 x[ia] = cf{a.x + b.x, a.y + b.y}; const cf d{a.x - b.x, a.y - b.y};
;                 x[ib] = cmul(d, twc(ws, (mm << s) * (16 / R))); }
;         ws = cmul(ws, ws); }
; }
; __device__ __forceinline__ void fft_conv(ldsf2 buf, const LAS unsigned* spec) {
;     ...
;     { const int tid = otid(); cf x[16];
; #pragma unroll
;       for (int m = 0; m < 16; ++m) { const v2f v = buf[tid * 17 + m]; x[m] = cf{v.x, v.y}; }
;       dif_reg<4>(x, cf{1.0f, 0.0f});
	v_mov_b32_e32 v162, v195
	s_movk_i32 s0, 0x88
	s_waitcnt lgkmcnt(0)
	s_mov_b32 s86, s63
	v_mul_lo_u32 v78, v162, s0
	v_add_u32_e32 v151, 0, v78
	ds_read2_b64 v[80:83], v151 offset1:1
	ds_read2_b64 v[84:87], v151 offset0:2 offset1:3
	ds_read2_b64 v[98:101], v151 offset0:4 offset1:5
	ds_read2_b64 v[102:105], v151 offset0:6 offset1:7
	ds_read2_b64 v[106:109], v151 offset0:8 offset1:9
	ds_read2_b64 v[110:113], v151 offset0:10 offset1:11
	ds_read2_b64 v[126:129], v151 offset0:12 offset1:13
	ds_read2_b64 v[134:137], v151 offset0:14 offset1:15
	s_waitcnt lgkmcnt(7)
	v_mov_b32_e32 v79, v82
	s_waitcnt lgkmcnt(3)
	v_pk_add_f32 v[114:115], v[80:81], v[106:107] neg_lo:[0,1] neg_hi:[0,1]
	v_mov_b32_e32 v88, v106
	s_waitcnt lgkmcnt(1)
	v_pk_add_f32 v[140:141], v[98:99], v[126:127] neg_lo:[0,1] neg_hi:[0,1]
	v_sub_f32_e32 v78, v101, v129
	v_mul_f32_e32 v115, 0x3f6c835e, v78
	v_mul_f32_e32 v140, 0x3ec3ef15, v78
	v_mov_b32_e32 v78, v80
	v_mov_b32_e32 v89, v108
	v_pk_add_f32 v[90:91], v[78:79], v[88:89]
	v_mov_b32_e32 v152, v110
	v_mov_b32_e32 v153, v112
	v_mov_b32_e32 v78, v98
	v_mov_b32_e32 v79, v100
	v_mov_b32_e32 v88, v126
	v_mov_b32_e32 v89, v128
	v_mov_b32_e32 v112, v111
	v_mov_b32_e32 v110, v99
	v_mov_b32_e32 v111, v101
	v_mov_b32_e32 v120, v127
	v_mov_b32_e32 v121, v129
	v_pk_add_f32 v[130:131], v[82:83], v[108:109] neg_lo:[0,1] neg_hi:[0,1]
	v_mov_b32_e32 v142, v84
	v_mov_b32_e32 v143, v86
	v_pk_add_f32 v[94:95], v[78:79], v[88:89]
	v_mov_b32_e32 v78, v102
	v_mov_b32_e32 v79, v104
	s_waitcnt lgkmcnt(0)
	v_mov_b32_e32 v88, v134
	v_mov_b32_e32 v89, v136
	v_mov_b32_e32 v82, v81
	v_mov_b32_e32 v108, v107
	v_mov_b32_e32 v86, v85
	v_pk_add_f32 v[110:111], v[110:111], v[120:121]
	v_mov_b32_e32 v120, v103
	v_mov_b32_e32 v121, v105
	v_mov_b32_e32 v122, v135
	v_mov_b32_e32 v123, v137
	v_pk_add_f32 v[92:93], v[142:143], v[152:153]
	v_pk_add_f32 v[96:97], v[78:79], v[88:89]
	v_pk_add_f32 v[118:119], v[82:83], v[108:109]
	v_pk_add_f32 v[84:85], v[86:87], v[112:113]
	v_pk_add_f32 v[154:155], v[120:121], v[122:123]
	v_pk_add_f32 v[88:89], v[90:91], v[94:95]
	v_pk_add_f32 v[116:117], v[92:93], v[96:97]
	v_pk_add_f32 v[120:121], v[118:119], v[110:111]
	v_pk_add_f32 v[122:123], v[84:85], v[154:155]
	v_sub_f32_e32 v78, v91, v95
	v_pk_add_f32 v[132:133], v[120:121], v[122:123]
	v_mov_b32_e32 v124, v88
	v_mov_b32_e32 v125, v121
	v_mov_b32_e32 v160, v116
	v_mov_b32_e32 v161, v123
	v_mov_b32_e32 v121, v89
	v_mov_b32_e32 v123, v117
	v_mul_f32_e32 v138, 0x3f3504f3, v78
	v_pk_add_f32 v[78:79], v[88:89], v[116:117]
	v_pk_add_f32 v[124:125], v[124:125], v[160:161] neg_lo:[0,1] neg_hi:[0,1]
	v_pk_add_f32 v[116:117], v[120:121], v[122:123] neg_lo:[0,1] neg_hi:[0,1]
	v_mov_b32_e32 v91, v93
	v_mov_b32_e32 v95, v97
	v_pk_fma_f32 v[88:89], v[116:117], 0, v[124:125] op_sel_hi:[1,0,1] neg_lo:[1,0,0] neg_hi:[1,0,0]
	v_pk_fma_f32 v[120:121], v[116:117], 0, v[124:125] op_sel_hi:[1,0,1]
	v_pk_fma_f32 v[122:123], v[124:125], 0, v[116:117] op_sel_hi:[1,0,1]
	v_pk_fma_f32 v[124:125], v[124:125], 0, v[116:117] op_sel_hi:[1,0,1] neg_lo:[0,0,1] neg_hi:[0,0,1]
	v_mov_b32_e32 v116, v92
	v_mov_b32_e32 v117, v119
	v_mov_b32_e32 v160, v96
	v_mov_b32_e32 v161, v111
	v_mov_b32_e32 v119, v85
	v_mov_b32_e32 v111, v155
	v_pk_add_f32 v[90:91], v[90:91], v[94:95] neg_lo:[0,1] neg_hi:[0,1]
	v_pk_add_f32 v[156:157], v[84:85], v[154:155] neg_lo:[0,1] neg_hi:[0,1]
	v_pk_add_f32 v[116:117], v[116:117], v[160:161] neg_lo:[0,1] neg_hi:[0,1]
	s_mov_b32 s10, s63
	s_mov_b32 s11, s16
	v_pk_add_f32 v[84:85], v[118:119], v[110:111] neg_lo:[0,1] neg_hi:[0,1]
	v_pk_mul_f32 v[92:93], v[90:91], s[86:87]
	v_pk_mul_f32 v[160:161], v[116:117], s[10:11]
	v_pk_mul_f32 v[110:111], v[84:85], s[86:87]
	v_mov_b32_e32 v157, v138
	v_mov_b32_e32 v92, v90
	v_mul_f32_e32 v158, 0, v156
	v_pk_fma_f32 v[154:155], v[116:117], s[10:11], v[156:157]
	v_mov_b32_e32 v159, v161
	v_mov_b32_e32 v117, v138
	v_pk_fma_f32 v[92:93], v[84:85], s[86:87], v[92:93] neg_lo:[1,0,0] neg_hi:[1,0,0]
	v_mov_b32_e32 v85, v111
	v_pk_add_f32 v[94:95], v[158:159], v[116:117] neg_lo:[0,1] neg_hi:[0,1]
	v_pk_fma_f32 v[84:85], v[90:91], s[86:87], v[84:85]
	v_mov_b32_e32 v90, v92
	v_pk_add_f32 v[118:119], v[84:85], v[94:95]
	v_mov_b32_e32 v91, v95
	v_mov_b32_e32 v96, v154
	v_mov_b32_e32 v97, v85
	v_mov_b32_e32 v85, v155
	v_mov_b32_e32 v95, v93
	v_pk_add_f32 v[96:97], v[90:91], v[96:97] neg_lo:[0,1] neg_hi:[0,1]
	v_pk_add_f32 v[84:85], v[84:85], v[94:95] neg_lo:[0,1] neg_hi:[0,1]
	v_pk_add_f32 v[116:117], v[92:93], v[154:155]
	v_pk_fma_f32 v[90:91], v[84:85], 0, v[96:97] op_sel_hi:[1,0,1] neg_lo:[1,0,0] neg_hi:[1,0,0]
	v_pk_fma_f32 v[92:93], v[84:85], 0, v[96:97] op_sel_hi:[1,0,1]
	v_pk_fma_f32 v[94:95], v[96:97], 0, v[84:85] op_sel_hi:[1,0,1]
	v_pk_fma_f32 v[96:97], v[96:97], 0, v[84:85] op_sel_hi:[1,0,1] neg_lo:[0,0,1] neg_hi:[0,0,1]
	v_pk_mov_b32 v[80:81], v[80:81], v[100:101] op_sel:[1,0]
	v_pk_mov_b32 v[84:85], v[106:107], v[128:129] op_sel:[1,0]
	v_mov_b32_e32 v99, v83
	v_mov_b32_e32 v127, v109
	v_pk_add_f32 v[80:81], v[80:81], v[84:85] neg_lo:[0,1] neg_hi:[0,1]
	v_pk_add_f32 v[84:85], v[98:99], v[126:127] neg_lo:[0,1] neg_hi:[0,1]
	v_mul_f32_e32 v100, 0x3ec3ef15, v130
	v_pk_mov_b32 v[98:99], v[84:85], v[130:131] op_sel:[1,0]
	v_pk_add_f32 v[86:87], v[86:87], v[112:113] neg_lo:[0,1] neg_hi:[0,1]
	v_pk_fma_f32 v[98:99], v[98:99], s[4:5], v[100:101] op_sel_hi:[1,1,0] neg_lo:[0,0,1] neg_hi:[0,0,1]
	v_pk_add_f32 v[100:101], v[142:143], v[152:153] neg_lo:[0,1] neg_hi:[0,1]
	s_mov_b32 s17, s5
	s_mov_b32 s0, s16
	s_mov_b32 s1, s4
	v_pk_mul_f32 v[106:107], v[100:101], s[16:17]
	v_pk_mul_f32 v[108:109], v[86:87], s[0:1]
	s_mov_b32 s0, s63
	s_mov_b32 s1, s5
; __device__ __forceinline__ cf twc(cf ws, int k16) { if (k16 == 0) return ws; if (k16 == 4) return cf{ws.y, -ws.x}; return cmul(ws, cf{c16(k16), -s16(k16)}); }
; template <int LR> __device__ __forceinline__ void dif_reg(cf (&x)[1 << LR], cf w) {
;     constexpr int R = 1 << LR; cf ws = w;
; #pragma unroll
;     for (int s = 0; s < LR; ++s) { const int half = R >> (s + 1);
; #pragma unroll
;         for (int m0 = 0; m0 < R; m0 += 2 * half)
; #pragma unroll
;             for (int mm = 0; mm < half; ++mm) { const int ia = m0 + mm, ib = ia + half; const cf a = x[ia], b = x[ib];
;                 x[ia] = cf{a.x + b.x, a.y + b.y}; const cf d{a.x - b.x, a.y - b.y};
;                 x[ib] = cmul(d, twc(ws, (mm << s) * (16 / R))); }
;         ws = cmul(ws, ws); }
; }
; __device__ __forceinline__ void fft_conv(ldsf2 buf, const LAS unsigned* spec) {
;     ...
;       dif_reg<4>(x, cf{1.0f, 0.0f});
; #pragma unroll
;       for (int m = 0; m < 16; ++m) { const h2_t hv = __builtin_bit_cast(h2_t, spec[tid * 17 + m]); x[m] = cmul(x[m], cf{(float)hv.x, (float)hv.y}); }
	v_mul_f32_e32 v139, 0x3f6c835e, v130
	v_fma_f32 v82, 0, v114, v80
	v_pk_fma_f32 v[112:113], v[100:101], s[16:17], v[108:109]
	v_mul_f32_e32 v107, 0x3f6c835e, v101
	v_mov_b32_e32 v138, v141
	v_pk_fma_f32 v[100:101], v[80:81], s[0:1], v[114:115] neg_lo:[1,0,0] neg_hi:[1,0,0]
	v_pk_mov_b32 v[110:111], v[102:103], v[104:105] op_sel:[1,0]
	v_pk_mov_b32 v[114:115], v[134:135], v[136:137] op_sel:[1,0]
	v_mul_f32_e32 v109, 0x3ec3ef15, v87
	v_pk_fma_f32 v[86:87], v[84:85], s[0:1], v[138:139]
	v_pk_add_f32 v[110:111], v[110:111], v[114:115] neg_lo:[0,1] neg_hi:[0,1]
	v_mov_b32_e32 v103, v105
	v_mov_b32_e32 v135, v137
	s_mov_b32 s0, s87
	s_mov_b32 s1, s4
	v_pk_add_f32 v[102:103], v[102:103], v[134:135] neg_lo:[0,1] neg_hi:[0,1]
	v_pk_mul_f32 v[104:105], v[110:111], s[0:1]
	s_mov_b32 s1, s5
	v_pk_fma_f32 v[114:115], v[102:103], s[0:1], v[104:105]
	v_pk_fma_f32 v[128:129], v[102:103], s[0:1], v[104:105] neg_lo:[0,0,1] neg_hi:[0,0,1]
	v_mov_b32_e32 v102, v111
	s_mov_b32 s35, s4
	v_mul_f32_e32 v80, 0x3f6c835e, v103
	v_pk_fma_f32 v[130:131], v[102:103], s[34:35], v[80:81] op_sel_hi:[1,1,0] neg_lo:[0,0,1] neg_hi:[0,0,1]
	v_mov_b32_e32 v80, v141
	s_mov_b32 s12, s63
	v_mov_b32_e32 v85, v140
	v_pk_add_f32 v[136:137], v[108:109], v[106:107] neg_lo:[0,1] neg_hi:[0,1]
	v_pk_fma_f32 v[80:81], v[80:81], s[12:13], v[84:85] neg_lo:[0,0,1] neg_hi:[0,0,1]
	v_mov_b32_e32 v83, v98
	v_mov_b32_e32 v115, v130
	v_pk_add_f32 v[102:103], v[100:101], v[86:87]
	v_pk_add_f32 v[104:105], v[112:113], v[128:129]
	v_pk_add_f32 v[84:85], v[82:83], v[80:81]
	v_pk_add_f32 v[106:107], v[136:137], v[114:115]
	v_mov_b32_e32 v108, v102
	v_pk_add_f32 v[126:127], v[84:85], v[106:107]
	v_mov_b32_e32 v109, v85
	v_mov_b32_e32 v138, v104
	v_mov_b32_e32 v139, v107
	v_mov_b32_e32 v85, v103
	v_mov_b32_e32 v107, v105
	v_pk_add_f32 v[108:109], v[108:109], v[138:139] neg_lo:[0,1] neg_hi:[0,1]
	v_pk_add_f32 v[84:85], v[84:85], v[106:107] neg_lo:[0,1] neg_hi:[0,1]
	v_pk_add_f32 v[134:135], v[86:87], v[100:101] neg_lo:[0,1] neg_hi:[0,1]
	v_pk_add_f32 v[110:111], v[102:103], v[104:105]
	v_pk_fma_f32 v[102:103], v[84:85], 0, v[108:109] op_sel_hi:[1,0,1] neg_lo:[1,0,0] neg_hi:[1,0,0]
	v_pk_fma_f32 v[104:105], v[84:85], 0, v[108:109] op_sel_hi:[1,0,1]
	v_pk_fma_f32 v[106:107], v[108:109], 0, v[84:85] op_sel_hi:[1,0,1]
	v_pk_fma_f32 v[108:109], v[108:109], 0, v[84:85] op_sel_hi:[1,0,1] neg_lo:[0,0,1] neg_hi:[0,0,1]
	v_mov_b32_e32 v83, v137
	v_mov_b32_e32 v84, v80
	v_mov_b32_e32 v85, v130
	v_pk_add_f32 v[82:83], v[82:83], v[84:85] neg_lo:[0,1] neg_hi:[0,1]
	v_mov_b32_e32 v84, v112
	v_mov_b32_e32 v85, v98
	v_mov_b32_e32 v80, v128
	v_mov_b32_e32 v137, v245
	v_mov_b32_e32 v115, v135
	v_mov_b32_e32 v101, v113
	v_mov_b32_e32 v87, v129
	v_pk_add_f32 v[80:81], v[84:85], v[80:81] neg_lo:[0,1] neg_hi:[0,1]
	v_pk_add_f32 v[98:99], v[136:137], v[114:115] neg_lo:[0,1] neg_hi:[0,1]
	v_pk_mul_f32 v[114:115], v[136:137], v[114:115]
	v_pk_add_f32 v[86:87], v[100:101], v[86:87] neg_lo:[0,1] neg_hi:[0,1]
	v_pk_mul_f32 v[84:85], v[80:81], s[10:11]
	v_mov_b32_e32 v99, v115
	v_pk_mul_f32 v[100:101], v[86:87], s[86:87]
	v_pk_fma_f32 v[130:131], v[80:81], s[10:11], v[98:99]
	v_mul_f32_e32 v84, 0, v98
	v_pk_mul_f32 v[98:99], v[82:83], s[86:87]
	v_mov_b32_e32 v81, v115
	v_mov_b32_e32 v100, v86
	v_pk_add_f32 v[80:81], v[84:85], v[80:81] neg_lo:[0,1] neg_hi:[0,1]
	v_pk_fma_f32 v[84:85], v[82:83], s[86:87], v[100:101] neg_lo:[1,0,0] neg_hi:[1,0,0]
	v_mov_b32_e32 v83, v99
	v_pk_fma_f32 v[82:83], v[86:87], s[86:87], v[82:83]
	v_mov_b32_e32 v86, v84
	v_pk_add_f32 v[100:101], v[82:83], v[80:81]
	v_mov_b32_e32 v87, v81
	v_mov_b32_e32 v112, v130
	v_mov_b32_e32 v113, v83
	v_mov_b32_e32 v83, v131
	v_mov_b32_e32 v81, v85
	v_pk_add_f32 v[86:87], v[86:87], v[112:113] neg_lo:[0,1] neg_hi:[0,1]
	v_pk_add_f32 v[112:113], v[82:83], v[80:81] neg_lo:[0,1] neg_hi:[0,1]
	v_pk_add_f32 v[98:99], v[84:85], v[130:131]
	v_pk_fma_f32 v[80:81], v[112:113], 0, v[86:87] op_sel_hi:[1,0,1] neg_lo:[1,0,0] neg_hi:[1,0,0]
	v_pk_fma_f32 v[82:83], v[112:113], 0, v[86:87] op_sel_hi:[1,0,1]
	v_pk_fma_f32 v[84:85], v[86:87], 0, v[112:113] op_sel_hi:[1,0,1]
	v_pk_fma_f32 v[86:87], v[86:87], 0, v[112:113] op_sel_hi:[1,0,1] neg_lo:[0,0,1] neg_hi:[0,0,1]
	v_mov_b32_e32 v112, v78
	v_mov_b32_e32 v113, v132
	v_mov_b32_e32 v114, v79
	v_mov_b32_e32 v115, v133
	v_pk_add_f32 v[136:137], v[112:113], v[114:115] neg_lo:[0,1] neg_hi:[0,1]
	v_mov_b32_e32 v112, v88
	v_mov_b32_e32 v113, v122
	v_mov_b32_e32 v114, v121
	v_mov_b32_e32 v115, v125
	v_pk_add_f32 v[154:155], v[112:113], v[114:115] neg_lo:[0,1] neg_hi:[0,1]
	v_mov_b32_e32 v112, v116
	v_mov_b32_e32 v113, v118
	v_mov_b32_e32 v114, v117
	v_mov_b32_e32 v115, v119
	v_pk_add_f32 v[158:159], v[112:113], v[114:115] neg_lo:[0,1] neg_hi:[0,1]
	v_mov_b32_e32 v112, v90
	v_mov_b32_e32 v113, v94
	v_mov_b32_e32 v114, v93
	v_mov_b32_e32 v115, v97
	v_pk_add_f32 v[140:141], v[112:113], v[114:115] neg_lo:[0,1] neg_hi:[0,1]
	v_mov_b32_e32 v112, v110
	v_mov_b32_e32 v113, v126
	v_mov_b32_e32 v114, v111
	v_mov_b32_e32 v115, v127
	v_pk_add_f32 v[134:135], v[112:113], v[114:115] neg_lo:[0,1] neg_hi:[0,1]
	v_mov_b32_e32 v112, v102
	v_mov_b32_e32 v113, v106
	v_mov_b32_e32 v114, v105
	v_mov_b32_e32 v115, v109
	v_pk_add_f32 v[130:131], v[112:113], v[114:115] neg_lo:[0,1] neg_hi:[0,1]
	v_mov_b32_e32 v112, v98
	v_mov_b32_e32 v113, v100
	v_mov_b32_e32 v114, v99
	v_mov_b32_e32 v115, v101
	v_pk_add_f32 v[112:113], v[112:113], v[114:115] neg_lo:[0,1] neg_hi:[0,1]
	v_mov_b32_e32 v114, v80
	v_mov_b32_e32 v115, v84
	v_mov_b32_e32 v128, v83
	v_mov_b32_e32 v129, v87
	v_pk_add_f32 v[114:115], v[114:115], v[128:129] neg_lo:[0,1] neg_hi:[0,1]
	s_movk_i32 s0, 0x44
	v_fmamk_f32 v144, v141, 0x80000000, v140
	v_fmac_f32_e32 v141, 0, v140
	v_fmamk_f32 v140, v135, 0x80000000, v134
	v_fmac_f32_e32 v135, 0, v134
	v_fmamk_f32 v134, v131, 0x80000000, v130
	v_fmac_f32_e32 v131, 0, v130
	v_fmamk_f32 v130, v113, 0x80000000, v112
	v_fmac_f32_e32 v113, 0, v112
	v_fmamk_f32 v112, v115, 0x80000000, v114
	v_fmac_f32_e32 v115, 0, v114
	v_mul_lo_u32 v114, v162, s0
	v_add_u32_e32 v114, 0, v114
	v_add_u32_e32 v114, 0x19800, v114
	ds_read2_b32 v[160:161], v114 offset1:1
	ds_read2_b32 v[162:163], v114 offset0:2 offset1:3
	ds_read2_b32 v[164:165], v114 offset0:4 offset1:5
	ds_read2_b32 v[166:167], v114 offset0:6 offset1:7
	ds_read2_b32 v[168:169], v114 offset0:8 offset1:9
	ds_read2_b32 v[142:143], v114 offset0:10 offset1:11
	ds_read2_b32 v[138:139], v114 offset0:12 offset1:13
	ds_read2_b32 v[128:129], v114 offset0:14 offset1:15
	s_waitcnt lgkmcnt(7)
; __device__ __forceinline__ void fft_conv(ldsf2 buf, const LAS unsigned* spec) {
;     ...
; #pragma unroll
;       for (int m = 0; m < 16; ++m) { const h2_t hv = __builtin_bit_cast(h2_t, spec[tid * 17 + m]); x[m] = cmul(x[m], cf{(float)hv.x, (float)hv.y}); }
;       dit_reg<4>(x, cf{1.0f, 0.0f});
	v_cvt_f32_f16_e32 v170, v160
	v_cvt_f32_f16_sdwa v171, v160 dst_sel:DWORD dst_unused:UNUSED_PAD src0_sel:WORD_1
	v_cvt_f32_f16_e32 v160, v161
	v_cvt_f32_f16_sdwa v161, v161 dst_sel:DWORD dst_unused:UNUSED_PAD src0_sel:WORD_1
	v_fmamk_f32 v152, v137, 0x80000000, v136
	v_fmac_f32_e32 v137, 0, v136
	v_pk_add_f32 v[172:173], v[78:79], v[78:79] op_sel:[0,1] op_sel_hi:[0,1]
	v_pk_add_f32 v[78:79], v[132:133], v[132:133] op_sel:[0,1] op_sel_hi:[0,1]
	v_pk_mul_f32 v[132:133], v[78:79], v[170:171] op_sel:[0,1] op_sel_hi:[1,0]
	v_mov_b32_e32 v114, v137
	v_pk_fma_f32 v[78:79], v[172:173], v[170:171], v[132:133] neg_lo:[0,0,1] neg_hi:[0,0,1]
	v_pk_fma_f32 v[132:133], v[172:173], v[170:171], v[132:133]
	v_pk_mul_f32 v[136:137], v[114:115], v[160:161] op_sel:[0,1] op_sel_hi:[0,0]
	v_mov_b32_e32 v79, v133
	v_pk_fma_f32 v[132:133], v[152:153], v[160:161], v[136:137] op_sel_hi:[0,1,1] neg_lo:[0,0,1] neg_hi:[0,0,1]
	v_pk_fma_f32 v[136:137], v[152:153], v[160:161], v[136:137] op_sel_hi:[0,1,1]
	s_waitcnt lgkmcnt(6)
	v_cvt_f32_f16_e32 v152, v162
	v_cvt_f32_f16_sdwa v153, v162 dst_sel:DWORD dst_unused:UNUSED_PAD src0_sel:WORD_1
	v_pk_add_f32 v[120:121], v[88:89], v[120:121] op_sel:[0,1] op_sel_hi:[0,1]
	v_pk_add_f32 v[88:89], v[122:123], v[124:125] op_sel:[0,1] op_sel_hi:[0,1]
	v_fmamk_f32 v156, v155, 0x80000000, v154
	v_pk_mul_f32 v[122:123], v[88:89], v[152:153] op_sel:[0,1] op_sel_hi:[1,0]
	v_fmac_f32_e32 v155, 0, v154
	v_pk_fma_f32 v[88:89], v[120:121], v[152:153], v[122:123] neg_lo:[0,0,1] neg_hi:[0,0,1]
	v_pk_fma_f32 v[120:121], v[120:121], v[152:153], v[122:123]
	v_cvt_f32_f16_e32 v122, v163
	v_cvt_f32_f16_sdwa v123, v163 dst_sel:DWORD dst_unused:UNUSED_PAD src0_sel:WORD_1
	v_mov_b32_e32 v114, v155
	v_mov_b32_e32 v89, v121
	v_pk_add_f32 v[152:153], v[116:117], v[116:117] op_sel:[0,1] op_sel_hi:[0,1]
	v_pk_mul_f32 v[124:125], v[114:115], v[122:123] op_sel:[0,1] op_sel_hi:[0,0]
	v_pk_fma_f32 v[120:121], v[156:157], v[122:123], v[124:125] op_sel_hi:[0,1,1] neg_lo:[0,0,1] neg_hi:[0,0,1]
	v_pk_fma_f32 v[122:123], v[156:157], v[122:123], v[124:125] op_sel_hi:[0,1,1]
	s_waitcnt lgkmcnt(5)
	v_cvt_f32_f16_e32 v124, v164
	v_cvt_f32_f16_sdwa v125, v164 dst_sel:DWORD dst_unused:UNUSED_PAD src0_sel:WORD_1
	v_pk_add_f32 v[116:117], v[118:119], v[118:119] op_sel:[0,1] op_sel_hi:[0,1]
	v_fmamk_f32 v154, v159, 0x80000000, v158
	v_fmac_f32_e32 v159, 0, v158
	v_pk_mul_f32 v[118:119], v[116:117], v[124:125] op_sel:[0,1] op_sel_hi:[1,0]
	v_mov_b32_e32 v114, v159
	v_pk_fma_f32 v[116:117], v[152:153], v[124:125], v[118:119] neg_lo:[0,0,1] neg_hi:[0,0,1]
	v_pk_fma_f32 v[118:119], v[152:153], v[124:125], v[118:119]
	v_cvt_f32_f16_e32 v124, v165
	v_cvt_f32_f16_sdwa v125, v165 dst_sel:DWORD dst_unused:UNUSED_PAD src0_sel:WORD_1
	v_pk_add_f32 v[90:91], v[90:91], v[92:93] op_sel:[0,1] op_sel_hi:[0,1]
	v_pk_add_f32 v[92:93], v[94:95], v[96:97] op_sel:[0,1] op_sel_hi:[0,1]
	v_pk_add_f32 v[110:111], v[110:111], v[110:111] op_sel:[0,1] op_sel_hi:[0,1]
	v_pk_mul_f32 v[152:153], v[114:115], v[124:125] op_sel:[0,1] op_sel_hi:[0,0]
	v_pk_fma_f32 v[156:157], v[154:155], v[124:125], v[152:153] op_sel_hi:[0,1,1] neg_lo:[0,0,1] neg_hi:[0,0,1]
	v_pk_fma_f32 v[124:125], v[154:155], v[124:125], v[152:153] op_sel_hi:[0,1,1]
	s_waitcnt lgkmcnt(4)
	v_cvt_f32_f16_e32 v154, v166
	v_cvt_f32_f16_sdwa v155, v166 dst_sel:DWORD dst_unused:UNUSED_PAD src0_sel:WORD_1
	v_pk_add_f32 v[102:103], v[102:103], v[104:105] op_sel:[0,1] op_sel_hi:[0,1]
	v_pk_add_f32 v[100:101], v[100:101], v[100:101] op_sel:[0,1] op_sel_hi:[0,1]
	v_pk_add_f32 v[98:99], v[98:99], v[98:99] op_sel:[0,1] op_sel_hi:[0,1]
	v_pk_mul_f32 v[92:93], v[92:93], v[154:155] op_sel:[0,1] op_sel_hi:[1,0]
	v_pk_add_f32 v[80:81], v[80:81], v[82:83] op_sel:[0,1] op_sel_hi:[0,1]
	v_pk_fma_f32 v[94:95], v[90:91], v[154:155], v[92:93] neg_lo:[0,0,1] neg_hi:[0,0,1]
	v_pk_fma_f32 v[90:91], v[90:91], v[154:155], v[92:93]
	v_mov_b32_e32 v92, v141
	v_mov_b32_e32 v95, v91
	v_cvt_f32_f16_e32 v90, v167
	v_cvt_f32_f16_sdwa v91, v167 dst_sel:DWORD dst_unused:UNUSED_PAD src0_sel:WORD_1
	v_pk_add_f32 v[82:83], v[84:85], v[86:87] op_sel:[0,1] op_sel_hi:[0,1]
	v_mov_b32_e32 v152, v156
	v_mov_b32_e32 v153, v125
	v_pk_mul_f32 v[92:93], v[92:93], v[90:91] op_sel:[0,1] op_sel_hi:[0,0]
	v_pk_fma_f32 v[96:97], v[144:145], v[90:91], v[92:93] op_sel_hi:[0,1,1] neg_lo:[0,0,1] neg_hi:[0,0,1]
	v_pk_fma_f32 v[154:155], v[144:145], v[90:91], v[92:93] op_sel_hi:[0,1,1]
	s_waitcnt lgkmcnt(3)
	v_cvt_f32_f16_e32 v92, v168
	v_cvt_f32_f16_sdwa v93, v168 dst_sel:DWORD dst_unused:UNUSED_PAD src0_sel:WORD_1
	v_pk_add_f32 v[90:91], v[126:127], v[126:127] op_sel:[0,1] op_sel_hi:[0,1]
	v_mov_b32_e32 v117, v119
	s_mov_b32 s0, s5
	v_pk_mul_f32 v[126:127], v[90:91], v[92:93] op_sel:[0,1] op_sel_hi:[1,0]
	s_mov_b64 s[14:15], -1
	v_pk_fma_f32 v[90:91], v[110:111], v[92:93], v[126:127] neg_lo:[0,0,1] neg_hi:[0,0,1]
	v_pk_fma_f32 v[92:93], v[110:111], v[92:93], v[126:127]
	v_mov_b32_e32 v110, v135
	v_mov_b32_e32 v91, v93
	v_cvt_f32_f16_e32 v92, v169
	v_cvt_f32_f16_sdwa v93, v169 dst_sel:DWORD dst_unused:UNUSED_PAD src0_sel:WORD_1
	v_pk_mul_f32 v[110:111], v[110:111], v[92:93] op_sel:[0,1] op_sel_hi:[0,0]
	v_pk_fma_f32 v[126:127], v[140:141], v[92:93], v[110:111] op_sel_hi:[0,1,1] neg_lo:[0,0,1] neg_hi:[0,0,1]
	v_pk_fma_f32 v[110:111], v[140:141], v[92:93], v[110:111] op_sel_hi:[0,1,1]
	s_waitcnt lgkmcnt(2)
; __device__ __forceinline__ cf twc(cf ws, int k16) { if (k16 == 0) return ws; if (k16 == 4) return cf{ws.y, -ws.x}; return cmul(ws, cf{c16(k16), -s16(k16)}); }
; template <int LR> __device__ __forceinline__ void dit_reg(cf (&x)[1 << LR], cf w) {
;     constexpr int R = 1 << LR; cf wsv[LR]; wsv[0] = w;
; #pragma unroll
;     for (int s = 1; s < LR; ++s) wsv[s] = cmul(wsv[s - 1], wsv[s - 1]);
; #pragma unroll
;     for (int s = LR - 1; s >= 0; --s) { const int half = R >> (s + 1);
; #pragma unroll
;         for (int m0 = 0; m0 < R; m0 += 2 * half)
; #pragma unroll
;             for (int mm = 0; mm < half; ++mm) { const int ia = m0 + mm, ib = ia + half; const cf a = x[ia];
;                 const cf b = cmulc(x[ib], twc(wsv[s], (mm << s) * (16 / R)));
;                 x[ia] = cf{a.x + b.x, a.y + b.y}; x[ib] = cf{a.x - b.x, a.y - b.y}; } }
; __device__ __forceinline__ void fft_conv(ldsf2 buf, const LAS unsigned* spec) {
;     ...
;       for (int m = 0; m < 16; ++m) { const h2_t hv = __builtin_bit_cast(h2_t, spec[tid * 17 + m]); x[m] = cmul(x[m], cf{(float)hv.x, (float)hv.y}); }
;       dit_reg<4>(x, cf{1.0f, 0.0f});
	v_cvt_f32_f16_e32 v140, v142
	v_cvt_f32_f16_sdwa v141, v142 dst_sel:DWORD dst_unused:UNUSED_PAD src0_sel:WORD_1
	v_pk_add_f32 v[92:93], v[106:107], v[108:109] op_sel:[0,1] op_sel_hi:[0,1]
	v_pk_mul_f32 v[104:105], v[92:93], v[140:141] op_sel:[0,1] op_sel_hi:[1,0]
	s_nop 0
	v_pk_fma_f32 v[92:93], v[102:103], v[140:141], v[104:105] neg_lo:[0,0,1] neg_hi:[0,0,1]
	v_pk_fma_f32 v[102:103], v[102:103], v[140:141], v[104:105]
	v_mov_b32_e32 v104, v131
	v_mov_b32_e32 v93, v103
	v_cvt_f32_f16_e32 v102, v143
	v_cvt_f32_f16_sdwa v103, v143 dst_sel:DWORD dst_unused:UNUSED_PAD src0_sel:WORD_1
	v_pk_mul_f32 v[104:105], v[104:105], v[102:103] op_sel:[0,1] op_sel_hi:[0,0]
	v_pk_fma_f32 v[106:107], v[134:135], v[102:103], v[104:105] op_sel_hi:[0,1,1] neg_lo:[0,0,1] neg_hi:[0,0,1]
	v_pk_fma_f32 v[102:103], v[134:135], v[102:103], v[104:105] op_sel_hi:[0,1,1]
	s_waitcnt lgkmcnt(1)
	v_cvt_f32_f16_e32 v104, v138
	v_cvt_f32_f16_sdwa v105, v138 dst_sel:DWORD dst_unused:UNUSED_PAD src0_sel:WORD_1
	v_pk_mul_f32 v[100:101], v[100:101], v[104:105] op_sel:[0,1] op_sel_hi:[1,0]
	s_nop 0
	v_pk_fma_f32 v[108:109], v[98:99], v[104:105], v[100:101] neg_lo:[0,0,1] neg_hi:[0,0,1]
	v_pk_fma_f32 v[98:99], v[98:99], v[104:105], v[100:101]
	v_cvt_f32_f16_e32 v100, v139
	v_cvt_f32_f16_sdwa v101, v139 dst_sel:DWORD dst_unused:UNUSED_PAD src0_sel:WORD_1
	v_mov_b32_e32 v98, v113
	v_mov_b32_e32 v109, v99
	v_pk_mul_f32 v[104:105], v[98:99], v[100:101] op_sel:[0,1] op_sel_hi:[0,0]
	v_pk_fma_f32 v[134:135], v[130:131], v[100:101], v[104:105] op_sel_hi:[0,1,1] neg_lo:[0,0,1] neg_hi:[0,0,1]
	v_pk_fma_f32 v[100:101], v[130:131], v[100:101], v[104:105] op_sel_hi:[0,1,1]
	s_waitcnt lgkmcnt(0)
	v_cvt_f32_f16_e32 v130, v128
	v_cvt_f32_f16_sdwa v131, v128 dst_sel:DWORD dst_unused:UNUSED_PAD src0_sel:WORD_1
	v_mov_b32_e32 v105, v101
	v_mov_b32_e32 v104, v134
	v_pk_mul_f32 v[82:83], v[82:83], v[130:131] op_sel:[0,1] op_sel_hi:[1,0]
	s_nop 0
	v_pk_fma_f32 v[84:85], v[80:81], v[130:131], v[82:83] neg_lo:[0,0,1] neg_hi:[0,0,1]
	v_pk_fma_f32 v[80:81], v[80:81], v[130:131], v[82:83]
	v_mov_b32_e32 v82, v115
	v_pk_mov_b32 v[114:115], v[122:123], v[120:121] op_sel:[1,0]
	v_mov_b32_e32 v85, v81
	v_pk_fma_f32 v[120:121], v[114:115], 0, v[120:121] op_sel_hi:[1,0,1]
	v_pk_fma_f32 v[114:115], v[114:115], 0, v[122:123] op_sel_hi:[1,0,1] neg_lo:[1,0,0] neg_hi:[1,0,0]
	v_pk_mov_b32 v[122:123], v[124:125], v[156:157] op_sel:[1,0]
	v_cvt_f32_f16_e32 v80, v129
	v_cvt_f32_f16_sdwa v81, v129 dst_sel:DWORD dst_unused:UNUSED_PAD src0_sel:WORD_1
	v_pk_fma_f32 v[128:129], v[122:123], 0, v[152:153] op_sel_hi:[1,0,1]
	v_pk_fma_f32 v[122:123], v[122:123], 0, v[124:125] op_sel_hi:[1,0,1] neg_lo:[1,0,0] neg_hi:[1,0,0]
	v_mov_b32_e32 v121, v115
	v_sub_f32_e32 v130, v119, v123
	v_pk_mov_b32 v[118:119], v[154:155], v[96:97] op_sel:[1,0]
	v_mov_b32_e32 v129, v123
	v_pk_fma_f32 v[96:97], v[118:119], 0, v[96:97] op_sel_hi:[1,0,1]
	v_pk_fma_f32 v[118:119], v[118:119], 0, v[154:155] op_sel_hi:[1,0,1] neg_lo:[1,0,0] neg_hi:[1,0,0]
	v_pk_mul_f32 v[82:83], v[82:83], v[80:81] op_sel:[0,1] op_sel_hi:[0,0]
	v_mov_b32_e32 v97, v119
	v_pk_add_f32 v[118:119], v[94:95], v[96:97]
	v_pk_add_f32 v[94:95], v[94:95], v[96:97] neg_lo:[0,1] neg_hi:[0,1]
	v_pk_mov_b32 v[96:97], v[110:111], v[126:127] op_sel:[1,0]
	v_pk_fma_f32 v[86:87], v[112:113], v[80:81], v[82:83] op_sel_hi:[0,1,1] neg_lo:[0,0,1] neg_hi:[0,0,1]
	v_pk_fma_f32 v[122:123], v[96:97], 0, v[126:127] op_sel_hi:[1,0,1]
	v_pk_fma_f32 v[96:97], v[96:97], 0, v[110:111] op_sel_hi:[1,0,1] neg_lo:[1,0,0] neg_hi:[1,0,0]
	v_pk_mov_b32 v[110:111], v[102:103], v[106:107] op_sel:[1,0]
	v_pk_fma_f32 v[80:81], v[112:113], v[80:81], v[82:83] op_sel_hi:[0,1,1]
	v_pk_fma_f32 v[106:107], v[110:111], 0, v[106:107] op_sel_hi:[1,0,1]
	v_pk_fma_f32 v[102:103], v[110:111], 0, v[102:103] op_sel_hi:[1,0,1] neg_lo:[1,0,0] neg_hi:[1,0,0]
	v_pk_mov_b32 v[110:111], v[100:101], v[134:135] op_sel:[1,0]
	v_mov_b32_e32 v107, v103
	v_pk_fma_f32 v[100:101], v[110:111], 0, v[100:101] op_sel_hi:[1,0,1] neg_lo:[1,0,0] neg_hi:[1,0,0]
	v_pk_add_f32 v[124:125], v[116:117], v[128:129]
	v_sub_f32_e32 v126, v99, v101
	v_pk_mov_b32 v[98:99], v[80:81], v[86:87] op_sel:[1,0]
	v_pk_add_f32 v[102:103], v[92:93], v[106:107]
	v_pk_fma_f32 v[86:87], v[98:99], 0, v[86:87] op_sel_hi:[1,0,1]
	v_pk_fma_f32 v[80:81], v[98:99], 0, v[80:81] op_sel_hi:[1,0,1] neg_lo:[1,0,0] neg_hi:[1,0,0]
	v_mul_f32_e32 v117, 0, v94
	v_mov_b32_e32 v129, v95
	v_fmac_f32_e32 v94, 0, v95
	v_mov_b32_e32 v123, v97
	v_mov_b32_e32 v87, v81
	v_pk_add_f32 v[116:117], v[116:117], v[128:129] neg_lo:[0,1] neg_hi:[0,1]
	v_add_f32_e32 v128, v130, v94
	v_sub_f32_e32 v130, v130, v94
	v_pk_mul_f32 v[94:95], v[102:103], 0 op_sel_hi:[1,0]
	v_pk_add_f32 v[114:115], v[88:89], v[120:121]
	v_pk_add_f32 v[96:97], v[90:91], v[122:123]
	v_pk_fma_f32 v[104:105], v[110:111], 0, v[104:105] op_sel_hi:[1,0,1]
	v_pk_add_f32 v[80:81], v[84:85], v[86:87]
	v_add_f32_e32 v127, v116, v117
	v_sub_f32_e32 v129, v116, v117
	v_pk_add_f32 v[116:117], v[102:103], v[94:95] op_sel:[0,1] op_sel_hi:[1,0]
	v_pk_add_f32 v[94:95], v[102:103], v[94:95] op_sel:[0,1] op_sel_hi:[1,0] neg_lo:[0,1] neg_hi:[0,1]
	v_mov_b32_e32 v105, v101
	v_pk_add_f32 v[84:85], v[84:85], v[86:87] neg_lo:[0,1] neg_hi:[0,1]
	v_pk_mul_f32 v[86:87], v[114:115], 0 op_sel_hi:[1,0]
	v_pk_mul_f32 v[100:101], v[118:119], 0 op_sel_hi:[1,0]
	v_mov_b32_e32 v117, v95
	v_sub_f32_e32 v131, v97, v95
	v_pk_mul_f32 v[94:95], v[80:81], 0 op_sel_hi:[1,0]
	v_pk_add_f32 v[98:99], v[114:115], v[86:87] op_sel:[0,1] op_sel_hi:[1,0]
	v_pk_add_f32 v[86:87], v[114:115], v[86:87] op_sel:[0,1] op_sel_hi:[1,0] neg_lo:[0,1] neg_hi:[0,1]
; __device__ __forceinline__ cf twc(cf ws, int k16) { if (k16 == 0) return ws; if (k16 == 4) return cf{ws.y, -ws.x}; return cmul(ws, cf{c16(k16), -s16(k16)}); }
; template <int LR> __device__ __forceinline__ void dit_reg(cf (&x)[1 << LR], cf w) {
;     constexpr int R = 1 << LR; cf wsv[LR]; wsv[0] = w;
; #pragma unroll
;     for (int s = 1; s < LR; ++s) wsv[s] = cmul(wsv[s - 1], wsv[s - 1]);
; #pragma unroll
;     for (int s = LR - 1; s >= 0; --s) { const int half = R >> (s + 1);
; #pragma unroll
;         for (int m0 = 0; m0 < R; m0 += 2 * half)
; #pragma unroll
;             for (int mm = 0; mm < half; ++mm) { const int ia = m0 + mm, ib = ia + half; const cf a = x[ia];
;                 const cf b = cmulc(x[ib], twc(wsv[s], (mm << s) * (16 / R)));
;                 x[ia] = cf{a.x + b.x, a.y + b.y}; x[ib] = cf{a.x - b.x, a.y - b.y}; } }
; __device__ __forceinline__ void fft_conv(ldsf2 buf, const LAS unsigned* spec) {
;     ...
;       dit_reg<4>(x, cf{1.0f, 0.0f});
	v_pk_add_f32 v[114:115], v[118:119], v[100:101] op_sel:[0,1] op_sel_hi:[1,0]
	v_pk_add_f32 v[100:101], v[118:119], v[100:101] op_sel:[0,1] op_sel_hi:[1,0] neg_lo:[0,1] neg_hi:[0,1]
	v_pk_add_f32 v[118:119], v[80:81], v[94:95] op_sel:[0,1] op_sel_hi:[1,0]
	v_pk_add_f32 v[80:81], v[80:81], v[94:95] op_sel:[0,1] op_sel_hi:[1,0] neg_lo:[0,1] neg_hi:[0,1]
	v_pk_add_f32 v[110:111], v[108:109], v[104:105]
	v_mov_b32_e32 v119, v81
	v_pk_add_f32 v[80:81], v[110:111], v[118:119]
	v_mul_f32_e32 v109, 0, v84
	v_mov_b32_e32 v105, v85
	v_pk_add_f32 v[104:105], v[108:109], v[104:105] neg_lo:[0,1] neg_hi:[0,1]
	v_pk_mul_f32 v[108:109], v[80:81], 0 op_sel_hi:[1,0]
	v_pk_mov_b32 v[82:83], v[136:137], v[132:133] op_sel:[1,0]
	v_mov_b32_e32 v115, v101
	v_pk_add_f32 v[94:95], v[110:111], v[118:119] neg_lo:[0,1] neg_hi:[0,1]
	v_fmac_f32_e32 v84, 0, v85
	v_pk_add_f32 v[110:111], v[80:81], v[108:109] op_sel:[0,1] op_sel_hi:[1,0]
	v_pk_add_f32 v[80:81], v[80:81], v[108:109] op_sel:[0,1] op_sel_hi:[1,0] neg_lo:[0,1] neg_hi:[0,1]
	v_pk_fma_f32 v[112:113], v[82:83], 0, v[132:133] op_sel_hi:[1,0,1]
	v_pk_fma_f32 v[82:83], v[82:83], 0, v[136:137] op_sel_hi:[1,0,1] neg_lo:[1,0,0] neg_hi:[1,0,0]
	v_pk_add_f32 v[100:101], v[124:125], v[114:115]
	v_pk_add_f32 v[102:103], v[96:97], v[116:117]
	v_add_f32_e32 v97, v126, v84
	v_mov_b32_e32 v111, v81
	v_mov_b32_e32 v113, v83
	v_sub_f32_e32 v126, v126, v84
	v_pk_mul_f32 v[84:85], v[100:101], 0 op_sel_hi:[1,0]
	v_pk_add_f32 v[80:81], v[102:103], v[110:111]
	v_mul_f32_e32 v109, 0x3f3504f3, v97
	v_mul_f32_e32 v97, 0, v94
	v_mov_b32_e32 v117, v95
	v_fmac_f32_e32 v94, 0, v95
	v_pk_add_f32 v[82:83], v[78:79], v[112:113]
	v_mov_b32_e32 v99, v87
	v_add_f32_e32 v118, v104, v105
	v_sub_f32_e32 v119, v104, v105
	v_pk_add_f32 v[104:105], v[100:101], v[84:85] op_sel:[0,1] op_sel_hi:[1,0]
	v_pk_add_f32 v[84:85], v[100:101], v[84:85] op_sel:[0,1] op_sel_hi:[1,0] neg_lo:[0,1] neg_hi:[0,1]
	v_pk_add_f32 v[96:97], v[96:97], v[116:117] neg_lo:[0,1] neg_hi:[0,1]
	v_add_f32_e32 v133, v131, v94
	v_sub_f32_e32 v131, v131, v94
	v_pk_mul_f32 v[94:95], v[80:81], 0 op_sel_hi:[1,0]
	v_pk_add_f32 v[86:87], v[82:83], v[98:99]
	v_mov_b32_e32 v105, v85
	v_add_f32_e32 v132, v96, v97
	v_sub_f32_e32 v134, v96, v97
	v_pk_add_f32 v[96:97], v[80:81], v[94:95] op_sel:[0,1] op_sel_hi:[1,0]
	v_pk_add_f32 v[80:81], v[80:81], v[94:95] op_sel:[0,1] op_sel_hi:[1,0] neg_lo:[0,1] neg_hi:[0,1]
	v_pk_add_f32 v[84:85], v[86:87], v[104:105]
	v_mov_b32_e32 v97, v81
	v_pk_add_f32 v[92:93], v[92:93], v[106:107] neg_lo:[0,1] neg_hi:[0,1]
	v_pk_add_f32 v[80:81], v[84:85], v[96:97]
	v_pk_add_f32 v[84:85], v[84:85], v[96:97] neg_lo:[0,1] neg_hi:[0,1]
	v_pk_add_f32 v[88:89], v[88:89], v[120:121] neg_lo:[0,1] neg_hi:[0,1]
	v_pk_fma_f32 v[96:97], v[92:93], 0, v[92:93] op_sel:[0,0,1] op_sel_hi:[1,0,0] neg_lo:[0,0,1] neg_hi:[0,0,1]
	v_pk_fma_f32 v[92:93], v[92:93], 0, v[92:93] op_sel:[0,0,1] op_sel_hi:[1,0,0]
	v_mul_f32_e32 v108, 0x3f3504f3, v118
	v_pk_add_f32 v[90:91], v[90:91], v[122:123] neg_lo:[0,1] neg_hi:[0,1]
	v_pk_fma_f32 v[94:95], v[88:89], 0, v[88:89] op_sel:[0,0,1] op_sel_hi:[1,0,0] neg_lo:[0,0,1] neg_hi:[0,0,1]
	v_pk_fma_f32 v[88:89], v[88:89], 0, v[88:89] op_sel:[0,0,1] op_sel_hi:[1,0,0]
	v_mov_b32_e32 v97, v93
	v_mul_f32_e32 v100, 0x3f3504f3, v127
	v_mul_f32_e32 v101, 0x3f3504f3, v128
	v_pk_add_f32 v[78:79], v[78:79], v[112:113] neg_lo:[0,1] neg_hi:[0,1]
	v_mov_b32_e32 v95, v89
	v_pk_add_f32 v[92:93], v[90:91], v[96:97]
	v_sub_f32_e32 v108, v108, v109
	v_fmac_f32_e32 v109, 0x3f3504f3, v118
	v_pk_add_f32 v[88:89], v[78:79], v[94:95]
	v_sub_f32_e32 v100, v100, v101
	v_fmac_f32_e32 v101, 0x3f3504f3, v127
	v_pk_add_f32 v[112:113], v[92:93], v[108:109]
	v_pk_add_f32 v[92:93], v[92:93], v[108:109] neg_lo:[0,1] neg_hi:[0,1]
	v_mul_f32_e32 v119, 0xbf3504f3, v119
	v_mul_f32_e32 v135, 0xbf3504f3, v126
	v_pk_add_f32 v[106:107], v[88:89], v[100:101]
	v_pk_add_f32 v[82:83], v[82:83], v[98:99] neg_lo:[0,1] neg_hi:[0,1]
	v_pk_add_f32 v[98:99], v[124:125], v[114:115] neg_lo:[0,1] neg_hi:[0,1]
	v_pk_add_f32 v[88:89], v[88:89], v[100:101] neg_lo:[0,1] neg_hi:[0,1]
	v_pk_mul_f32 v[100:101], v[92:93], s[4:5] op_sel:[1,0]
	v_pk_mul_f32 v[108:109], v[112:113], s[0:1] op_sel_hi:[1,0]
	v_pk_fma_f32 v[114:115], v[98:99], 0, v[98:99] op_sel:[0,0,1] op_sel_hi:[1,0,0] neg_lo:[0,0,1] neg_hi:[0,0,1]
	v_pk_fma_f32 v[98:99], v[98:99], 0, v[98:99] op_sel:[0,0,1] op_sel_hi:[1,0,0]
	v_add_f32_e32 v118, v135, v119
	v_fma_f32 v119, v126, s87, -v119
	v_pk_add_f32 v[90:91], v[90:91], v[96:97] neg_lo:[0,1] neg_hi:[0,1]
	v_pk_add_f32 v[102:103], v[102:103], v[110:111] neg_lo:[0,1] neg_hi:[0,1]
	v_pk_fma_f32 v[92:93], v[92:93], s[34:35], v[100:101] op_sel_hi:[0,1,1] neg_lo:[0,0,1] neg_hi:[0,0,1]
	v_pk_fma_f32 v[116:117], v[112:113], s[4:5], v[108:109] op_sel:[0,0,1] op_sel_hi:[1,0,0] neg_lo:[0,0,1] neg_hi:[0,0,1]
	v_pk_fma_f32 v[108:109], v[112:113], s[4:5], v[108:109] op_sel:[0,0,1] op_sel_hi:[1,0,0]
	v_mul_f32_e32 v112, 0x3f3504f3, v132
	v_mul_f32_e32 v113, 0x3f3504f3, v133
	v_mov_b32_e32 v115, v99
	v_pk_add_f32 v[96:97], v[90:91], v[118:119]
	v_pk_add_f32 v[86:87], v[86:87], v[104:105] neg_lo:[0,1] neg_hi:[0,1]
	v_pk_fma_f32 v[104:105], v[102:103], 0, v[102:103] op_sel:[0,0,1] op_sel_hi:[1,0,0] neg_lo:[0,0,1] neg_hi:[0,0,1]
	v_pk_fma_f32 v[102:103], v[102:103], 0, v[102:103] op_sel:[0,0,1] op_sel_hi:[1,0,0]
	v_pk_add_f32 v[100:101], v[88:89], v[92:93]
	v_pk_add_f32 v[88:89], v[88:89], v[92:93] neg_lo:[0,1] neg_hi:[0,1]
	v_mul_f32_e32 v93, 0xbf3504f3, v134
	v_mul_f32_e32 v92, 0xbf3504f3, v131
	v_mul_f32_e32 v128, 0xbf3504f3, v129
	v_mul_f32_e32 v129, 0xbf3504f3, v130
	v_mov_b32_e32 v117, v109
; #define LAS __attribute__((address_space(3)))
; __device__ __forceinline__ cf twc(cf ws, int k16) { if (k16 == 0) return ws; if (k16 == 4) return cf{ws.y, -ws.x}; return cmul(ws, cf{c16(k16), -s16(k16)}); }
; __device__ __forceinline__ void wave_lds_fence() { asm volatile("s_waitcnt lgkmcnt(0)" ::: "memory"); }
; template <int LR> __device__ __forceinline__ void dit_reg(cf (&x)[1 << LR], cf w) {
;     constexpr int R = 1 << LR; cf wsv[LR]; wsv[0] = w;
; #pragma unroll
;     for (int s = 1; s < LR; ++s) wsv[s] = cmul(wsv[s - 1], wsv[s - 1]);
; #pragma unroll
;     for (int s = LR - 1; s >= 0; --s) { const int half = R >> (s + 1);
; #pragma unroll
;         for (int m0 = 0; m0 < R; m0 += 2 * half)
; #pragma unroll
;             for (int mm = 0; mm < half; ++mm) { const int ia = m0 + mm, ib = ia + half; const cf a = x[ia];
;                 const cf b = cmulc(x[ib], twc(wsv[s], (mm << s) * (16 / R)));
;                 x[ia] = cf{a.x + b.x, a.y + b.y}; x[ib] = cf{a.x - b.x, a.y - b.y}; } }
; }
; __device__ __forceinline__ void lds_barrier() { asm volatile("s_waitcnt lgkmcnt(0)\n\ts_barrier" ::: "memory"); }
; template <int LR, bool INV> __device__ __forceinline__ void fft_pass(ldsf2 buf, int base, int stride, int twi) {
;     constexpr int R = 1 << LR; cf x[R];
;     const v2f wv = ((ldsf2)((LAS unsigned char*)buf + 139264))[twi];
; #pragma unroll
;     for (int m = 0; m < R; ++m) { const v2f v = buf[base + m * stride]; x[m] = cf{v.x, v.y}; }
;     const cf w{wv.x, wv.y};
;     if (INV) dit_reg<LR>(x, w); else dif_reg<LR>(x, w);
; #pragma unroll
;     for (int m = 0; m < R; ++m) buf[base + m * stride] = mkv2(x[m].x, x[m].y);
; }
; __device__ __forceinline__ void fft_conv(ldsf2 buf, const LAS unsigned* spec) {
;     ...
;       dit_reg<4>(x, cf{1.0f, 0.0f});
; #pragma unroll
;       for (int m = 0; m < 16; ++m) buf[tid * 17 + m] = mkv2(x[m].x, x[m].y); }
;     wave_lds_fence();
;     fft_inv_cba(buf);
	v_pk_add_f32 v[98:99], v[82:83], v[114:115]
	v_sub_f32_e32 v112, v112, v113
	v_fmac_f32_e32 v113, 0x3f3504f3, v132
	v_pk_add_f32 v[90:91], v[90:91], v[118:119] neg_lo:[0,1] neg_hi:[0,1]
	v_pk_mul_f32 v[118:119], v[96:97], s[4:5] op_sel_hi:[1,0]
	v_mov_b32_e32 v105, v103
	v_pk_add_f32 v[82:83], v[82:83], v[114:115] neg_lo:[0,1] neg_hi:[0,1]
	v_add_f32_e32 v92, v92, v93
	v_fma_f32 v93, v131, s87, -v93
	s_mov_b32 s35, s13
	v_pk_add_f32 v[108:109], v[106:107], v[116:117]
	v_pk_add_f32 v[106:107], v[106:107], v[116:117] neg_lo:[0,1] neg_hi:[0,1]
	v_pk_add_f32 v[116:117], v[98:99], v[112:113]
	v_pk_add_f32 v[98:99], v[98:99], v[112:113] neg_lo:[0,1] neg_hi:[0,1]
	v_add_f32_e32 v112, v129, v128
	v_fma_f32 v113, v130, s87, -v128
	v_pk_add_f32 v[78:79], v[78:79], v[94:95] neg_lo:[0,1] neg_hi:[0,1]
	v_pk_fma_f32 v[120:121], v[96:97], s[0:1], v[118:119] op_sel:[0,0,1] op_sel_hi:[1,0,0] neg_lo:[0,0,1] neg_hi:[0,0,1]
	v_pk_fma_f32 v[96:97], v[96:97], s[0:1], v[118:119] op_sel:[0,0,1] op_sel_hi:[1,0,0]
	v_pk_add_f32 v[102:103], v[86:87], v[104:105]
	v_pk_add_f32 v[86:87], v[86:87], v[104:105] neg_lo:[0,1] neg_hi:[0,1]
	v_pk_add_f32 v[104:105], v[82:83], v[92:93]
	v_pk_add_f32 v[82:83], v[82:83], v[92:93] neg_lo:[0,1] neg_hi:[0,1]
	v_pk_mul_f32 v[92:93], v[90:91], s[34:35] op_sel:[1,0]
	s_mov_b32 s0, s13
	v_pk_add_f32 v[94:95], v[78:79], v[112:113]
	v_pk_add_f32 v[78:79], v[78:79], v[112:113] neg_lo:[0,1] neg_hi:[0,1]
	v_pk_fma_f32 v[90:91], v[90:91], s[0:1], v[92:93] op_sel_hi:[0,1,1]
	v_mov_b32_e32 v121, v97
	v_pk_add_f32 v[92:93], v[78:79], v[90:91]
	v_pk_add_f32 v[78:79], v[78:79], v[90:91] neg_lo:[0,1] neg_hi:[0,1]
	v_pk_add_f32 v[96:97], v[94:95], v[120:121]
	v_pk_add_f32 v[94:95], v[94:95], v[120:121] neg_lo:[0,1] neg_hi:[0,1]
	ds_write2_b64 v151, v[80:81], v[108:109] offset1:1
	ds_write2_b64 v151, v[116:117], v[96:97] offset0:2 offset1:3
	ds_write2_b64 v151, v[102:103], v[100:101] offset0:4 offset1:5
	ds_write2_b64 v151, v[104:105], v[92:93] offset0:6 offset1:7
	ds_write2_b64 v151, v[84:85], v[106:107] offset0:8 offset1:9
	ds_write2_b64 v151, v[98:99], v[94:95] offset0:10 offset1:11
	ds_write2_b64 v151, v[86:87], v[88:89] offset0:12 offset1:13
	ds_write2_b64 v151, v[82:83], v[78:79] offset0:14 offset1:15
	v_mov_b32_e32 v78, v195
	s_waitcnt lgkmcnt(0)
	s_mov_b32 s0, 0
	v_and_b32_e32 v81, 15, v78
	v_lshlrev_b32_e32 v80, 4, v78
	v_lshlrev_b32_e32 v83, 9, v81
	v_and_b32_e32 v80, 0xfffffc00, v80
	v_lshlrev_b32_e32 v82, 3, v78
	v_add_u32_e32 v83, 0, v83
	v_and_b32_e32 v79, 63, v78
	v_lshl_add_u32 v81, v81, 3, 0
	v_and_or_b32 v82, v82, s90, v80
	v_add_u32_e32 v83, 0x22000, v83
.LBB0_365:
	ds_read_b64 v[100:101], v83
	v_cndmask_b32_e64 v84, 0, 1, s[14:15]
	v_cmp_ne_u32_e32 vcc, 1, v84
	v_or_b32_e32 v84, s0, v82
	v_lshlrev_b32_e32 v85, 3, v84
	v_ashrrev_i32_e32 v84, 1, v84
	v_add3_u32 v130, v81, v85, v84
	ds_read2_b64 v[84:87], v130 offset1:17
	ds_read2_b64 v[88:91], v130 offset0:34 offset1:51
	ds_read2_b64 v[92:95], v130 offset0:68 offset1:85
	ds_read2_b64 v[96:99], v130 offset0:102 offset1:119
	s_waitcnt lgkmcnt(4)
	v_pk_add_f32 v[102:103], v[100:101], v[100:101] op_sel:[0,1] op_sel_hi:[1,0] neg_lo:[0,0] neg_hi:[0,1]
	v_pk_mul_f32 v[104:105], v[102:103], s[16:17] op_sel:[0,0] op_sel_hi:[1,0]
	v_pk_mul_f32 v[106:107], v[102:103], s[16:17] op_sel:[1,0] op_sel_hi:[0,0] neg_lo:[0,0] neg_hi:[1,0]
	v_pk_mul_f32 v[108:109], v[100:101], v[100:101] op_sel:[1,1] op_sel_hi:[1,0]
	v_pk_fma_f32 v[108:109], v[100:101], v[100:101], v[108:109] op_sel:[0,0,0] op_sel_hi:[0,1,1] neg_lo:[0,0,1] neg_hi:[0,0,0]
	v_pk_mul_f32 v[110:111], v[108:109], v[108:109] op_sel:[1,1] op_sel_hi:[1,0]
	v_pk_fma_f32 v[110:111], v[108:109], v[108:109], v[110:111] op_sel:[0,0,0] op_sel_hi:[0,1,1] neg_lo:[0,0,1] neg_hi:[0,0,0]
	s_waitcnt lgkmcnt(0)
	v_pk_mul_f32 v[112:113], v[86:87], v[110:111] op_sel:[1,1] op_sel_hi:[1,0]
	v_pk_mul_f32 v[114:115], v[90:91], v[110:111] op_sel:[1,1] op_sel_hi:[1,0]
	v_pk_mul_f32 v[116:117], v[94:95], v[110:111] op_sel:[1,1] op_sel_hi:[1,0]
	v_pk_mul_f32 v[118:119], v[98:99], v[110:111] op_sel:[1,1] op_sel_hi:[1,0]
	v_pk_fma_f32 v[112:113], v[86:87], v[110:111], v[112:113] op_sel:[0,0,0] op_sel_hi:[0,1,1] neg_lo:[0,0,0] neg_hi:[0,1,0]
	v_pk_fma_f32 v[114:115], v[90:91], v[110:111], v[114:115] op_sel:[0,0,0] op_sel_hi:[0,1,1] neg_lo:[0,0,0] neg_hi:[0,1,0]
	v_pk_fma_f32 v[116:117], v[94:95], v[110:111], v[116:117] op_sel:[0,0,0] op_sel_hi:[0,1,1] neg_lo:[0,0,0] neg_hi:[0,1,0]
	v_pk_fma_f32 v[118:119], v[98:99], v[110:111], v[118:119] op_sel:[0,0,0] op_sel_hi:[0,1,1] neg_lo:[0,0,0] neg_hi:[0,1,0]
	v_pk_add_f32 v[86:87], v[84:85], v[112:113] neg_lo:[0,1] neg_hi:[0,1]
	v_pk_add_f32 v[90:91], v[88:89], v[114:115] neg_lo:[0,1] neg_hi:[0,1]
	v_pk_add_f32 v[94:95], v[92:93], v[116:117] neg_lo:[0,1] neg_hi:[0,1]
	v_pk_add_f32 v[98:99], v[96:97], v[118:119] neg_lo:[0,1] neg_hi:[0,1]
	v_pk_add_f32 v[84:85], v[84:85], v[112:113]
	v_pk_add_f32 v[88:89], v[88:89], v[114:115]
	v_pk_add_f32 v[92:93], v[92:93], v[116:117]
	v_pk_add_f32 v[96:97], v[96:97], v[118:119]
	v_pk_mul_f32 v[112:113], v[88:89], v[108:109] op_sel:[1,1] op_sel_hi:[1,0]
	v_pk_mul_f32 v[114:115], v[90:91], v[108:109] op_sel:[1,0] op_sel_hi:[1,1]
	v_pk_mul_f32 v[116:117], v[96:97], v[108:109] op_sel:[1,1] op_sel_hi:[1,0]
	v_pk_mul_f32 v[118:119], v[98:99], v[108:109] op_sel:[1,0] op_sel_hi:[1,1]
	v_pk_fma_f32 v[112:113], v[88:89], v[108:109], v[112:113] op_sel:[0,0,0] op_sel_hi:[0,1,1] neg_lo:[0,0,0] neg_hi:[0,1,0]
	v_pk_fma_f32 v[114:115], v[90:91], v[108:109], v[114:115] op_sel:[0,1,0] op_sel_hi:[0,0,1] neg_lo:[0,0,1] neg_hi:[0,0,0]
	v_pk_fma_f32 v[116:117], v[96:97], v[108:109], v[116:117] op_sel:[0,0,0] op_sel_hi:[0,1,1] neg_lo:[0,0,0] neg_hi:[0,1,0]
; #define LAS __attribute__((address_space(3)))
; __device__ __forceinline__ cf twc(cf ws, int k16) { if (k16 == 0) return ws; if (k16 == 4) return cf{ws.y, -ws.x}; return cmul(ws, cf{c16(k16), -s16(k16)}); }
; __device__ __forceinline__ void wave_lds_fence() { asm volatile("s_waitcnt lgkmcnt(0)" ::: "memory"); }
; template <int LR> __device__ __forceinline__ void dit_reg(cf (&x)[1 << LR], cf w) {
;     constexpr int R = 1 << LR; cf wsv[LR]; wsv[0] = w;
; #pragma unroll
;     for (int s = 1; s < LR; ++s) wsv[s] = cmul(wsv[s - 1], wsv[s - 1]);
; #pragma unroll
;     for (int s = LR - 1; s >= 0; --s) { const int half = R >> (s + 1);
; #pragma unroll
;         for (int m0 = 0; m0 < R; m0 += 2 * half)
; #pragma unroll
;             for (int mm = 0; mm < half; ++mm) { const int ia = m0 + mm, ib = ia + half; const cf a = x[ia];
;                 const cf b = cmulc(x[ib], twc(wsv[s], (mm << s) * (16 / R)));
;                 x[ia] = cf{a.x + b.x, a.y + b.y}; x[ib] = cf{a.x - b.x, a.y - b.y}; } }
; }
; __device__ __forceinline__ void lds_barrier() { asm volatile("s_waitcnt lgkmcnt(0)\n\ts_barrier" ::: "memory"); }
; template <int LR, bool INV> __device__ __forceinline__ void fft_pass(ldsf2 buf, int base, int stride, int twi) {
;     constexpr int R = 1 << LR; cf x[R];
;     const v2f wv = ((ldsf2)((LAS unsigned char*)buf + 139264))[twi];
; #pragma unroll
;     for (int m = 0; m < R; ++m) { const v2f v = buf[base + m * stride]; x[m] = cf{v.x, v.y}; }
;     const cf w{wv.x, wv.y};
;     if (INV) dit_reg<LR>(x, w); else dif_reg<LR>(x, w);
; #pragma unroll
;     for (int m = 0; m < R; ++m) buf[base + m * stride] = mkv2(x[m].x, x[m].y);
; }
; __device__ __forceinline__ void fft_inv_cba(ldsf2 buf) {
;     ...
;     for (int u = 0; u < 2; ++u) { const int j = l + 64 * u, o = j & 15, e0 = wv * 1024 + (j >> 4) * 128 + o; fft_pass<3, true>(buf, e0 + (e0 >> 4), 17, o * 64); }
;     wave_lds_fence();
; #pragma unroll 1
;     for (int u = 0; u < 2; ++u) { const int o = l + 64 * u, e0 = wv * 1024 + o; fft_pass<3, true>(buf, e0 + (e0 >> 4), 136, o * 8); }
;     lds_barrier();
	v_pk_fma_f32 v[118:119], v[98:99], v[108:109], v[118:119] op_sel:[0,1,0] op_sel_hi:[0,0,1] neg_lo:[0,0,1] neg_hi:[0,0,0]
	v_pk_add_f32 v[88:89], v[84:85], v[112:113] neg_lo:[0,1] neg_hi:[0,1]
	v_pk_add_f32 v[90:91], v[86:87], v[114:115] neg_lo:[0,1] neg_hi:[0,1]
	v_pk_add_f32 v[96:97], v[92:93], v[116:117] neg_lo:[0,1] neg_hi:[0,1]
	v_pk_add_f32 v[98:99], v[94:95], v[118:119] neg_lo:[0,1] neg_hi:[0,1]
	v_pk_add_f32 v[84:85], v[84:85], v[112:113]
	v_pk_add_f32 v[86:87], v[86:87], v[114:115]
	v_pk_add_f32 v[92:93], v[92:93], v[116:117]
	v_pk_add_f32 v[94:95], v[94:95], v[118:119]
	v_pk_mul_f32 v[112:113], v[92:93], v[100:101] op_sel:[1,1] op_sel_hi:[1,0]
	v_pk_mul_f32 v[114:115], v[94:95], v[104:105] op_sel:[1,1] op_sel_hi:[1,0]
	v_pk_mul_f32 v[116:117], v[96:97], v[100:101] op_sel:[1,0] op_sel_hi:[1,1]
	v_pk_mul_f32 v[118:119], v[98:99], v[106:107] op_sel:[1,1] op_sel_hi:[1,0]
	v_pk_fma_f32 v[112:113], v[92:93], v[100:101], v[112:113] op_sel:[0,0,0] op_sel_hi:[0,1,1] neg_lo:[0,0,0] neg_hi:[0,1,0]
	v_pk_fma_f32 v[114:115], v[94:95], v[104:105], v[114:115] op_sel:[0,0,0] op_sel_hi:[0,1,1] neg_lo:[0,0,0] neg_hi:[0,1,0]
	v_pk_fma_f32 v[116:117], v[96:97], v[100:101], v[116:117] op_sel:[0,1,0] op_sel_hi:[0,0,1] neg_lo:[0,0,1] neg_hi:[0,0,0]
	v_pk_fma_f32 v[118:119], v[98:99], v[106:107], v[118:119] op_sel:[0,0,0] op_sel_hi:[0,1,1] neg_lo:[0,0,0] neg_hi:[0,1,0]
	v_pk_add_f32 v[92:93], v[84:85], v[112:113] neg_lo:[0,1] neg_hi:[0,1]
	v_pk_add_f32 v[94:95], v[86:87], v[114:115] neg_lo:[0,1] neg_hi:[0,1]
	v_pk_add_f32 v[96:97], v[88:89], v[116:117] neg_lo:[0,1] neg_hi:[0,1]
	v_pk_add_f32 v[98:99], v[90:91], v[118:119] neg_lo:[0,1] neg_hi:[0,1]
	v_pk_add_f32 v[84:85], v[84:85], v[112:113]
	v_pk_add_f32 v[86:87], v[86:87], v[114:115]
	v_pk_add_f32 v[88:89], v[88:89], v[116:117]
	v_pk_add_f32 v[90:91], v[90:91], v[118:119]
	ds_write2_b64 v130, v[84:85], v[86:87] offset1:17
	ds_write2_b64 v130, v[88:89], v[90:91] offset0:34 offset1:51
	ds_write2_b64 v130, v[92:93], v[94:95] offset0:68 offset1:85
	ds_write2_b64 v130, v[96:97], v[98:99] offset0:102 offset1:119
	s_movk_i32 s0, 0x200
	s_mov_b64 s[14:15], 0
	s_and_b64 vcc, exec, vcc
	s_cbranch_vccz .LBB0_365
	s_waitcnt lgkmcnt(0)
	s_mov_b32 s0, 0
	s_mov_b64 s[14:15], -1
.LBB0_367:
	v_cndmask_b32_e64 v81, 0, 1, s[14:15]
	v_cmp_ne_u32_e32 vcc, 1, v81
	v_or_b32_e32 v81, s0, v79
	v_or_b32_e32 v82, v81, v80
	v_lshl_add_u32 v81, v81, 6, 0
	v_add_u32_e32 v81, 0x22000, v81
	ds_read_b64 v[98:99], v81
	v_ashrrev_i32_e32 v83, 4, v82
	v_lshlrev_b32_e32 v81, 3, v82
	v_lshlrev_b32_e32 v82, 3, v83
	v_add3_u32 v81, 0, v81, v82
	v_add_u32_e32 v130, 0x1800, v81
	v_add_u32_e32 v129, 0x1000, v81
	ds_read2_b64 v[94:97], v130 offset0:48 offset1:184
	ds_read2_b64 v[90:93], v129 offset0:32 offset1:168
	v_add_u32_e32 v128, 0x800, v81
	ds_read2_b64 v[82:85], v81 offset1:136
	ds_read2_b64 v[86:89], v128 offset0:16 offset1:152
	s_waitcnt lgkmcnt(4)
	v_pk_add_f32 v[100:101], v[98:99], v[98:99] op_sel:[0,1] op_sel_hi:[1,0] neg_lo:[0,0] neg_hi:[0,1]
	v_pk_mul_f32 v[102:103], v[100:101], s[16:17] op_sel:[0,0] op_sel_hi:[1,0]
	v_pk_mul_f32 v[104:105], v[100:101], s[16:17] op_sel:[1,0] op_sel_hi:[0,0] neg_lo:[0,0] neg_hi:[1,0]
	v_pk_mul_f32 v[106:107], v[98:99], v[98:99] op_sel:[1,1] op_sel_hi:[1,0]
	v_pk_fma_f32 v[106:107], v[98:99], v[98:99], v[106:107] op_sel:[0,0,0] op_sel_hi:[0,1,1] neg_lo:[0,0,1] neg_hi:[0,0,0]
	v_pk_mul_f32 v[108:109], v[106:107], v[106:107] op_sel:[1,1] op_sel_hi:[1,0]
	v_pk_fma_f32 v[108:109], v[106:107], v[106:107], v[108:109] op_sel:[0,0,0] op_sel_hi:[0,1,1] neg_lo:[0,0,1] neg_hi:[0,0,0]
	s_waitcnt lgkmcnt(0)
	v_pk_mul_f32 v[110:111], v[84:85], v[108:109] op_sel:[1,1] op_sel_hi:[1,0]
	v_pk_mul_f32 v[112:113], v[88:89], v[108:109] op_sel:[1,1] op_sel_hi:[1,0]
	v_pk_mul_f32 v[114:115], v[92:93], v[108:109] op_sel:[1,1] op_sel_hi:[1,0]
	v_pk_mul_f32 v[116:117], v[96:97], v[108:109] op_sel:[1,1] op_sel_hi:[1,0]
	v_pk_fma_f32 v[110:111], v[84:85], v[108:109], v[110:111] op_sel:[0,0,0] op_sel_hi:[0,1,1] neg_lo:[0,0,0] neg_hi:[0,1,0]
	v_pk_fma_f32 v[112:113], v[88:89], v[108:109], v[112:113] op_sel:[0,0,0] op_sel_hi:[0,1,1] neg_lo:[0,0,0] neg_hi:[0,1,0]
	v_pk_fma_f32 v[114:115], v[92:93], v[108:109], v[114:115] op_sel:[0,0,0] op_sel_hi:[0,1,1] neg_lo:[0,0,0] neg_hi:[0,1,0]
	v_pk_fma_f32 v[116:117], v[96:97], v[108:109], v[116:117] op_sel:[0,0,0] op_sel_hi:[0,1,1] neg_lo:[0,0,0] neg_hi:[0,1,0]
	v_pk_add_f32 v[84:85], v[82:83], v[110:111] neg_lo:[0,1] neg_hi:[0,1]
	v_pk_add_f32 v[88:89], v[86:87], v[112:113] neg_lo:[0,1] neg_hi:[0,1]
	v_pk_add_f32 v[92:93], v[90:91], v[114:115] neg_lo:[0,1] neg_hi:[0,1]
	v_pk_add_f32 v[96:97], v[94:95], v[116:117] neg_lo:[0,1] neg_hi:[0,1]
	v_pk_add_f32 v[82:83], v[82:83], v[110:111]
	v_pk_add_f32 v[86:87], v[86:87], v[112:113]
	v_pk_add_f32 v[90:91], v[90:91], v[114:115]
	v_pk_add_f32 v[94:95], v[94:95], v[116:117]
	v_pk_mul_f32 v[110:111], v[86:87], v[106:107] op_sel:[1,1] op_sel_hi:[1,0]
	v_pk_mul_f32 v[112:113], v[88:89], v[106:107] op_sel:[1,0] op_sel_hi:[1,1]
	v_pk_mul_f32 v[114:115], v[94:95], v[106:107] op_sel:[1,1] op_sel_hi:[1,0]
	v_pk_mul_f32 v[116:117], v[96:97], v[106:107] op_sel:[1,0] op_sel_hi:[1,1]
	v_pk_fma_f32 v[110:111], v[86:87], v[106:107], v[110:111] op_sel:[0,0,0] op_sel_hi:[0,1,1] neg_lo:[0,0,0] neg_hi:[0,1,0]
	v_pk_fma_f32 v[112:113], v[88:89], v[106:107], v[112:113] op_sel:[0,1,0] op_sel_hi:[0,0,1] neg_lo:[0,0,1] neg_hi:[0,0,0]
	v_pk_fma_f32 v[114:115], v[94:95], v[106:107], v[114:115] op_sel:[0,0,0] op_sel_hi:[0,1,1] neg_lo:[0,0,0] neg_hi:[0,1,0]
	v_pk_fma_f32 v[116:117], v[96:97], v[106:107], v[116:117] op_sel:[0,1,0] op_sel_hi:[0,0,1] neg_lo:[0,0,1] neg_hi:[0,0,0]
; #define LAS __attribute__((address_space(3)))
; __device__ __forceinline__ cf twc(cf ws, int k16) { if (k16 == 0) return ws; if (k16 == 4) return cf{ws.y, -ws.x}; return cmul(ws, cf{c16(k16), -s16(k16)}); }
; __device__ __forceinline__ void wave_lds_fence() { asm volatile("s_waitcnt lgkmcnt(0)" ::: "memory"); }
; template <int LR> __device__ __forceinline__ void dit_reg(cf (&x)[1 << LR], cf w) {
;     constexpr int R = 1 << LR; cf wsv[LR]; wsv[0] = w;
; #pragma unroll
;     for (int s = 1; s < LR; ++s) wsv[s] = cmul(wsv[s - 1], wsv[s - 1]);
; #pragma unroll
;     for (int s = LR - 1; s >= 0; --s) { const int half = R >> (s + 1);
; #pragma unroll
;         for (int m0 = 0; m0 < R; m0 += 2 * half)
; #pragma unroll
;             for (int mm = 0; mm < half; ++mm) { const int ia = m0 + mm, ib = ia + half; const cf a = x[ia];
;                 const cf b = cmulc(x[ib], twc(wsv[s], (mm << s) * (16 / R)));
;                 x[ia] = cf{a.x + b.x, a.y + b.y}; x[ib] = cf{a.x - b.x, a.y - b.y}; } }
; }
; __device__ __forceinline__ void lds_barrier() { asm volatile("s_waitcnt lgkmcnt(0)\n\ts_barrier" ::: "memory"); }
; template <int LR, bool INV> __device__ __forceinline__ void fft_pass(ldsf2 buf, int base, int stride, int twi) {
;     constexpr int R = 1 << LR; cf x[R];
;     const v2f wv = ((ldsf2)((LAS unsigned char*)buf + 139264))[twi];
; #pragma unroll
;     for (int m = 0; m < R; ++m) { const v2f v = buf[base + m * stride]; x[m] = cf{v.x, v.y}; }
;     const cf w{wv.x, wv.y};
;     if (INV) dit_reg<LR>(x, w); else dif_reg<LR>(x, w);
; #pragma unroll
;     for (int m = 0; m < R; ++m) buf[base + m * stride] = mkv2(x[m].x, x[m].y);
; }
; __device__ __forceinline__ void fft_inv_cba(ldsf2 buf) {
;     ...
;     for (int u = 0; u < 2; ++u) { const int j = l + 64 * u, o = j & 15, e0 = wv * 1024 + (j >> 4) * 128 + o; fft_pass<3, true>(buf, e0 + (e0 >> 4), 17, o * 64); }
;     wave_lds_fence();
; #pragma unroll 1
;     for (int u = 0; u < 2; ++u) { const int o = l + 64 * u, e0 = wv * 1024 + o; fft_pass<3, true>(buf, e0 + (e0 >> 4), 136, o * 8); }
;     lds_barrier();
; #pragma unroll 1
;     for (int u = 0; u < 2; ++u) { const int bf = tid + NT * u; fft_pass<3, true>(buf, bf + (bf >> 4), 1088, bf); }
	v_pk_add_f32 v[86:87], v[82:83], v[110:111] neg_lo:[0,1] neg_hi:[0,1]
	v_pk_add_f32 v[88:89], v[84:85], v[112:113] neg_lo:[0,1] neg_hi:[0,1]
	v_pk_add_f32 v[94:95], v[90:91], v[114:115] neg_lo:[0,1] neg_hi:[0,1]
	v_pk_add_f32 v[96:97], v[92:93], v[116:117] neg_lo:[0,1] neg_hi:[0,1]
	v_pk_add_f32 v[82:83], v[82:83], v[110:111]
	v_pk_add_f32 v[84:85], v[84:85], v[112:113]
	v_pk_add_f32 v[90:91], v[90:91], v[114:115]
	v_pk_add_f32 v[92:93], v[92:93], v[116:117]
	v_pk_mul_f32 v[110:111], v[90:91], v[98:99] op_sel:[1,1] op_sel_hi:[1,0]
	v_pk_mul_f32 v[112:113], v[92:93], v[102:103] op_sel:[1,1] op_sel_hi:[1,0]
	v_pk_mul_f32 v[114:115], v[94:95], v[98:99] op_sel:[1,0] op_sel_hi:[1,1]
	v_pk_mul_f32 v[116:117], v[96:97], v[104:105] op_sel:[1,1] op_sel_hi:[1,0]
	v_pk_fma_f32 v[110:111], v[90:91], v[98:99], v[110:111] op_sel:[0,0,0] op_sel_hi:[0,1,1] neg_lo:[0,0,0] neg_hi:[0,1,0]
	v_pk_fma_f32 v[112:113], v[92:93], v[102:103], v[112:113] op_sel:[0,0,0] op_sel_hi:[0,1,1] neg_lo:[0,0,0] neg_hi:[0,1,0]
	v_pk_fma_f32 v[114:115], v[94:95], v[98:99], v[114:115] op_sel:[0,1,0] op_sel_hi:[0,0,1] neg_lo:[0,0,1] neg_hi:[0,0,0]
	v_pk_fma_f32 v[116:117], v[96:97], v[104:105], v[116:117] op_sel:[0,0,0] op_sel_hi:[0,1,1] neg_lo:[0,0,0] neg_hi:[0,1,0]
	v_pk_add_f32 v[90:91], v[82:83], v[110:111] neg_lo:[0,1] neg_hi:[0,1]
	v_pk_add_f32 v[92:93], v[84:85], v[112:113] neg_lo:[0,1] neg_hi:[0,1]
	v_pk_add_f32 v[94:95], v[86:87], v[114:115] neg_lo:[0,1] neg_hi:[0,1]
	v_pk_add_f32 v[96:97], v[88:89], v[116:117] neg_lo:[0,1] neg_hi:[0,1]
	v_pk_add_f32 v[82:83], v[82:83], v[110:111]
	v_pk_add_f32 v[84:85], v[84:85], v[112:113]
	v_pk_add_f32 v[86:87], v[86:87], v[114:115]
	v_pk_add_f32 v[88:89], v[88:89], v[116:117]
	ds_write2_b64 v81, v[82:83], v[84:85] offset1:136
	ds_write2_b64 v128, v[86:87], v[88:89] offset0:16 offset1:152
	ds_write2_b64 v129, v[90:91], v[92:93] offset0:32 offset1:168
	ds_write2_b64 v130, v[94:95], v[96:97] offset0:48 offset1:184
	s_mov_b32 s0, 64
	s_mov_b64 s[14:15], 0
	s_and_b64 vcc, exec, vcc
	s_cbranch_vccz .LBB0_367
	s_waitcnt lgkmcnt(0)
	s_barrier
	s_mov_b32 s0, 0
	s_mov_b64 s[30:31], -1
.LBB0_369:
	v_add_u32_e32 v79, s0, v78
	v_ashrrev_i32_e32 v80, 4, v79
	v_lshl_add_u32 v79, v79, 3, 0
	v_add_u32_e32 v81, 0x22000, v79
	ds_read_b64 v[96:97], v81
	v_lshl_add_u32 v79, v80, 3, v79
	ds_read2st64_b64 v[80:83], v79 offset1:17
	ds_read2st64_b64 v[84:87], v79 offset0:34 offset1:51
	ds_read2st64_b64 v[88:91], v79 offset0:68 offset1:85
	ds_read2st64_b64 v[92:95], v79 offset0:102 offset1:119
	s_waitcnt lgkmcnt(4)
	v_pk_add_f32 v[98:99], v[96:97], v[96:97] op_sel:[0,1] op_sel_hi:[1,0] neg_lo:[0,0] neg_hi:[0,1]
	v_pk_mul_f32 v[100:101], v[98:99], s[16:17] op_sel:[0,0] op_sel_hi:[1,0]
	v_pk_mul_f32 v[102:103], v[98:99], s[16:17] op_sel:[1,0] op_sel_hi:[0,0] neg_lo:[0,0] neg_hi:[1,0]
	v_pk_mul_f32 v[104:105], v[96:97], v[96:97] op_sel:[1,1] op_sel_hi:[1,0]
	v_pk_fma_f32 v[104:105], v[96:97], v[96:97], v[104:105] op_sel:[0,0,0] op_sel_hi:[0,1,1] neg_lo:[0,0,1] neg_hi:[0,0,0]
	v_pk_mul_f32 v[106:107], v[104:105], v[104:105] op_sel:[1,1] op_sel_hi:[1,0]
	v_pk_fma_f32 v[106:107], v[104:105], v[104:105], v[106:107] op_sel:[0,0,0] op_sel_hi:[0,1,1] neg_lo:[0,0,1] neg_hi:[0,0,0]
	s_waitcnt lgkmcnt(0)
	v_pk_mul_f32 v[108:109], v[82:83], v[106:107] op_sel:[1,1] op_sel_hi:[1,0]
	v_pk_mul_f32 v[110:111], v[86:87], v[106:107] op_sel:[1,1] op_sel_hi:[1,0]
	v_pk_mul_f32 v[112:113], v[90:91], v[106:107] op_sel:[1,1] op_sel_hi:[1,0]
	v_pk_mul_f32 v[114:115], v[94:95], v[106:107] op_sel:[1,1] op_sel_hi:[1,0]
	v_pk_fma_f32 v[108:109], v[82:83], v[106:107], v[108:109] op_sel:[0,0,0] op_sel_hi:[0,1,1] neg_lo:[0,0,0] neg_hi:[0,1,0]
	v_pk_fma_f32 v[110:111], v[86:87], v[106:107], v[110:111] op_sel:[0,0,0] op_sel_hi:[0,1,1] neg_lo:[0,0,0] neg_hi:[0,1,0]
	v_pk_fma_f32 v[112:113], v[90:91], v[106:107], v[112:113] op_sel:[0,0,0] op_sel_hi:[0,1,1] neg_lo:[0,0,0] neg_hi:[0,1,0]
	v_pk_fma_f32 v[114:115], v[94:95], v[106:107], v[114:115] op_sel:[0,0,0] op_sel_hi:[0,1,1] neg_lo:[0,0,0] neg_hi:[0,1,0]
	v_pk_add_f32 v[82:83], v[80:81], v[108:109] neg_lo:[0,1] neg_hi:[0,1]
	v_pk_add_f32 v[86:87], v[84:85], v[110:111] neg_lo:[0,1] neg_hi:[0,1]
	v_pk_add_f32 v[90:91], v[88:89], v[112:113] neg_lo:[0,1] neg_hi:[0,1]
	v_pk_add_f32 v[94:95], v[92:93], v[114:115] neg_lo:[0,1] neg_hi:[0,1]
	v_pk_add_f32 v[80:81], v[80:81], v[108:109]
	v_pk_add_f32 v[84:85], v[84:85], v[110:111]
	v_pk_add_f32 v[88:89], v[88:89], v[112:113]
	v_pk_add_f32 v[92:93], v[92:93], v[114:115]
	v_pk_mul_f32 v[108:109], v[84:85], v[104:105] op_sel:[1,1] op_sel_hi:[1,0]
	v_pk_mul_f32 v[110:111], v[86:87], v[104:105] op_sel:[1,0] op_sel_hi:[1,1]
	v_pk_mul_f32 v[112:113], v[92:93], v[104:105] op_sel:[1,1] op_sel_hi:[1,0]
	v_pk_mul_f32 v[114:115], v[94:95], v[104:105] op_sel:[1,0] op_sel_hi:[1,1]
	v_pk_fma_f32 v[108:109], v[84:85], v[104:105], v[108:109] op_sel:[0,0,0] op_sel_hi:[0,1,1] neg_lo:[0,0,0] neg_hi:[0,1,0]
	v_pk_fma_f32 v[110:111], v[86:87], v[104:105], v[110:111] op_sel:[0,1,0] op_sel_hi:[0,0,1] neg_lo:[0,0,1] neg_hi:[0,0,0]
	v_pk_fma_f32 v[112:113], v[92:93], v[104:105], v[112:113] op_sel:[0,0,0] op_sel_hi:[0,1,1] neg_lo:[0,0,0] neg_hi:[0,1,0]
	v_pk_fma_f32 v[114:115], v[94:95], v[104:105], v[114:115] op_sel:[0,1,0] op_sel_hi:[0,0,1] neg_lo:[0,0,1] neg_hi:[0,0,0]
	v_pk_add_f32 v[84:85], v[80:81], v[108:109] neg_lo:[0,1] neg_hi:[0,1]
	v_pk_add_f32 v[86:87], v[82:83], v[110:111] neg_lo:[0,1] neg_hi:[0,1]
	v_pk_add_f32 v[92:93], v[88:89], v[112:113] neg_lo:[0,1] neg_hi:[0,1]
	v_pk_add_f32 v[94:95], v[90:91], v[114:115] neg_lo:[0,1] neg_hi:[0,1]
	v_pk_add_f32 v[80:81], v[80:81], v[108:109]
	v_pk_add_f32 v[82:83], v[82:83], v[110:111]
; #define LAS __attribute__((address_space(3)))
; template <int LR> __device__ __forceinline__ void dit_reg(cf (&x)[1 << LR], cf w) {
;     constexpr int R = 1 << LR; cf wsv[LR]; wsv[0] = w;
; #pragma unroll
;     for (int s = 1; s < LR; ++s) wsv[s] = cmul(wsv[s - 1], wsv[s - 1]);
; #pragma unroll
;     for (int s = LR - 1; s >= 0; --s) { const int half = R >> (s + 1);
; #pragma unroll
;         for (int m0 = 0; m0 < R; m0 += 2 * half)
; #pragma unroll
;             for (int mm = 0; mm < half; ++mm) { const int ia = m0 + mm, ib = ia + half; const cf a = x[ia];
;                 const cf b = cmulc(x[ib], twc(wsv[s], (mm << s) * (16 / R)));
;                 x[ia] = cf{a.x + b.x, a.y + b.y}; x[ib] = cf{a.x - b.x, a.y - b.y}; } }
; }
; __device__ __forceinline__ void lds_barrier() { asm volatile("s_waitcnt lgkmcnt(0)\n\ts_barrier" ::: "memory"); }
; template <int LR, bool INV> __device__ __forceinline__ void fft_pass(ldsf2 buf, int base, int stride, int twi) {
;     constexpr int R = 1 << LR; cf x[R];
;     const v2f wv = ((ldsf2)((LAS unsigned char*)buf + 139264))[twi];
; #pragma unroll
;     for (int m = 0; m < R; ++m) { const v2f v = buf[base + m * stride]; x[m] = cf{v.x, v.y}; }
;     const cf w{wv.x, wv.y};
;     if (INV) dit_reg<LR>(x, w); else dif_reg<LR>(x, w);
; #pragma unroll
;     for (int m = 0; m < R; ++m) buf[base + m * stride] = mkv2(x[m].x, x[m].y);
; }
; __device__ void ph_hyena_fft(const Params& P, int j, const bf16_t* __restrict__ projAT, const float* __restrict__ kf, bf16_t* __restrict__ yaT, unsigned char* lds_raw) {
;     ...
;             { float xa[8], xb[8]; sconv8(xb0, n0, wb0, wb1, wb2, bb, xa); sconv8(xb1, n0, wb0, wb1, wb2, bb, xb);
;               const unsigned gw0[4] = {g0.x, g0.y, g0.z, g0.w}, gw1[4] = {g1.x, g1.y, g1.z, g1.w}; unsigned w0[4], w1[4];
; #pragma unroll
;               for (int k2 = 0; k2 < 4; ++k2) { const v2f ya = buf[ph0 + 2 * k2], yb = buf[ph0 + 2 * k2 + 1];
;                   const float ra = xa[2 * k2] * (ya.x * invN + sk1 * va[2 * k2]) * silu(__uint_as_float(gw0[k2] << 16));
;                   const float rb = xa[2 * k2 + 1] * (yb.x * invN + sk1 * va[2 * k2 + 1]) * silu(__uint_as_float(gw0[k2] & 0xffff0000u));
;                   const float rc = xb[2 * k2] * (ya.y * invN + sk1 * vb[2 * k2]) * silu(__uint_as_float(gw1[k2] << 16));
	v_pk_add_f32 v[88:89], v[88:89], v[112:113]
	v_pk_add_f32 v[90:91], v[90:91], v[114:115]
	v_pk_mul_f32 v[108:109], v[88:89], v[96:97] op_sel:[1,1] op_sel_hi:[1,0]
	v_pk_mul_f32 v[110:111], v[90:91], v[100:101] op_sel:[1,1] op_sel_hi:[1,0]
	v_pk_mul_f32 v[112:113], v[92:93], v[96:97] op_sel:[1,0] op_sel_hi:[1,1]
	v_pk_mul_f32 v[114:115], v[94:95], v[102:103] op_sel:[1,1] op_sel_hi:[1,0]
	v_pk_fma_f32 v[108:109], v[88:89], v[96:97], v[108:109] op_sel:[0,0,0] op_sel_hi:[0,1,1] neg_lo:[0,0,0] neg_hi:[0,1,0]
	v_pk_fma_f32 v[110:111], v[90:91], v[100:101], v[110:111] op_sel:[0,0,0] op_sel_hi:[0,1,1] neg_lo:[0,0,0] neg_hi:[0,1,0]
	v_pk_fma_f32 v[112:113], v[92:93], v[96:97], v[112:113] op_sel:[0,1,0] op_sel_hi:[0,0,1] neg_lo:[0,0,1] neg_hi:[0,0,0]
	v_pk_fma_f32 v[114:115], v[94:95], v[102:103], v[114:115] op_sel:[0,0,0] op_sel_hi:[0,1,1] neg_lo:[0,0,0] neg_hi:[0,1,0]
	v_pk_add_f32 v[88:89], v[80:81], v[108:109] neg_lo:[0,1] neg_hi:[0,1]
	v_pk_add_f32 v[90:91], v[82:83], v[110:111] neg_lo:[0,1] neg_hi:[0,1]
	v_pk_add_f32 v[92:93], v[84:85], v[112:113] neg_lo:[0,1] neg_hi:[0,1]
	v_pk_add_f32 v[94:95], v[86:87], v[114:115] neg_lo:[0,1] neg_hi:[0,1]
	v_pk_add_f32 v[80:81], v[80:81], v[108:109]
	v_pk_add_f32 v[82:83], v[82:83], v[110:111]
	v_pk_add_f32 v[84:85], v[84:85], v[112:113]
	v_pk_add_f32 v[86:87], v[86:87], v[114:115]
	ds_write2st64_b64 v79, v[80:81], v[82:83] offset1:17
	ds_write2st64_b64 v79, v[84:85], v[86:87] offset0:34 offset1:51
	ds_write2st64_b64 v79, v[88:89], v[90:91] offset0:68 offset1:85
	ds_write2st64_b64 v79, v[92:93], v[94:95] offset0:102 offset1:119
	s_movk_i32 s0, 0x200
	s_and_b64 vcc, exec, s[30:31]
	s_mov_b64 s[30:31], 0
	s_cbranch_vccnz .LBB0_369
	s_waitcnt vmcnt(6)
	v_lshlrev_b32_e32 v78, 16, v147
	v_cndmask_b32_e64 v97, 0, v78, s[42:43]
	s_waitcnt vmcnt(5)
	v_lshlrev_b32_e32 v78, 16, v148
	s_waitcnt vmcnt(1)
	v_lshlrev_b32_e32 v114, 16, v12
	v_cndmask_b32_e64 v99, 0, v78, s[44:45]
	v_and_b32_e32 v12, 0xffff0000, v12
	v_mul_f32_e32 v78, 0xbfb8aa3b, v114
	v_exp_f32_e32 v78, v78
	v_mul_f32_e32 v82, 0xbfb8aa3b, v12
	v_lshlrev_b32_e32 v104, 16, v5
	v_exp_f32_e32 v82, v82
	v_and_b32_e32 v102, 0xffff0000, v4
	v_mov_b32_e32 v96, v104
	v_lshlrev_b32_e32 v100, 16, v4
	v_and_b32_e32 v103, 0xffff0000, v5
	v_mov_b32_e32 v101, v102
	v_pk_mul_f32 v[96:97], v[38:39], v[96:97]
	v_lshlrev_b32_e32 v115, 16, v13
	v_pk_fma_f32 v[96:97], v[38:39], v[100:101], v[96:97] op_sel:[0,0,1] op_sel_hi:[1,1,0]
	v_mov_b32_e32 v101, v104
	v_pk_mul_f32 v[122:123], v[54:55], v[102:103]
	v_add_f32_e32 v78, 1.0, v78
	v_pk_fma_f32 v[100:101], v[52:53], v[100:101], v[122:123]
	v_rcp_f32_e32 v122, v78
	v_add_f32_e32 v78, 1.0, v82
	v_mul_f32_e32 v82, 0xbfb8aa3b, v115
	v_exp_f32_e32 v82, v82
	s_waitcnt lgkmcnt(0)
	s_barrier
	ds_read2_b64 v[88:91], v145 offset1:1
	ds_read2_b64 v[92:95], v145 offset0:2 offset1:3
	v_and_b32_e32 v13, 0xffff0000, v13
	v_rcp_f32_e32 v124, v78
	v_add_f32_e32 v78, 1.0, v82
	v_rcp_f32_e32 v123, v78
	v_mul_f32_e32 v78, 0xbfb8aa3b, v13
	v_exp_f32_e32 v78, v78
	s_waitcnt lgkmcnt(1)
	v_mov_b32_e32 v126, v88
	s_waitcnt lgkmcnt(0)
	v_mov_b32_e32 v127, v92
	v_pk_fma_f32 v[96:97], v[40:41], v[102:103], v[96:97]
	v_pk_mul_f32 v[126:127], v[126:127], s[80:81] op_sel_hi:[1,0]
	v_pk_add_f32 v[96:97], v[42:43], v[96:97]
	v_pk_fma_f32 v[76:77], v[46:47], v[76:77], v[126:127]
	v_add_f32_e32 v78, 1.0, v78
	v_pk_mul_f32 v[76:77], v[96:97], v[76:77]
	v_pk_mul_f32 v[96:97], v[122:123], v[114:115]
	v_rcp_f32_e32 v125, v78
	v_lshlrev_b32_e32 v105, 16, v6
	v_pk_mul_f32 v[76:77], v[96:97], v[76:77]
	v_mov_b32_e32 v96, v90
	v_mov_b32_e32 v97, v94
	v_pk_fma_f32 v[100:101], v[40:41], v[104:105], v[100:101]
	v_pk_mul_f32 v[96:97], v[96:97], s[80:81] op_sel_hi:[1,0]
	v_pk_add_f32 v[100:101], v[42:43], v[100:101]
	v_pk_fma_f32 v[74:75], v[46:47], v[74:75], v[96:97]
	v_pk_mul_f32 v[12:13], v[124:125], v[12:13]
	v_pk_mul_f32 v[74:75], v[100:101], v[74:75]
	v_lshlrev_b32_e32 v118, 16, v14
	v_pk_mul_f32 v[12:13], v[12:13], v[74:75]
	v_and_b32_sdwa v74, v77, v229 dst_sel:DWORD dst_unused:UNUSED_PAD src0_sel:WORD_1 src1_sel:DWORD
	v_add3_u32 v74, v77, v74, s33
	v_and_b32_sdwa v77, v12, v229 dst_sel:DWORD dst_unused:UNUSED_PAD src0_sel:WORD_1 src1_sel:DWORD
	v_and_b32_sdwa v75, v76, v229 dst_sel:DWORD dst_unused:UNUSED_PAD src0_sel:WORD_1 src1_sel:DWORD
	v_add3_u32 v12, v12, v77, s33
	v_and_b32_e32 v14, 0xffff0000, v14
	v_add3_u32 v75, v76, v75, s33
	v_and_b32_e32 v12, 0xffff0000, v12
	v_or_b32_sdwa v12, v12, v75 dst_sel:DWORD dst_unused:UNUSED_PAD src0_sel:DWORD src1_sel:WORD_1
	v_mul_f32_e32 v75, 0xbfb8aa3b, v14
	v_exp_f32_e32 v75, v75
	v_lshlrev_b32_e32 v4, 16, v149
	v_lshlrev_b32_e32 v119, 16, v15
	v_and_b32_sdwa v76, v13, v229 dst_sel:DWORD dst_unused:UNUSED_PAD src0_sel:WORD_1 src1_sel:DWORD
	v_add_f32_e32 v75, 1.0, v75
	v_cndmask_b32_e64 v111, 0, v4, s[42:43]
	v_lshlrev_b32_e32 v4, 16, v150
	v_add3_u32 v13, v13, v76, s33
	v_rcp_f32_e32 v76, v75
	v_mul_f32_e32 v75, 0xbfb8aa3b, v119
	v_and_b32_e32 v106, 0xffff0000, v6
	v_lshlrev_b32_e32 v109, 16, v7
	v_and_b32_e32 v107, 0xffff0000, v7
	v_cndmask_b32_e64 v79, 0, v4, s[44:45]
	v_lshlrev_b32_e32 v112, 16, v8
	v_and_b32_e32 v86, 0xffff0000, v8
	v_lshlrev_b32_e32 v80, 16, v9
	v_and_b32_e32 v87, 0xffff0000, v9
	v_lshlrev_b32_e32 v81, 16, v10
	v_and_b32_e32 v84, 0xffff0000, v10
	v_lshlrev_b32_e32 v83, 16, v11
	v_and_b32_e32 v85, 0xffff0000, v11
	ds_read2_b64 v[4:7], v145 offset0:4 offset1:5
	ds_read2_b64 v[8:11], v145 offset0:6 offset1:7
	v_exp_f32_e32 v75, v75
	v_and_b32_e32 v15, 0xffff0000, v15
	v_and_b32_e32 v13, 0xffff0000, v13
	s_waitcnt lgkmcnt(1)
; __device__ __forceinline__ bf16_t f2bf(float f) { unsigned u = __float_as_uint(f); u += 0x7FFFu + ((u >> 16) & 1u); return (bf16_t)(u >> 16); }
; __device__ __forceinline__ float silu(float x) { return x * __builtin_amdgcn_rcpf(1.0f + __expf(-x)); }
; __device__ void ph_hyena_fft(const Params& P, int j, const bf16_t* __restrict__ projAT, const float* __restrict__ kf, bf16_t* __restrict__ yaT, unsigned char* lds_raw) {
;     ...
;             { float xa[8], xb[8]; sconv8(xb0, n0, wb0, wb1, wb2, bb, xa); sconv8(xb1, n0, wb0, wb1, wb2, bb, xb);
;               const unsigned gw0[4] = {g0.x, g0.y, g0.z, g0.w}, gw1[4] = {g1.x, g1.y, g1.z, g1.w}; unsigned w0[4], w1[4];
; #pragma unroll
;               for (int k2 = 0; k2 < 4; ++k2) { const v2f ya = buf[ph0 + 2 * k2], yb = buf[ph0 + 2 * k2 + 1];
;                   const float ra = xa[2 * k2] * (ya.x * invN + sk1 * va[2 * k2]) * silu(__uint_as_float(gw0[k2] << 16));
;                   const float rb = xa[2 * k2 + 1] * (yb.x * invN + sk1 * va[2 * k2 + 1]) * silu(__uint_as_float(gw0[k2] & 0xffff0000u));
;                   const float rc = xb[2 * k2] * (ya.y * invN + sk1 * vb[2 * k2]) * silu(__uint_as_float(gw1[k2] << 16));
;                   const float rd = xb[2 * k2 + 1] * (yb.y * invN + sk1 * vb[2 * k2 + 1]) * silu(__uint_as_float(gw1[k2] & 0xffff0000u));
;                   w0[k2] = (unsigned)f2bf(ra) | ((unsigned)f2bf(rb) << 16); w1[k2] = (unsigned)f2bf(rc) | ((unsigned)f2bf(rd) << 16); }
;               *(uint4*)(yaT + (size_t)c * T_TOK + o0 + n0) = make_uint4(w0[0], w0[1], w0[2], w0[3]);
;               *(uint4*)(yaT + (size_t)c * T_TOK + o1 + n0) = make_uint4(w1[0], w1[1], w1[2], w1[3]); }
	v_mov_b32_e32 v96, v4
	v_add_f32_e32 v4, 1.0, v75
	v_rcp_f32_e32 v75, v4
	v_mul_f32_e32 v4, 0xbfb8aa3b, v15
	v_exp_f32_e32 v4, v4
	s_waitcnt lgkmcnt(0)
	v_mov_b32_e32 v97, v8
	v_or_b32_sdwa v13, v13, v74 dst_sel:DWORD dst_unused:UNUSED_PAD src0_sel:DWORD src1_sel:WORD_1
	v_mul_f32_e32 v74, 0xbfb8aa3b, v118
	v_add_f32_e32 v4, 1.0, v4
	v_pk_mul_f32 v[96:97], v[96:97], s[80:81] op_sel_hi:[1,0]
	v_rcp_f32_e32 v77, v4
	v_exp_f32_e32 v74, v74
	v_pk_fma_f32 v[72:73], v[46:47], v[72:73], v[96:97]
	v_mov_b32_e32 v96, v6
	v_mov_b32_e32 v97, v10
	v_pk_mul_f32 v[96:97], v[96:97], s[80:81] op_sel_hi:[1,0]
	v_pk_mul_f32 v[14:15], v[76:77], v[14:15]
	v_pk_fma_f32 v[70:71], v[46:47], v[70:71], v[96:97]
	v_mov_b32_e32 v96, v105
	v_mov_b32_e32 v97, v109
	v_pk_mov_b32 v[76:77], v[102:103], v[106:107] op_sel:[1,0]
	v_pk_mul_f32 v[96:97], v[54:55], v[96:97]
	v_mov_b32_e32 v104, v107
	v_mov_b32_e32 v108, v106
	v_add_f32_e32 v74, 1.0, v74
	v_pk_fma_f32 v[76:77], v[52:53], v[76:77], v[96:97]
	v_pk_mul_f32 v[96:97], v[38:39], v[104:105]
	v_mov_b32_e32 v98, v109
	v_rcp_f32_e32 v74, v74
	v_pk_fma_f32 v[96:97], v[38:39], v[108:109], v[96:97] op_sel:[0,0,1] op_sel_hi:[1,1,0]
	v_pk_fma_f32 v[76:77], v[40:41], v[106:107], v[76:77]
	v_pk_fma_f32 v[96:97], v[40:41], v[98:99], v[96:97]
	v_pk_add_f32 v[76:77], v[42:43], v[76:77]
	v_pk_add_f32 v[96:97], v[42:43], v[96:97]
	v_pk_mul_f32 v[74:75], v[74:75], v[118:119]
	v_pk_mul_f32 v[70:71], v[96:97], v[70:71]
	v_pk_mul_f32 v[72:73], v[76:77], v[72:73]
	v_pk_mul_f32 v[14:15], v[14:15], v[70:71]
	v_pk_mul_f32 v[72:73], v[74:75], v[72:73]
	v_and_b32_sdwa v8, v15, v229 dst_sel:DWORD dst_unused:UNUSED_PAD src0_sel:WORD_1 src1_sel:DWORD
	v_and_b32_sdwa v4, v73, v229 dst_sel:DWORD dst_unused:UNUSED_PAD src0_sel:WORD_1 src1_sel:DWORD
	v_and_b32_sdwa v10, v14, v229 dst_sel:DWORD dst_unused:UNUSED_PAD src0_sel:WORD_1 src1_sel:DWORD
	v_add3_u32 v8, v15, v8, s33
	s_waitcnt vmcnt(0)
; __device__ __forceinline__ bf16_t f2bf(float f) { unsigned u = __float_as_uint(f); u += 0x7FFFu + ((u >> 16) & 1u); return (bf16_t)(u >> 16); }
; __device__ __forceinline__ float silu(float x) { return x * __builtin_amdgcn_rcpf(1.0f + __expf(-x)); }
; __device__ __forceinline__ void lds_barrier() { asm volatile("s_waitcnt lgkmcnt(0)\n\ts_barrier" ::: "memory"); }
; __device__ void ph_hyena_fft(const Params& P, int j, const bf16_t* __restrict__ projAT, const float* __restrict__ kf, bf16_t* __restrict__ yaT, unsigned char* lds_raw) {
;     ...
;             { float xa[8], xb[8]; sconv8(xb0, n0, wb0, wb1, wb2, bb, xa); sconv8(xb1, n0, wb0, wb1, wb2, bb, xb);
;               const unsigned gw0[4] = {g0.x, g0.y, g0.z, g0.w}, gw1[4] = {g1.x, g1.y, g1.z, g1.w}; unsigned w0[4], w1[4];
; #pragma unroll
;               for (int k2 = 0; k2 < 4; ++k2) { const v2f ya = buf[ph0 + 2 * k2], yb = buf[ph0 + 2 * k2 + 1];
;                   const float ra = xa[2 * k2] * (ya.x * invN + sk1 * va[2 * k2]) * silu(__uint_as_float(gw0[k2] << 16));
;                   const float rb = xa[2 * k2 + 1] * (yb.x * invN + sk1 * va[2 * k2 + 1]) * silu(__uint_as_float(gw0[k2] & 0xffff0000u));
;                   const float rc = xb[2 * k2] * (ya.y * invN + sk1 * vb[2 * k2]) * silu(__uint_as_float(gw1[k2] << 16));
;                   const float rd = xb[2 * k2 + 1] * (yb.y * invN + sk1 * vb[2 * k2 + 1]) * silu(__uint_as_float(gw1[k2] & 0xffff0000u));
;                   w0[k2] = (unsigned)f2bf(ra) | ((unsigned)f2bf(rb) << 16); w1[k2] = (unsigned)f2bf(rc) | ((unsigned)f2bf(rd) << 16); }
;               *(uint4*)(yaT + (size_t)c * T_TOK + o0 + n0) = make_uint4(w0[0], w0[1], w0[2], w0[3]);
;               *(uint4*)(yaT + (size_t)c * T_TOK + o1 + n0) = make_uint4(w1[0], w1[1], w1[2], w1[3]); }
;             lds_barrier();
;         }
;     }
	v_lshlrev_b32_e32 v116, 16, v0
	v_and_b32_sdwa v6, v72, v229 dst_sel:DWORD dst_unused:UNUSED_PAD src0_sel:WORD_1 src1_sel:DWORD
	v_add3_u32 v4, v73, v4, s33
	v_add3_u32 v10, v14, v10, s33
	v_and_b32_e32 v8, 0xffff0000, v8
	v_and_b32_e32 v0, 0xffff0000, v0
	v_add3_u32 v6, v72, v6, s33
	v_and_b32_e32 v10, 0xffff0000, v10
	v_or_b32_sdwa v15, v8, v4 dst_sel:DWORD dst_unused:UNUSED_PAD src0_sel:DWORD src1_sel:WORD_1
	v_mul_f32_e32 v4, 0xbfb8aa3b, v116
	v_or_b32_sdwa v14, v10, v6 dst_sel:DWORD dst_unused:UNUSED_PAD src0_sel:DWORD src1_sel:WORD_1
	v_exp_f32_e32 v4, v4
	v_mul_f32_e32 v6, 0xbfb8aa3b, v0
	v_exp_f32_e32 v6, v6
	v_lshlrev_b32_e32 v117, 16, v1
	v_add_f32_e32 v4, 1.0, v4
	v_rcp_f32_e32 v72, v4
	v_add_f32_e32 v4, 1.0, v6
	v_rcp_f32_e32 v74, v4
	v_mul_f32_e32 v4, 0xbfb8aa3b, v117
	v_exp_f32_e32 v4, v4
	v_and_b32_e32 v1, 0xffff0000, v1
	v_lshl_add_u64 v[120:121], v[50:51], 0, s[62:63]
	v_mov_b32_e32 v110, v80
	v_add_f32_e32 v4, 1.0, v4
	v_rcp_f32_e32 v73, v4
	v_mul_f32_e32 v4, 0xbfb8aa3b, v1
	v_exp_f32_e32 v4, v4
	global_store_dwordx4 v[120:121], v[12:15], off
	v_mov_b32_e32 v113, v86
	v_mov_b32_e32 v92, v89
	v_pk_mul_f32 v[14:15], v[38:39], v[110:111]
	v_pk_mul_f32 v[76:77], v[92:93], s[80:81] op_sel_hi:[1,0]
	v_pk_fma_f32 v[14:15], v[38:39], v[112:113], v[14:15] op_sel:[0,0,1] op_sel_hi:[1,1,0]
	v_add_f32_e32 v4, 1.0, v4
	v_pk_fma_f32 v[14:15], v[40:41], v[86:87], v[14:15]
	v_mov_b32_e32 v113, v80
	v_pk_add_f32 v[14:15], v[42:43], v[14:15]
	v_pk_mul_f32 v[70:71], v[54:55], v[86:87]
	v_pk_fma_f32 v[68:69], v[46:47], v[68:69], v[76:77]
	v_rcp_f32_e32 v75, v4
	v_pk_fma_f32 v[70:71], v[52:53], v[112:113], v[70:71]
	v_pk_mul_f32 v[14:15], v[14:15], v[68:69]
	v_pk_mul_f32 v[68:69], v[72:73], v[116:117]
	v_mov_b32_e32 v94, v91
	v_pk_fma_f32 v[70:71], v[40:41], v[80:81], v[70:71]
	v_pk_mul_f32 v[14:15], v[68:69], v[14:15]
	v_pk_mul_f32 v[68:69], v[94:95], s[80:81] op_sel_hi:[1,0]
	v_pk_add_f32 v[70:71], v[42:43], v[70:71]
	v_pk_fma_f32 v[66:67], v[46:47], v[66:67], v[68:69]
	v_pk_mul_f32 v[0:1], v[74:75], v[0:1]
	v_pk_mul_f32 v[66:67], v[70:71], v[66:67]
	v_and_b32_sdwa v6, v14, v229 dst_sel:DWORD dst_unused:UNUSED_PAD src0_sel:WORD_1 src1_sel:DWORD
	v_pk_mul_f32 v[0:1], v[0:1], v[66:67]
	v_and_b32_sdwa v4, v15, v229 dst_sel:DWORD dst_unused:UNUSED_PAD src0_sel:WORD_1 src1_sel:DWORD
	v_and_b32_sdwa v10, v0, v229 dst_sel:DWORD dst_unused:UNUSED_PAD src0_sel:WORD_1 src1_sel:DWORD
	v_and_b32_sdwa v8, v1, v229 dst_sel:DWORD dst_unused:UNUSED_PAD src0_sel:WORD_1 src1_sel:DWORD
	v_add3_u32 v0, v0, v10, s33
	v_add3_u32 v6, v14, v6, s33
	v_add3_u32 v1, v1, v8, s33
	v_and_b32_e32 v0, 0xffff0000, v0
	v_lshlrev_b32_e32 v14, 16, v2
	v_and_b32_e32 v2, 0xffff0000, v2
	v_add3_u32 v4, v15, v4, s33
	v_and_b32_e32 v1, 0xffff0000, v1
	v_or_b32_sdwa v0, v0, v6 dst_sel:DWORD dst_unused:UNUSED_PAD src0_sel:DWORD src1_sel:WORD_1
	v_lshlrev_b32_e32 v15, 16, v3
	v_mul_f32_e32 v6, 0xbfb8aa3b, v2
	v_or_b32_sdwa v1, v1, v4 dst_sel:DWORD dst_unused:UNUSED_PAD src0_sel:DWORD src1_sel:WORD_1
	v_mul_f32_e32 v4, 0xbfb8aa3b, v14
	v_exp_f32_e32 v6, v6
	v_mul_f32_e32 v8, 0xbfb8aa3b, v15
	v_exp_f32_e32 v4, v4
	v_exp_f32_e32 v10, v8
	v_and_b32_e32 v3, 0xffff0000, v3
	v_add_f32_e32 v6, 1.0, v6
	v_add_f32_e32 v4, 1.0, v4
	v_rcp_f32_e32 v66, v6
	v_mov_b32_e32 v8, v5
	v_add_f32_e32 v5, 1.0, v10
	v_mul_f32_e32 v6, 0xbfb8aa3b, v3
	v_rcp_f32_e32 v4, v4
	v_rcp_f32_e32 v5, v5
	v_exp_f32_e32 v6, v6
	v_mov_b32_e32 v10, v7
	v_mov_b32_e32 v80, v85
	v_pk_mul_f32 v[4:5], v[4:5], v[14:15]
	v_add_f32_e32 v6, 1.0, v6
	v_mov_b32_e32 v14, v81
	v_mov_b32_e32 v15, v83
	v_rcp_f32_e32 v67, v6
	v_pk_mul_f32 v[6:7], v[10:11], s[80:81] op_sel_hi:[1,0]
	v_pk_mov_b32 v[10:11], v[86:87], v[84:85] op_sel:[1,0]
	v_pk_mul_f32 v[14:15], v[54:55], v[14:15]
	v_mov_b32_e32 v82, v84
	v_pk_fma_f32 v[10:11], v[52:53], v[10:11], v[14:15]
	v_pk_mul_f32 v[14:15], v[38:39], v[80:81]
	v_mov_b32_e32 v78, v83
	v_pk_mul_f32 v[8:9], v[8:9], s[80:81] op_sel_hi:[1,0]
	v_pk_fma_f32 v[10:11], v[40:41], v[84:85], v[10:11]
	v_pk_fma_f32 v[14:15], v[38:39], v[82:83], v[14:15] op_sel:[0,0,1] op_sel_hi:[1,1,0]
	v_pk_fma_f32 v[8:9], v[46:47], v[64:65], v[8:9]
	v_pk_add_f32 v[10:11], v[42:43], v[10:11]
	v_pk_fma_f32 v[14:15], v[40:41], v[78:79], v[14:15]
	v_pk_fma_f32 v[6:7], v[46:47], v[62:63], v[6:7]
	v_pk_add_f32 v[14:15], v[42:43], v[14:15]
	v_pk_mul_f32 v[8:9], v[10:11], v[8:9]
	v_pk_mul_f32 v[2:3], v[66:67], v[2:3]
	v_pk_mul_f32 v[4:5], v[4:5], v[8:9]
	v_pk_mul_f32 v[6:7], v[14:15], v[6:7]
	s_mov_b32 s7, s63
	v_pk_mul_f32 v[2:3], v[2:3], v[6:7]
	v_and_b32_sdwa v6, v5, v229 dst_sel:DWORD dst_unused:UNUSED_PAD src0_sel:WORD_1 src1_sel:DWORD
	v_and_b32_sdwa v7, v4, v229 dst_sel:DWORD dst_unused:UNUSED_PAD src0_sel:WORD_1 src1_sel:DWORD
	v_add3_u32 v4, v4, v7, s33
	v_add3_u32 v5, v5, v6, s33
	v_and_b32_sdwa v6, v3, v229 dst_sel:DWORD dst_unused:UNUSED_PAD src0_sel:WORD_1 src1_sel:DWORD
	v_and_b32_sdwa v7, v2, v229 dst_sel:DWORD dst_unused:UNUSED_PAD src0_sel:WORD_1 src1_sel:DWORD
	v_add3_u32 v3, v3, v6, s33
	v_add3_u32 v2, v2, v7, s33
	v_and_b32_e32 v3, 0xffff0000, v3
	v_and_b32_e32 v2, 0xffff0000, v2
	v_lshl_add_u64 v[12:13], v[50:51], 0, s[6:7]
	v_or_b32_sdwa v3, v3, v5 dst_sel:DWORD dst_unused:UNUSED_PAD src0_sel:DWORD src1_sel:WORD_1
	v_or_b32_sdwa v2, v2, v4 dst_sel:DWORD dst_unused:UNUSED_PAD src0_sel:DWORD src1_sel:WORD_1
	global_store_dwordx4 v[12:13], v[0:3], off
	s_waitcnt lgkmcnt(0)
	s_barrier
	s_add_i32 s53, s53, 1
	s_cmp_eq_u32 s53, 4
	s_cbranch_scc0 .LBB0_346
	s_add_i32 s46, s46, s22
	v_readlane_b32 s60, v255, 27
	s_cmpk_gt_i32 s46, 0x3ff
	v_readlane_b32 s61, v255, 28
	s_movk_i32 s59, 0xffd0
	s_cbranch_scc0 .LBB0_333
